# adds: log2e folded into gate weights / ln2 into up weights at conversion (no per-element -log2e multiply in SwiGLU epilogue); grid-barrier constants via ds_read
# speedup vs baseline: 1.0244x; 1.0055x over previous
; DI int ltid() { int t = threadIdx.x; asm volatile("" : "+v"(t)); return t; }
; DI void conv_tile(const float* __restrict__ src, int K, int N, u16* __restrict__ dst, int ldd, int mode, int tile, float* tl) {
;   const int tid = ltid();
;   const int nNt = N >> 6;
;   const int kt = tile / nNt, nt = tile - kt * nNt;
;   const int k0 = kt << 6, n0 = nt << 6;
;   {
;     const int kl = tid >> 4, n4 = (tid & 15) * 4;
;     const float* sp = src + (size_t)(k0 + kl) * N + n0 + n4;
;     const f32x4 v0 = __builtin_nontemporal_load((const f32x4*)(sp));
;     const f32x4 v1 = __builtin_nontemporal_load((const f32x4*)(sp + (size_t)32 * N));
;     __builtin_amdgcn_sched_barrier(0);
;     float* d = tl + kl * 65 + n4;
;     d[0] = v0[0]; d[1] = v0[1]; d[2] = v0[2]; d[3] = v0[3];
;     d += 32 * 65;
;     d[0] = v1[0]; d[1] = v1[1]; d[2] = v1[2]; d[3] = v1[3];
;   }
;   __syncthreads();
;   {
;     const int nl = tid >> 3, k8 = (tid & 7) * 8;
;     const int n = n0 + nl;
;     float sc = 1.f;
;     int row = n;
;     if (mode == 1) row = ((n >> 4) << 5) + (n & 15);
;     else if (mode == 2) row = ((n >> 4) << 5) + 16 + (n & 15);
;     else if (mode == 3) {
;       if (n < 384) sc = 0.125f * LOG2E;
;       else if (n >= 1152 && n < 1408) sc = 0.17677669529663687f * LOG2E;
;       else if (n >= 1920 && n < 2304) sc = 0.125f * LOG2E;
;     }
;     const float* t = tl + k8 * 65 + nl;
;     uint4 o = {pack2(t[0] * sc, t[65] * sc), pack2(t[130] * sc, t[195] * sc), pack2(t[260] * sc, t[325] * sc),
;                pack2(t[390] * sc, t[455] * sc)};
;     *(uint4*)(dst + (size_t)row * ldd + k0 + k8) = o;
;   }
;   __syncthreads();
; DI void conv_phase(const Params& p, int layer, char* smem) {
;     ...
;     if (t < 4 * 704) {
;       int seg = t / 704, tt = t - seg * 704;
;       int f = seg >> 1, up = seg & 1;
;       const float* src = (up ? p.wu : p.wg) + (size_t)(layer * 2 + f) * DM * DFF;
;       conv_tile(src, DM, DFF, (u16*)(p.ws + (f ? OFF_WGU1 : OFF_WGU0)), LDH, 1 + up, tt, tl);
.LBB0_17:
	s_andn2_b64 vcc, exec, s[14:15]
	s_cbranch_vccnz .LBB0_6
	s_mul_hi_i32 s12, s55, 0x2e8ba2e9
	s_lshr_b32 s14, s12, 31
	s_ashr_i32 s12, s12, 7
	s_add_i32 s12, s12, s14
	s_mul_i32 s14, s12, 0xfffffd40
	s_add_i32 s14, s10, s14
	s_add_i32 s55, s14, 0x1380
	s_ashr_i32 s14, s12, 1
	s_and_b32 s59, s12, 1
	s_cmp_eq_u32 s59, 0
	s_waitcnt lgkmcnt(0)
	s_cselect_b32 s56, s40, s42
	s_mul_hi_i32 s57, s14, 0xb00000
	s_mul_i32 s14, s14, 0xb00000
	s_cselect_b32 s15, s41, s43
	s_add_u32 s14, s56, s14
	s_addc_u32 s15, s15, s57
	s_cmp_lt_u32 s12, 2
	s_cselect_b32 s56, 0, 0xbb0000
	s_add_u32 s56, s24, s56
	s_mul_hi_i32 s55, s55, 0x2e8ba2e9
	s_addc_u32 s57, s25, 0
	s_lshr_b32 s58, s55, 31
	s_ashr_i32 s55, s55, 3
	s_add_i32 s55, s55, s58
	s_mul_i32 s58, s55, 0x3ffffd4
	s_mulk_i32 s12, 0x2c0
	s_sub_i32 s12, s58, s12
	v_mov_b32_e32 v5, v158
	s_add_i32 s12, s10, s12
	s_lshl_b32 s12, s12, 6
	s_lshl_b32 s58, s55, 6
	v_ashrrev_i32_e32 v14, 4, v5
	s_add_i32 s60, s12, 0x4e000
	v_add_u32_e32 v2, s58, v14
	v_mov_b64_e32 v[6:7], s[14:15]
	v_mad_i64_i32 v[6:7], s[14:15], v2, s53, v[6:7]
	s_ashr_i32 s61, s60, 31
	v_lshlrev_b32_e32 v2, 4, v5
	v_lshl_add_u64 v[6:7], s[60:61], 2, v[6:7]
	v_and_b32_e32 v2, 0xf0, v2
	v_lshl_add_u64 v[6:7], v[6:7], 0, v[2:3]
	v_add_co_u32_e32 v10, vcc, s54, v6
	s_nop 1
	v_addc_co_u32_e32 v11, vcc, 0, v7, vcc
	global_load_dwordx4 v[6:9], v[6:7], off nt
	s_nop 0
	global_load_dwordx4 v[10:13], v[10:11], off nt
	v_mad_u64_u32 v[14:15], s[14:15], v14, s26, v[2:3]
	v_add_u32_e32 v2, 0x2080, v14
	s_waitcnt vmcnt(1)
	ds_write2_b32 v14, v6, v7 offset1:1
	ds_write2_b32 v14, v8, v9 offset0:2 offset1:3
	s_waitcnt vmcnt(0)
	ds_write2_b32 v2, v10, v11 offset1:1
	v_add_u32_e32 v2, 0x2088, v14
	ds_write2_b32 v2, v12, v13 offset1:1
	v_ashrrev_i32_e32 v2, 3, v5
	v_lshlrev_b32_e32 v5, 3, v5
	v_add_lshl_u32 v6, v2, s60, 1
	v_and_b32_e32 v15, 15, v2
	v_and_b32_e32 v5, 56, v5
	v_lshlrev_b32_e32 v2, 2, v2
	v_mad_u32_u24 v2, v5, s26, v2
	s_waitcnt lgkmcnt(0)
	s_barrier
	v_and_b32_e32 v14, 0xffffffe0, v6
	ds_read2_b32 v[6:7], v2 offset1:65
	ds_read2_b32 v[8:9], v2 offset0:130 offset1:195
	v_add_u32_e32 v2, 0x400, v2
	ds_read2_b32 v[10:11], v2 offset0:4 offset1:69
	ds_read2_b32 v[12:13], v2 offset0:134 offset1:199
	s_lshl_b32 s12, s59, 4
	v_or3_b32 v2, v15, v14, s12
	s_mov_b32 s100, 0x3f317218
	s_cmp_eq_u32 s59, 0
	s_cselect_b32 s100, 0x3fb8aa3b, s100
	v_mov_b32_e32 v20, s100
	s_waitcnt lgkmcnt(3)
	v_pk_mul_f32 v[6:7], v[20:21], v[6:7] op_sel_hi:[0,1]
	v_cvt_pk_bf16_f32 v6, v6, v7
	s_waitcnt lgkmcnt(2)
	v_pk_mul_f32 v[8:9], v[20:21], v[8:9] op_sel_hi:[0,1]
	v_cvt_pk_bf16_f32 v7, v8, v9
	s_waitcnt lgkmcnt(1)
	v_pk_mul_f32 v[10:11], v[20:21], v[10:11] op_sel_hi:[0,1]
	v_cvt_pk_bf16_f32 v8, v10, v11
	v_mov_b64_e32 v[10:11], s[56:57]
	v_mad_i64_i32 v[10:11], s[14:15], v2, s27, v[10:11]
	s_ashr_i32 s59, s58, 31
	v_lshl_add_u64 v[10:11], s[58:59], 1, v[10:11]
	v_lshlrev_b32_e32 v2, 1, v5
	s_waitcnt lgkmcnt(0)
	v_pk_mul_f32 v[12:13], v[20:21], v[12:13] op_sel_hi:[0,1]
	v_cvt_pk_bf16_f32 v9, v12, v13
	v_lshl_add_u64 v[10:11], v[10:11], 0, v[2:3]
	global_store_dwordx4 v[10:11], v[6:9], off
	s_barrier
	s_branch .LBB0_6

; DI unsigned bar_add(unsigned* p, unsigned v) { return __hip_atomic_fetch_add(p, v, __ATOMIC_RELAXED, __HIP_MEMORY_SCOPE_AGENT); }
; DI void grid_barrier(unsigned* bar, unsigned k, volatile unsigned* meta) {
;     ...
;   if (threadIdx.x == 0) {
;     const unsigned nloc = meta[0], nx = meta[1], x = meta[2];
;     const unsigned old = bar_add(bar + 1024 + 64 * x, 1u);
;     if (old + 1u == k * nloc) {
;       __builtin_amdgcn_fence(__ATOMIC_RELEASE, "agent");
;       asm volatile("s_waitcnt vmcnt(0)" ::: "memory");
;       const unsigned old2 = bar_add(bar + 3072, 1u);
.LBB0_42:
	s_or_b64 exec, exec, s[28:29]
	s_waitcnt lgkmcnt(0)
	s_barrier
	s_waitcnt vmcnt(0)
	s_barrier
	s_and_saveexec_b64 s[0:1], s[8:9]
	s_cbranch_execz .LBB0_52
	s_mov_b64 s[2:3], src_shared_base
	v_mov_b32_e32 v0, 0x24040
	ds_read_b32 v3, v0
	ds_read_b32 v2, v0 offset:4
	ds_read_b32 v0, v0 offset:8
	v_mov_b32_e32 v1, 0
	v_mov_b32_e32 v6, 1
	s_waitcnt lgkmcnt(0)
	v_lshlrev_b32_e32 v0, 6, v0
	v_lshl_add_u64 v[0:1], v[0:1], 2, s[24:25]
	v_add_co_u32_e32 v4, vcc, 0xef01000, v0
	s_nop 1
	v_addc_co_u32_e32 v5, vcc, 0, v1, vcc
	global_atomic_add v4, v[4:5], v6, off offset:1024 sc0
	s_waitcnt vmcnt(0)
	v_add_u32_e32 v4, 1, v4
	v_cmp_eq_u32_e32 vcc, v4, v3
	s_and_saveexec_b64 s[2:3], vcc
	s_cbranch_execz .LBB0_48
	s_mov_b64 s[4:5], exec
	buffer_wbl2 sc1
	s_waitcnt vmcnt(0)
	v_mbcnt_lo_u32_b32 v3, s4, 0
	v_mbcnt_hi_u32_b32 v3, s5, v3
	v_cmp_eq_u32_e32 vcc, 0, v3
	s_and_saveexec_b64 s[6:7], vcc
	s_cbranch_execz .LBB0_46
	s_bcnt1_i32_b64 s4, s[4:5]
	v_mov_b32_e32 v4, 0xef03000
	v_mov_b32_e32 v5, s4
	global_atomic_add v4, v4, v5, s[24:25] offset:1024 sc0

; #define PG8_STAGE(bufoff, gbase, voff) do { _Pragma("unroll") for (int _i = 0; _i < 2; ++_i) \
;         __builtin_amdgcn_global_load_lds((const unsigned*)((const char*)(gbase) + (voff)[_i]), (PG8_LAS unsigned*)(lds + (bufoff) + ldsw + _i * 8192), 16, 0, 0); } while (0)
; #define PG8_LDA(dst, b, h) do { _Pragma("unroll") for (int m = 0; m < 4; ++m) _Pragma("unroll") for (int k = 0; k < 2; ++k) dst[m][k] = *(const PG8_LAS bf16x8*)(lds + PG8_SA(b, h) + aoff + m * 2048 + k * 1024); } while (0)
; #define PG8_LDB(dst, b, h) do { _Pragma("unroll") for (int n = 0; n < 2; ++n) _Pragma("unroll") for (int k = 0; k < 2; ++k) dst[n][k] = *(const PG8_LAS bf16x8*)(lds + PG8_SB(b, h) + boff + n * 2048 + k * 1024); } while (0)
; #define PG8_MMA(ai, bj, At, Bt) do { __builtin_amdgcn_s_setprio(1); _Pragma("unroll") for (int m = 0; m < 4; ++m) _Pragma("unroll") for (int n = 0; n < 2; ++n) _Pragma("unroll") for (int k = 0; k < 2; ++k) \
;         acc[ai][bj][m][n] = __builtin_amdgcn_mfma_f32_16x16x32_bf16(Bt[n][k], At[m][k], acc[ai][bj][m][n], 0, 0, 0); __builtin_amdgcn_s_setprio(0); } while (0)
; #define PG8_WAIT_V(n) asm volatile("s_waitcnt vmcnt(" #n ")" ::: "memory")
; #define PG8_WAIT_L(n) asm volatile("s_waitcnt lgkmcnt(" #n ")" ::: "memory")
; #define PG8_BAR __builtin_amdgcn_s_barrier()
; #define PG8_SCHED __builtin_amdgcn_sched_barrier(0)
; template <class Epi, class Sched, bool STAMP = false>
; __device__ __forceinline__ void gemm_phase(PG8_LAS unsigned char* lds, const Gemm g, const Sched& S, const Epi& E, unsigned long long* stamps) {
;     ...
;             PG8_LDB(B0, 1, 0); PG8_SCHED; PG8_LDA(At, 1, 0); PG8_STAGE(PG8_SA(0, 1), a2 + hstep, voffA);
;             PG8_WAIT_L(8); PG8_BAR; PG8_WAIT_L(0); PG8_MMA(0, 0, At, B0); PG8_BAR; PG8_SCHED;
;             PG8_LDB(B1, 1, 1); PG8_STAGE(PG8_SB(1, 0), b3, voffB);
;             PG8_BAR; PG8_WAIT_L(0); PG8_MMA(0, 1, At, B1); PG8_BAR;
;             PG8_LDA(At, 1, 1); PG8_STAGE(PG8_SA(1, 0), a3, voffA);
;             PG8_BAR; PG8_WAIT_L(0); PG8_MMA(1, 0, At, B0); PG8_BAR; PG8_SCHED;
;             PG8_STAGE(PG8_SB(1, 1), b3 + hstep, voffB);
;             PG8_WAIT_V(6); PG8_BAR; PG8_MMA(1, 1, At, B1); PG8_BAR;
.Lzp1_mid:
	ds_read_b128 v[140:143], v156
	ds_read_b128 v[166:169], v157
	ds_read_b128 v[170:173], v159
	ds_read_b128 v[174:177], v160
	s_add_u32 s14, s28, 0x44000
	s_addc_u32 s15, s29, 0
	s_mov_b32 m0, s57
	ds_read_b128 v[178:181], v146 offset:32768
	ds_read_b128 v[182:185], v146 offset:33792
	ds_read_b128 v[186:189], v146 offset:34816
	ds_read_b128 v[190:193], v146 offset:35840
	ds_read_b128 v[194:197], v146 offset:36864
	ds_read_b128 v[198:201], v146 offset:37888
	ds_read_b128 v[202:205], v146 offset:38912
	ds_read_b128 v[206:209], v146 offset:39936
	global_load_lds_dwordx4 v130, s[14:15]
	s_mov_b32 m0, s58
	s_nop 0
	global_load_lds_dwordx4 v128, s[14:15]
	s_waitcnt lgkmcnt(8)
	s_barrier
	s_waitcnt lgkmcnt(0)
	s_setprio 1
	s_waitcnt lgkmcnt(0)
	v_mfma_f32_16x16x32_bf16 v[124:127], v[140:143], v[178:181], v[124:127]
	v_mfma_f32_16x16x32_bf16 v[120:123], v[170:173], v[178:181], v[120:123]
	v_mfma_f32_16x16x32_bf16 v[108:111], v[140:143], v[186:189], v[108:111]
	v_mfma_f32_16x16x32_bf16 v[104:107], v[170:173], v[186:189], v[104:107]
	v_mfma_f32_16x16x32_bf16 v[92:95], v[140:143], v[194:197], v[92:95]
	v_mfma_f32_16x16x32_bf16 v[88:91], v[170:173], v[194:197], v[88:91]
	v_mfma_f32_16x16x32_bf16 v[76:79], v[140:143], v[202:205], v[76:79]
	v_mfma_f32_16x16x32_bf16 v[72:75], v[170:173], v[202:205], v[72:75]
	v_mfma_f32_16x16x32_bf16 v[124:127], v[166:169], v[182:185], v[124:127]
	v_mfma_f32_16x16x32_bf16 v[120:123], v[174:177], v[182:185], v[120:123]
	v_mfma_f32_16x16x32_bf16 v[108:111], v[166:169], v[190:193], v[108:111]
	v_mfma_f32_16x16x32_bf16 v[104:107], v[174:177], v[190:193], v[104:107]
	v_mfma_f32_16x16x32_bf16 v[92:95], v[166:169], v[198:201], v[92:95]
	v_mfma_f32_16x16x32_bf16 v[88:91], v[174:177], v[198:201], v[88:91]
	v_mfma_f32_16x16x32_bf16 v[76:79], v[166:169], v[206:209], v[76:79]
	v_mfma_f32_16x16x32_bf16 v[72:75], v[174:177], v[206:209], v[72:75]
	s_setprio 0
	s_barrier
	s_mov_b32 m0, s61
	ds_read_b128 v[210:213], v161
	ds_read_b128 v[214:217], v162
	ds_read_b128 v[218:221], v163
	ds_read_b128 v[222:225], v164
	s_add_u32 s100, s18, 0x80
	s_addc_u32 s101, s19, 0
	global_load_lds_dwordx4 v130, s[100:101]
	s_mov_b32 m0, s62
	s_nop 0
	global_load_lds_dwordx4 v128, s[100:101]
	s_barrier
	s_waitcnt lgkmcnt(0)
	s_setprio 1
	s_waitcnt lgkmcnt(0)
	v_mfma_f32_16x16x32_bf16 v[116:119], v[210:213], v[178:181], v[116:119]
	v_mfma_f32_16x16x32_bf16 v[112:115], v[218:221], v[178:181], v[112:115]
	v_mfma_f32_16x16x32_bf16 v[100:103], v[210:213], v[186:189], v[100:103]
	v_mfma_f32_16x16x32_bf16 v[96:99], v[218:221], v[186:189], v[96:99]
	v_mfma_f32_16x16x32_bf16 v[84:87], v[210:213], v[194:197], v[84:87]
	v_mfma_f32_16x16x32_bf16 v[80:83], v[218:221], v[194:197], v[80:83]
	v_mfma_f32_16x16x32_bf16 v[68:71], v[210:213], v[202:205], v[68:71]
	v_mfma_f32_16x16x32_bf16 v[64:67], v[218:221], v[202:205], v[64:67]
	v_mfma_f32_16x16x32_bf16 v[116:119], v[214:217], v[182:185], v[116:119]
	v_mfma_f32_16x16x32_bf16 v[112:115], v[222:225], v[182:185], v[112:115]
	v_mfma_f32_16x16x32_bf16 v[100:103], v[214:217], v[190:193], v[100:103]
	v_mfma_f32_16x16x32_bf16 v[96:99], v[222:225], v[190:193], v[96:99]
	v_mfma_f32_16x16x32_bf16 v[84:87], v[214:217], v[198:201], v[84:87]
	v_mfma_f32_16x16x32_bf16 v[80:83], v[222:225], v[198:201], v[80:83]
	v_mfma_f32_16x16x32_bf16 v[68:71], v[214:217], v[206:209], v[68:71]
	v_mfma_f32_16x16x32_bf16 v[64:67], v[222:225], v[206:209], v[64:67]
	s_setprio 0
	s_mov_b32 m0, s63
	s_barrier
	ds_read_b128 v[178:181], v146 offset:49152
	ds_read_b128 v[182:185], v146 offset:50176
	ds_read_b128 v[186:189], v146 offset:51200
	ds_read_b128 v[190:193], v146 offset:52224
	ds_read_b128 v[194:197], v146 offset:53248
	ds_read_b128 v[198:201], v146 offset:54272
	ds_read_b128 v[202:205], v146 offset:55296
	ds_read_b128 v[206:209], v146 offset:56320
	s_add_u32 s100, s28, 0x80
	s_addc_u32 s101, s29, 0
	global_load_lds_dwordx4 v130, s[100:101]
	s_mov_b32 m0, s64
	s_nop 0
	global_load_lds_dwordx4 v128, s[100:101]
	s_barrier
	s_waitcnt lgkmcnt(0)
	s_setprio 1
	s_waitcnt lgkmcnt(0)
	v_mfma_f32_16x16x32_bf16 v[60:63], v[140:143], v[178:181], v[60:63]
	v_mfma_f32_16x16x32_bf16 v[56:59], v[170:173], v[178:181], v[56:59]
	v_mfma_f32_16x16x32_bf16 v[44:47], v[140:143], v[186:189], v[44:47]
	v_mfma_f32_16x16x32_bf16 v[40:43], v[170:173], v[186:189], v[40:43]
	v_mfma_f32_16x16x32_bf16 v[28:31], v[140:143], v[194:197], v[28:31]
	v_mfma_f32_16x16x32_bf16 v[24:27], v[170:173], v[194:197], v[24:27]
	v_mfma_f32_16x16x32_bf16 v[12:15], v[140:143], v[202:205], v[12:15]
	v_mfma_f32_16x16x32_bf16 v[8:11], v[170:173], v[202:205], v[8:11]
	v_mfma_f32_16x16x32_bf16 v[60:63], v[166:169], v[182:185], v[60:63]
	v_mfma_f32_16x16x32_bf16 v[56:59], v[174:177], v[182:185], v[56:59]
	v_mfma_f32_16x16x32_bf16 v[44:47], v[166:169], v[190:193], v[44:47]
	v_mfma_f32_16x16x32_bf16 v[40:43], v[174:177], v[190:193], v[40:43]
	v_mfma_f32_16x16x32_bf16 v[28:31], v[166:169], v[198:201], v[28:31]
	v_mfma_f32_16x16x32_bf16 v[24:27], v[174:177], v[198:201], v[24:27]
	v_mfma_f32_16x16x32_bf16 v[12:15], v[166:169], v[206:209], v[12:15]
	v_mfma_f32_16x16x32_bf16 v[8:11], v[174:177], v[206:209], v[8:11]
	s_setprio 0
	s_barrier
	s_add_u32 s14, s18, 0x44080
	s_addc_u32 s15, s19, 0
	s_mov_b32 m0, s65
	s_nop 0
	global_load_lds_dwordx4 v130, s[14:15]
	s_mov_b32 m0, s66
	s_nop 0
	global_load_lds_dwordx4 v128, s[14:15]
	s_waitcnt vmcnt(6)
	s_barrier
; DI float ex2(float x) { return __builtin_amdgcn_exp2f(x); }
; #define PG8_STAMP() do { if (STAMP && wid == 0 && nts < 64) { const unsigned long long _c = 0ull; \
;         ts_lo = (lane == nts) ? (int)(unsigned)_c : ts_lo; ts_hi = (lane == nts) ? (int)(unsigned)(_c >> 32) : ts_hi; ++nts; } } while (0)
; #define PG8_MMA(ai, bj, At, Bt) do { __builtin_amdgcn_s_setprio(1); _Pragma("unroll") for (int m = 0; m < 4; ++m) _Pragma("unroll") for (int n = 0; n < 2; ++n) _Pragma("unroll") for (int k = 0; k < 2; ++k) \
;         acc[ai][bj][m][n] = __builtin_amdgcn_mfma_f32_16x16x32_bf16(Bt[n][k], At[m][k], acc[ai][bj][m][n], 0, 0, 0); __builtin_amdgcn_s_setprio(0); } while (0)
; #define PG8_WAIT_V(n) asm volatile("s_waitcnt vmcnt(" #n ")" ::: "memory")
; #define PG8_BAR __builtin_amdgcn_s_barrier()
;     DI void operator()(const f32x4 (&acc)[2][2][4][2], const Unit& u, int wr, int wc, int fr, int fq) const {
;     ...
;             for (int m = 0; m < 4; ++m) { u16* rowp = O + (size_t)(row0 + ai * HALF + m * 16) * ldc + hcol0;
; #pragma unroll
;                 for (int bj = 0; bj < 2; ++bj) { const f32x4 g = acc[ai][bj][m][0], up = acc[ai][bj][m][1]; float r[4];
; #pragma unroll
;                     for (int j = 0; j < 4; ++j) r[j] = g[j] * up[j] * __builtin_amdgcn_rcpf(1.f + ex2(-LOG2E * g[j]));
;                     uint2 w = {pack2(r[0], r[1]), pack2(r[2], r[3])}; *(uint2*)(rowp + bj * (HALF / 2)) = w; } }
; template <class Epi, class Sched, bool STAMP = false>
; __device__ __forceinline__ void gemm_phase(PG8_LAS unsigned char* lds, const Gemm g, const Sched& S, const Epi& E, unsigned long long* stamps) {
;     ...
;             PG8_WAIT_V(6); PG8_BAR; PG8_MMA(1, 1, At, B1); PG8_BAR;
;         }
;         PG8_STAMP();
;         if constexpr (!Epi::AFTER_DRAIN) { E(acc, cur, wr, wc, fr, fq); S.done(cur); }
	s_setprio 1
	v_mfma_f32_16x16x32_bf16 v[52:55], v[210:213], v[178:181], v[52:55]
	v_mfma_f32_16x16x32_bf16 v[48:51], v[218:221], v[178:181], v[48:51]
	v_mfma_f32_16x16x32_bf16 v[36:39], v[210:213], v[186:189], v[36:39]
	v_mfma_f32_16x16x32_bf16 v[32:35], v[218:221], v[186:189], v[32:35]
	v_mfma_f32_16x16x32_bf16 v[20:23], v[210:213], v[194:197], v[20:23]
	v_mfma_f32_16x16x32_bf16 v[16:19], v[218:221], v[194:197], v[16:19]
	v_mfma_f32_16x16x32_bf16 v[4:7], v[210:213], v[202:205], v[4:7]
	v_mfma_f32_16x16x32_bf16 v[0:3], v[218:221], v[202:205], v[0:3]
	v_mfma_f32_16x16x32_bf16 v[52:55], v[214:217], v[182:185], v[52:55]
	v_mfma_f32_16x16x32_bf16 v[48:51], v[222:225], v[182:185], v[48:51]
	v_mfma_f32_16x16x32_bf16 v[36:39], v[214:217], v[190:193], v[36:39]
	v_mfma_f32_16x16x32_bf16 v[32:35], v[222:225], v[190:193], v[32:35]
	v_mfma_f32_16x16x32_bf16 v[20:23], v[214:217], v[198:201], v[20:23]
	v_mfma_f32_16x16x32_bf16 v[16:19], v[222:225], v[198:201], v[16:19]
	v_mfma_f32_16x16x32_bf16 v[4:7], v[214:217], v[206:209], v[4:7]
	v_mfma_f32_16x16x32_bf16 v[0:3], v[222:225], v[206:209], v[0:3]
	s_setprio 0
	s_add_i32 s77, s77, 2
	s_add_u32 s75, s75, 0x100
	s_addc_u32 s76, s76, 0
	s_cmp_gt_u32 s77, 13
	s_mov_b64 s[14:15], s[16:17]
	s_barrier
	s_cbranch_scc0 .LBB0_63
	v_exp_f32_e64 v168, -v124
	v_exp_f32_e64 v169, -v125
	v_exp_f32_e64 v170, -v126
	v_exp_f32_e64 v171, -v127
	v_add_f32_e32 v168, 1.0, v168
	v_add_f32_e32 v169, 1.0, v169
	v_add_f32_e32 v170, 1.0, v170
	v_add_f32_e32 v171, 1.0, v171
	v_rcp_f32_e32 v168, v168
	v_rcp_f32_e32 v169, v169
	v_rcp_f32_e32 v170, v170
	v_rcp_f32_e32 v171, v171
	s_lshl_b32 s10, s74, 8
	v_pk_mul_f32 v[122:123], v[126:127], v[122:123]
	v_pk_mul_f32 v[120:121], v[124:125], v[120:121]
	s_or_b32 s10, s10, s60
	v_pk_mul_f32 v[120:121], v[120:121], v[168:169]
	v_pk_mul_f32 v[122:123], v[122:123], v[170:171]
	s_ashr_i32 s10, s10, 1
	v_cvt_pk_bf16_f32 v120, v120, v121
	v_cvt_pk_bf16_f32 v121, v122, v123
	v_or_b32_e32 v140, s10, v147
	v_exp_f32_e64 v122, -v116
	v_exp_f32_e64 v123, -v117
	v_lshl_add_u32 v165, s73, 8, v145
	v_ashrrev_i32_e32 v141, 31, v140
	v_mov_b64_e32 v[142:143], s[12:13]
	v_mad_i64_i32 v[166:167], s[14:15], v165, s70, v[142:143]
	v_lshlrev_b64 v[140:141], 1, v[140:141]
	v_lshl_add_u64 v[166:167], v[166:167], 0, v[140:141]
	global_store_dwordx2 v[166:167], v[120:121], off
	v_add_f32_e32 v120, 1.0, v122
	v_add_f32_e32 v121, 1.0, v123
	v_exp_f32_e64 v122, -v118
	v_exp_f32_e64 v123, -v119
	v_rcp_f32_e32 v120, v120
	v_rcp_f32_e32 v121, v121
	v_add_f32_e32 v122, 1.0, v122
	v_add_f32_e32 v123, 1.0, v123
	v_rcp_f32_e32 v122, v122
	v_rcp_f32_e32 v123, v123
	v_pk_mul_f32 v[114:115], v[118:119], v[114:115]
	v_pk_mul_f32 v[112:113], v[116:117], v[112:113]
	v_pk_mul_f32 v[112:113], v[112:113], v[120:121]
	v_pk_mul_f32 v[114:115], v[114:115], v[122:123]
	v_cvt_pk_bf16_f32 v112, v112, v113
	v_cvt_pk_bf16_f32 v113, v114, v115
	v_exp_f32_e64 v114, -v108
	v_exp_f32_e64 v115, -v109
	v_exp_f32_e64 v116, -v110
	v_exp_f32_e64 v117, -v111
	v_add_f32_e32 v114, 1.0, v114
	v_add_f32_e32 v115, 1.0, v115
	v_add_f32_e32 v116, 1.0, v116
	v_add_f32_e32 v117, 1.0, v117
	v_rcp_f32_e32 v114, v114
	v_rcp_f32_e32 v115, v115
	v_rcp_f32_e32 v116, v116
	v_rcp_f32_e32 v117, v117
	v_pk_mul_f32 v[106:107], v[110:111], v[106:107]
	v_pk_mul_f32 v[104:105], v[108:109], v[104:105]
	global_store_dwordx2 v[166:167], v[112:113], off offset:128
	v_pk_mul_f32 v[104:105], v[104:105], v[114:115]
	v_pk_mul_f32 v[106:107], v[106:107], v[116:117]
	v_cvt_pk_bf16_f32 v104, v104, v105
	v_cvt_pk_bf16_f32 v105, v106, v107
	v_exp_f32_e64 v106, -v100
	v_exp_f32_e64 v107, -v101
	v_or_b32_e32 v112, 16, v165
	v_mad_i64_i32 v[112:113], s[14:15], v112, s70, v[142:143]
	v_lshl_add_u64 v[112:113], v[112:113], 0, v[140:141]
	global_store_dwordx2 v[112:113], v[104:105], off
	v_add_f32_e32 v104, 1.0, v106
	v_add_f32_e32 v105, 1.0, v107
	v_exp_f32_e64 v106, -v102
	v_exp_f32_e64 v107, -v103
	v_rcp_f32_e32 v104, v104
	v_rcp_f32_e32 v105, v105
	v_add_f32_e32 v106, 1.0, v106
	v_add_f32_e32 v107, 1.0, v107
	v_rcp_f32_e32 v106, v106
	v_rcp_f32_e32 v107, v107
	v_pk_mul_f32 v[98:99], v[102:103], v[98:99]
	v_pk_mul_f32 v[96:97], v[100:101], v[96:97]
	v_pk_mul_f32 v[96:97], v[96:97], v[104:105]
	v_pk_mul_f32 v[98:99], v[98:99], v[106:107]
	v_cvt_pk_bf16_f32 v96, v96, v97
	v_cvt_pk_bf16_f32 v97, v98, v99
	v_exp_f32_e64 v98, -v92
	v_exp_f32_e64 v99, -v93
	v_exp_f32_e64 v100, -v94
	v_exp_f32_e64 v101, -v95
	v_add_f32_e32 v98, 1.0, v98
	v_add_f32_e32 v99, 1.0, v99
	v_add_f32_e32 v100, 1.0, v100
	v_add_f32_e32 v101, 1.0, v101
	v_rcp_f32_e32 v98, v98
	v_rcp_f32_e32 v99, v99
	v_rcp_f32_e32 v100, v100
	v_rcp_f32_e32 v101, v101
	v_pk_mul_f32 v[90:91], v[94:95], v[90:91]
	v_pk_mul_f32 v[88:89], v[92:93], v[88:89]
	global_store_dwordx2 v[112:113], v[96:97], off offset:128
	v_pk_mul_f32 v[88:89], v[88:89], v[98:99]
	v_pk_mul_f32 v[90:91], v[90:91], v[100:101]
	v_cvt_pk_bf16_f32 v88, v88, v89
	v_cvt_pk_bf16_f32 v89, v90, v91
	v_exp_f32_e64 v90, -v84
	v_exp_f32_e64 v91, -v85
	v_or_b32_e32 v96, 32, v165
	v_mad_i64_i32 v[96:97], s[14:15], v96, s70, v[142:143]
	v_lshl_add_u64 v[96:97], v[96:97], 0, v[140:141]
	global_store_dwordx2 v[96:97], v[88:89], off
	v_add_f32_e32 v88, 1.0, v90
	v_add_f32_e32 v89, 1.0, v91
	v_exp_f32_e64 v90, -v86
	v_exp_f32_e64 v91, -v87
	v_rcp_f32_e32 v88, v88
	v_rcp_f32_e32 v89, v89
	v_add_f32_e32 v90, 1.0, v90
	v_add_f32_e32 v91, 1.0, v91
	v_rcp_f32_e32 v90, v90
	v_rcp_f32_e32 v91, v91
	v_pk_mul_f32 v[82:83], v[86:87], v[82:83]
	v_pk_mul_f32 v[80:81], v[84:85], v[80:81]
	v_pk_mul_f32 v[80:81], v[80:81], v[88:89]
	v_pk_mul_f32 v[82:83], v[82:83], v[90:91]
	v_cvt_pk_bf16_f32 v80, v80, v81
; DI float ex2(float x) { return __builtin_amdgcn_exp2f(x); }
;     DI void operator()(const f32x4 (&acc)[2][2][4][2], const Unit& u, int wr, int wc, int fr, int fq) const {
;     ...
;             for (int m = 0; m < 4; ++m) { u16* rowp = O + (size_t)(row0 + ai * HALF + m * 16) * ldc + hcol0;
; #pragma unroll
;                 for (int bj = 0; bj < 2; ++bj) { const f32x4 g = acc[ai][bj][m][0], up = acc[ai][bj][m][1]; float r[4];
; #pragma unroll
;                     for (int j = 0; j < 4; ++j) r[j] = g[j] * up[j] * __builtin_amdgcn_rcpf(1.f + ex2(-LOG2E * g[j]));
;                     uint2 w = {pack2(r[0], r[1]), pack2(r[2], r[3])}; *(uint2*)(rowp + bj * (HALF / 2)) = w; } }
	v_cvt_pk_bf16_f32 v81, v82, v83
	v_exp_f32_e64 v82, -v76
	v_exp_f32_e64 v83, -v77
	v_exp_f32_e64 v84, -v78
	v_exp_f32_e64 v85, -v79
	v_add_f32_e32 v82, 1.0, v82
	v_add_f32_e32 v83, 1.0, v83
	v_add_f32_e32 v84, 1.0, v84
	v_add_f32_e32 v85, 1.0, v85
	v_rcp_f32_e32 v82, v82
	v_rcp_f32_e32 v83, v83
	v_rcp_f32_e32 v84, v84
	v_rcp_f32_e32 v85, v85
	v_pk_mul_f32 v[74:75], v[78:79], v[74:75]
	v_pk_mul_f32 v[72:73], v[76:77], v[72:73]
	global_store_dwordx2 v[96:97], v[80:81], off offset:128
	v_pk_mul_f32 v[72:73], v[72:73], v[82:83]
	v_pk_mul_f32 v[74:75], v[74:75], v[84:85]
	v_cvt_pk_bf16_f32 v72, v72, v73
	v_cvt_pk_bf16_f32 v73, v74, v75
	v_exp_f32_e64 v74, -v68
	v_exp_f32_e64 v75, -v69
	v_or_b32_e32 v80, 48, v165
	v_mad_i64_i32 v[80:81], s[14:15], v80, s70, v[142:143]
	v_lshl_add_u64 v[80:81], v[80:81], 0, v[140:141]
	global_store_dwordx2 v[80:81], v[72:73], off
	v_add_f32_e32 v72, 1.0, v74
	v_add_f32_e32 v73, 1.0, v75
	v_exp_f32_e64 v74, -v70
	v_exp_f32_e64 v75, -v71
	v_rcp_f32_e32 v72, v72
	v_rcp_f32_e32 v73, v73
	v_add_f32_e32 v74, 1.0, v74
	v_add_f32_e32 v75, 1.0, v75
	v_rcp_f32_e32 v74, v74
	v_rcp_f32_e32 v75, v75
	v_pk_mul_f32 v[66:67], v[70:71], v[66:67]
	v_pk_mul_f32 v[64:65], v[68:69], v[64:65]
	v_pk_mul_f32 v[64:65], v[64:65], v[72:73]
	v_pk_mul_f32 v[66:67], v[66:67], v[74:75]
	v_cvt_pk_bf16_f32 v64, v64, v65
	v_cvt_pk_bf16_f32 v65, v66, v67
	v_exp_f32_e64 v66, -v60
	v_exp_f32_e64 v67, -v61
	v_exp_f32_e64 v68, -v62
	v_exp_f32_e64 v69, -v63
	v_add_f32_e32 v66, 1.0, v66
	v_add_f32_e32 v67, 1.0, v67
	v_add_f32_e32 v68, 1.0, v68
	v_add_f32_e32 v69, 1.0, v69
	v_rcp_f32_e32 v66, v66
	v_rcp_f32_e32 v67, v67
	v_rcp_f32_e32 v68, v68
	v_rcp_f32_e32 v69, v69
	v_pk_mul_f32 v[58:59], v[62:63], v[58:59]
	v_pk_mul_f32 v[56:57], v[60:61], v[56:57]
	global_store_dwordx2 v[80:81], v[64:65], off offset:128
	v_pk_mul_f32 v[56:57], v[56:57], v[66:67]
	v_pk_mul_f32 v[58:59], v[58:59], v[68:69]
	v_cvt_pk_bf16_f32 v56, v56, v57
	v_cvt_pk_bf16_f32 v57, v58, v59
	v_exp_f32_e64 v58, -v52
	v_exp_f32_e64 v59, -v53
	v_add_u32_e32 v64, 0x80, v165
	v_mad_i64_i32 v[64:65], s[14:15], v64, s70, v[142:143]
	v_lshl_add_u64 v[64:65], v[64:65], 0, v[140:141]
	global_store_dwordx2 v[64:65], v[56:57], off
	v_add_f32_e32 v56, 1.0, v58
	v_add_f32_e32 v57, 1.0, v59
	v_exp_f32_e64 v58, -v54
	v_exp_f32_e64 v59, -v55
	v_rcp_f32_e32 v56, v56
	v_rcp_f32_e32 v57, v57
	v_add_f32_e32 v58, 1.0, v58
	v_add_f32_e32 v59, 1.0, v59
	v_rcp_f32_e32 v58, v58
	v_rcp_f32_e32 v59, v59
	v_pk_mul_f32 v[50:51], v[54:55], v[50:51]
	v_pk_mul_f32 v[48:49], v[52:53], v[48:49]
	v_pk_mul_f32 v[48:49], v[48:49], v[56:57]
	v_pk_mul_f32 v[50:51], v[50:51], v[58:59]
	v_cvt_pk_bf16_f32 v48, v48, v49
	v_cvt_pk_bf16_f32 v49, v50, v51
	v_exp_f32_e64 v50, -v44
	v_exp_f32_e64 v51, -v45
	v_exp_f32_e64 v52, -v46
	v_exp_f32_e64 v53, -v47
	v_add_f32_e32 v50, 1.0, v50
	v_add_f32_e32 v51, 1.0, v51
	v_add_f32_e32 v52, 1.0, v52
	v_add_f32_e32 v53, 1.0, v53
	v_rcp_f32_e32 v50, v50
	v_rcp_f32_e32 v51, v51
	v_rcp_f32_e32 v52, v52
	v_rcp_f32_e32 v53, v53
	v_pk_mul_f32 v[42:43], v[46:47], v[42:43]
	v_pk_mul_f32 v[40:41], v[44:45], v[40:41]
	global_store_dwordx2 v[64:65], v[48:49], off offset:128
	v_pk_mul_f32 v[40:41], v[40:41], v[50:51]
	v_pk_mul_f32 v[42:43], v[42:43], v[52:53]
	v_cvt_pk_bf16_f32 v40, v40, v41
	v_cvt_pk_bf16_f32 v41, v42, v43
	v_exp_f32_e64 v42, -v36
	v_exp_f32_e64 v43, -v37
	v_add_u32_e32 v48, 0x90, v165
	v_mad_i64_i32 v[48:49], s[14:15], v48, s70, v[142:143]
	v_lshl_add_u64 v[48:49], v[48:49], 0, v[140:141]
	global_store_dwordx2 v[48:49], v[40:41], off
	v_add_f32_e32 v40, 1.0, v42
	v_add_f32_e32 v41, 1.0, v43
	v_exp_f32_e64 v42, -v38
	v_exp_f32_e64 v43, -v39
	v_rcp_f32_e32 v40, v40
	v_rcp_f32_e32 v41, v41
	v_add_f32_e32 v42, 1.0, v42
	v_add_f32_e32 v43, 1.0, v43
	v_rcp_f32_e32 v42, v42
	v_rcp_f32_e32 v43, v43
	v_pk_mul_f32 v[34:35], v[38:39], v[34:35]
	v_pk_mul_f32 v[32:33], v[36:37], v[32:33]
	v_pk_mul_f32 v[32:33], v[32:33], v[40:41]
	v_pk_mul_f32 v[34:35], v[34:35], v[42:43]
	v_cvt_pk_bf16_f32 v32, v32, v33
	v_cvt_pk_bf16_f32 v33, v34, v35
	v_exp_f32_e64 v34, -v28
	v_exp_f32_e64 v35, -v29
	v_exp_f32_e64 v36, -v30
	v_exp_f32_e64 v37, -v31
	v_add_f32_e32 v34, 1.0, v34
	v_add_f32_e32 v35, 1.0, v35
	v_add_f32_e32 v36, 1.0, v36
	v_add_f32_e32 v37, 1.0, v37
	v_rcp_f32_e32 v34, v34
	v_rcp_f32_e32 v35, v35
	v_rcp_f32_e32 v36, v36
	v_rcp_f32_e32 v37, v37
	v_pk_mul_f32 v[26:27], v[30:31], v[26:27]
	v_pk_mul_f32 v[24:25], v[28:29], v[24:25]
	global_store_dwordx2 v[48:49], v[32:33], off offset:128
	v_pk_mul_f32 v[24:25], v[24:25], v[34:35]
	v_pk_mul_f32 v[26:27], v[26:27], v[36:37]
	v_cvt_pk_bf16_f32 v24, v24, v25
	v_cvt_pk_bf16_f32 v25, v26, v27
	v_exp_f32_e64 v26, -v20
	v_exp_f32_e64 v27, -v21
	v_add_u32_e32 v32, 0xa0, v165
	v_mad_i64_i32 v[32:33], s[14:15], v32, s70, v[142:143]
	v_lshl_add_u64 v[32:33], v[32:33], 0, v[140:141]
	global_store_dwordx2 v[32:33], v[24:25], off
	v_add_f32_e32 v24, 1.0, v26
	v_add_f32_e32 v25, 1.0, v27
	v_exp_f32_e64 v26, -v22
	v_exp_f32_e64 v27, -v23
	v_rcp_f32_e32 v24, v24
	v_rcp_f32_e32 v25, v25
	v_add_f32_e32 v26, 1.0, v26
	v_add_f32_e32 v27, 1.0, v27
	v_rcp_f32_e32 v26, v26
	v_rcp_f32_e32 v27, v27
	v_pk_mul_f32 v[18:19], v[22:23], v[18:19]
	v_pk_mul_f32 v[16:17], v[20:21], v[16:17]
	v_pk_mul_f32 v[16:17], v[16:17], v[24:25]
	v_pk_mul_f32 v[18:19], v[18:19], v[26:27]
	v_cvt_pk_bf16_f32 v16, v16, v17
	v_cvt_pk_bf16_f32 v17, v18, v19
	v_exp_f32_e64 v18, -v12
	v_exp_f32_e64 v19, -v13
	v_exp_f32_e64 v20, -v14
	v_exp_f32_e64 v21, -v15
	v_add_f32_e32 v18, 1.0, v18
	v_add_f32_e32 v19, 1.0, v19
	v_add_f32_e32 v20, 1.0, v20
	v_add_f32_e32 v21, 1.0, v21
	v_rcp_f32_e32 v18, v18
	v_rcp_f32_e32 v19, v19
	v_rcp_f32_e32 v20, v20
	v_rcp_f32_e32 v21, v21
	v_pk_mul_f32 v[10:11], v[14:15], v[10:11]
	v_pk_mul_f32 v[8:9], v[12:13], v[8:9]
	global_store_dwordx2 v[32:33], v[16:17], off offset:128
	v_pk_mul_f32 v[8:9], v[8:9], v[18:19]
	v_pk_mul_f32 v[10:11], v[10:11], v[20:21]
	v_cvt_pk_bf16_f32 v8, v8, v9
	v_cvt_pk_bf16_f32 v9, v10, v11
	v_exp_f32_e64 v10, -v4
	v_exp_f32_e64 v11, -v5
	v_add_u32_e32 v16, 0xb0, v165
	v_mad_i64_i32 v[16:17], s[14:15], v16, s70, v[142:143]
	v_lshl_add_u64 v[16:17], v[16:17], 0, v[140:141]
	global_store_dwordx2 v[16:17], v[8:9], off
	v_add_f32_e32 v8, 1.0, v10
	v_add_f32_e32 v9, 1.0, v11
	v_exp_f32_e64 v10, -v6
	v_exp_f32_e64 v11, -v7
	v_rcp_f32_e32 v8, v8
	v_rcp_f32_e32 v9, v9
	v_add_f32_e32 v10, 1.0, v10
	v_add_f32_e32 v11, 1.0, v11
	v_rcp_f32_e32 v10, v10
	v_rcp_f32_e32 v11, v11
	v_pk_mul_f32 v[2:3], v[6:7], v[2:3]
	v_pk_mul_f32 v[0:1], v[4:5], v[0:1]
	s_and_b64 vcc, exec, s[2:3]
	v_pk_mul_f32 v[0:1], v[0:1], v[8:9]
	v_pk_mul_f32 v[2:3], v[2:3], v[10:11]
	v_cvt_pk_bf16_f32 v0, v0, v1
	v_cvt_pk_bf16_f32 v1, v2, v3
	s_mov_b32 s74, s71
	s_mov_b32 s73, s72
	s_mov_b64 s[16:17], s[0:1]
	s_mov_b64 s[14:15], s[4:5]
	global_store_dwordx2 v[16:17], v[0:1], off offset:128
	s_cbranch_vccz .LBB0_56
	s_branch .Lgu1_done

; #define PG8_STAGE(bufoff, gbase, voff) do { _Pragma("unroll") for (int _i = 0; _i < 2; ++_i) \
;         __builtin_amdgcn_global_load_lds((const unsigned*)((const char*)(gbase) + (voff)[_i]), (PG8_LAS unsigned*)(lds + (bufoff) + ldsw + _i * 8192), 16, 0, 0); } while (0)
; #define PG8_LDA(dst, b, h) do { _Pragma("unroll") for (int m = 0; m < 4; ++m) _Pragma("unroll") for (int k = 0; k < 2; ++k) dst[m][k] = *(const PG8_LAS bf16x8*)(lds + PG8_SA(b, h) + aoff + m * 2048 + k * 1024); } while (0)
; #define PG8_LDB(dst, b, h) do { _Pragma("unroll") for (int n = 0; n < 2; ++n) _Pragma("unroll") for (int k = 0; k < 2; ++k) dst[n][k] = *(const PG8_LAS bf16x8*)(lds + PG8_SB(b, h) + boff + n * 2048 + k * 1024); } while (0)
; #define PG8_WAIT_V(n) asm volatile("s_waitcnt vmcnt(" #n ")" ::: "memory")
; #define PG8_WAIT_L(n) asm volatile("s_waitcnt lgkmcnt(" #n ")" ::: "memory")
; #define PG8_BAR __builtin_amdgcn_s_barrier()
; template <class Epi, class Sched, bool STAMP = false>
; __device__ __forceinline__ void gemm_phase(PG8_LAS unsigned char* lds, const Gemm g, const Sched& S, const Epi& E, unsigned long long* stamps) {
;     ...
;             PG8_LDB(B0, 0, 0); PG8_SCHED; PG8_LDA(At, 0, 0); PG8_STAGE(PG8_SA(1, 1), a1 + hstep, voffA);
;             PG8_WAIT_L(8); PG8_BAR; PG8_WAIT_L(0); PG8_MMA(0, 0, At, B0); PG8_BAR; PG8_SCHED;
;             PG8_LDB(B1, 0, 1); PG8_STAGE(PG8_SB(0, 0), b2, voffB);
;             PG8_BAR; PG8_WAIT_L(0); PG8_MMA(0, 1, At, B1); PG8_BAR;
;             PG8_LDA(At, 0, 1); PG8_STAGE(PG8_SA(0, 0), a2, voffA);
;             PG8_BAR; PG8_WAIT_L(0); PG8_MMA(1, 0, At, B0); PG8_BAR; PG8_SCHED;
;             PG8_STAGE(PG8_SB(0, 1), b2 + hstep, voffB);
;             PG8_WAIT_V(6); PG8_BAR; PG8_MMA(1, 1, At, B1); PG8_BAR;
;             PG8_LDB(B0, 1, 0); PG8_SCHED; PG8_LDA(At, 1, 0); PG8_STAGE(PG8_SA(0, 1), a2 + hstep, voffA);
;             PG8_WAIT_L(8); PG8_BAR; PG8_WAIT_L(0); PG8_MMA(0, 0, At, B0); PG8_BAR; PG8_SCHED;
;             PG8_LDB(B1, 1, 1); PG8_STAGE(PG8_SB(1, 0), b3, voffB);
;             PG8_BAR; PG8_WAIT_L(0); PG8_MMA(0, 1, At, B1); PG8_BAR;
;             PG8_LDA(At, 1, 1); PG8_STAGE(PG8_SA(1, 0), a3, voffA);
;             PG8_BAR; PG8_WAIT_L(0); PG8_MMA(1, 0, At, B0); PG8_BAR; PG8_SCHED;
;             PG8_STAGE(PG8_SB(1, 1), b3 + hstep, voffB);
;             PG8_WAIT_V(6); PG8_BAR; PG8_MMA(1, 1, At, B1); PG8_BAR;
.Lgu1_half_loop:
	ds_read_b128 v[140:143], v148
	ds_read_b128 v[166:169], v149
	ds_read_b128 v[170:173], v150
	ds_read_b128 v[174:177], v151
	s_add_u32 s16, s14, 0x100
	s_addc_u32 s17, s15, 0
	s_cmp_eq_u32 s77, 12
	s_cselect_b32 s29, s5, s17
	s_cselect_b32 s28, s4, s16
	s_cselect_b32 s19, s1, s76
	s_cselect_b32 s18, s0, s75
	s_mov_b32 m0, s68
	ds_read_b128 v[178:181], v146
	ds_read_b128 v[182:185], v146 offset:1024
	ds_read_b128 v[186:189], v146 offset:2048
	ds_read_b128 v[190:193], v146 offset:3072
	ds_read_b128 v[194:197], v146 offset:4096
	ds_read_b128 v[198:201], v146 offset:5120
	ds_read_b128 v[202:205], v146 offset:6144
	ds_read_b128 v[206:209], v146 offset:7168
	global_load_lds_dwordx4 v132, s[14:15]
	s_mov_b32 m0, s69
	s_nop 0
	global_load_lds_dwordx4 v134, s[14:15]
	s_waitcnt lgkmcnt(8)
	s_barrier
	s_waitcnt lgkmcnt(0)
	s_setprio 1
	s_waitcnt lgkmcnt(0)
	v_mfma_f32_16x16x32_bf16 v[124:127], v[140:143], v[178:181], v[124:127]
	v_mfma_f32_16x16x32_bf16 v[120:123], v[170:173], v[178:181], v[120:123]
	v_mfma_f32_16x16x32_bf16 v[108:111], v[140:143], v[186:189], v[108:111]
	v_mfma_f32_16x16x32_bf16 v[104:107], v[170:173], v[186:189], v[104:107]
	v_mfma_f32_16x16x32_bf16 v[92:95], v[140:143], v[194:197], v[92:95]
	v_mfma_f32_16x16x32_bf16 v[88:91], v[170:173], v[194:197], v[88:91]
	v_mfma_f32_16x16x32_bf16 v[76:79], v[140:143], v[202:205], v[76:79]
	v_mfma_f32_16x16x32_bf16 v[72:75], v[170:173], v[202:205], v[72:75]
	v_mfma_f32_16x16x32_bf16 v[124:127], v[166:169], v[182:185], v[124:127]
	v_mfma_f32_16x16x32_bf16 v[120:123], v[174:177], v[182:185], v[120:123]
	v_mfma_f32_16x16x32_bf16 v[108:111], v[166:169], v[190:193], v[108:111]
	v_mfma_f32_16x16x32_bf16 v[104:107], v[174:177], v[190:193], v[104:107]
	v_mfma_f32_16x16x32_bf16 v[92:95], v[166:169], v[198:201], v[92:95]
	v_mfma_f32_16x16x32_bf16 v[88:91], v[174:177], v[198:201], v[88:91]
	v_mfma_f32_16x16x32_bf16 v[76:79], v[166:169], v[206:209], v[76:79]
	v_mfma_f32_16x16x32_bf16 v[72:75], v[174:177], v[206:209], v[72:75]
	s_setprio 0
	s_barrier
	s_mov_b32 m0, s52
	s_nop 0
	global_load_lds_dwordx4 v130, s[18:19]
	s_mov_b32 m0, s53
	s_nop 0
	global_load_lds_dwordx4 v128, s[18:19]
	s_barrier
	s_waitcnt lgkmcnt(0)
	s_setprio 1
	s_waitcnt lgkmcnt(0)
	s_setprio 0
	s_mov_b32 m0, s33
	s_barrier
	ds_read_b128 v[178:181], v146 offset:16384
	ds_read_b128 v[182:185], v146 offset:17408
	ds_read_b128 v[186:189], v146 offset:18432
	ds_read_b128 v[190:193], v146 offset:19456
	ds_read_b128 v[194:197], v146 offset:20480
	ds_read_b128 v[198:201], v146 offset:21504
	ds_read_b128 v[202:205], v146 offset:22528
	ds_read_b128 v[206:209], v146 offset:23552
	global_load_lds_dwordx4 v130, s[28:29]
	s_mov_b32 m0, s54
	s_nop 0
	global_load_lds_dwordx4 v128, s[28:29]
	s_barrier
	s_waitcnt lgkmcnt(0)
	s_setprio 1
	s_waitcnt lgkmcnt(0)
	v_mfma_f32_16x16x32_bf16 v[60:63], v[140:143], v[178:181], v[60:63]
	v_mfma_f32_16x16x32_bf16 v[56:59], v[170:173], v[178:181], v[56:59]
	v_mfma_f32_16x16x32_bf16 v[44:47], v[140:143], v[186:189], v[44:47]
	v_mfma_f32_16x16x32_bf16 v[40:43], v[170:173], v[186:189], v[40:43]
	v_mfma_f32_16x16x32_bf16 v[28:31], v[140:143], v[194:197], v[28:31]
	v_mfma_f32_16x16x32_bf16 v[24:27], v[170:173], v[194:197], v[24:27]
	v_mfma_f32_16x16x32_bf16 v[12:15], v[140:143], v[202:205], v[12:15]
	v_mfma_f32_16x16x32_bf16 v[8:11], v[170:173], v[202:205], v[8:11]
	v_mfma_f32_16x16x32_bf16 v[60:63], v[166:169], v[182:185], v[60:63]
	v_mfma_f32_16x16x32_bf16 v[56:59], v[174:177], v[182:185], v[56:59]
	v_mfma_f32_16x16x32_bf16 v[44:47], v[166:169], v[190:193], v[44:47]
	v_mfma_f32_16x16x32_bf16 v[40:43], v[174:177], v[190:193], v[40:43]
	v_mfma_f32_16x16x32_bf16 v[28:31], v[166:169], v[198:201], v[28:31]
	v_mfma_f32_16x16x32_bf16 v[24:27], v[174:177], v[198:201], v[24:27]
	v_mfma_f32_16x16x32_bf16 v[12:15], v[166:169], v[206:209], v[12:15]
	v_mfma_f32_16x16x32_bf16 v[8:11], v[174:177], v[206:209], v[8:11]
	s_setprio 0
	s_barrier
	s_add_u32 s14, s18, 0x44000
	s_addc_u32 s15, s19, 0
	s_mov_b32 m0, s55
	s_nop 0
	global_load_lds_dwordx4 v130, s[14:15]
	s_mov_b32 m0, s56
	s_nop 0
	global_load_lds_dwordx4 v128, s[14:15]
	s_waitcnt vmcnt(6)
	s_barrier
	s_setprio 1
	s_setprio 0
	s_barrier
	ds_read_b128 v[140:143], v156
	ds_read_b128 v[166:169], v157
	ds_read_b128 v[170:173], v159
	ds_read_b128 v[174:177], v160
	s_add_u32 s14, s28, 0x44000
	s_addc_u32 s15, s29, 0
	s_mov_b32 m0, s57
	ds_read_b128 v[178:181], v146 offset:32768
	ds_read_b128 v[182:185], v146 offset:33792
	ds_read_b128 v[186:189], v146 offset:34816
	ds_read_b128 v[190:193], v146 offset:35840
	ds_read_b128 v[194:197], v146 offset:36864
	ds_read_b128 v[198:201], v146 offset:37888
	ds_read_b128 v[202:205], v146 offset:38912
	ds_read_b128 v[206:209], v146 offset:39936
	global_load_lds_dwordx4 v130, s[14:15]
	s_mov_b32 m0, s58
	s_nop 0
	global_load_lds_dwordx4 v128, s[14:15]
	s_waitcnt lgkmcnt(8)
	s_barrier
	s_waitcnt lgkmcnt(0)
	s_setprio 1
	s_waitcnt lgkmcnt(0)
	v_mfma_f32_16x16x32_bf16 v[124:127], v[140:143], v[178:181], v[124:127]
	v_mfma_f32_16x16x32_bf16 v[120:123], v[170:173], v[178:181], v[120:123]
	v_mfma_f32_16x16x32_bf16 v[108:111], v[140:143], v[186:189], v[108:111]
	v_mfma_f32_16x16x32_bf16 v[104:107], v[170:173], v[186:189], v[104:107]
	v_mfma_f32_16x16x32_bf16 v[92:95], v[140:143], v[194:197], v[92:95]
	v_mfma_f32_16x16x32_bf16 v[88:91], v[170:173], v[194:197], v[88:91]
	v_mfma_f32_16x16x32_bf16 v[76:79], v[140:143], v[202:205], v[76:79]
	v_mfma_f32_16x16x32_bf16 v[72:75], v[170:173], v[202:205], v[72:75]
	v_mfma_f32_16x16x32_bf16 v[124:127], v[166:169], v[182:185], v[124:127]
	v_mfma_f32_16x16x32_bf16 v[120:123], v[174:177], v[182:185], v[120:123]
	v_mfma_f32_16x16x32_bf16 v[108:111], v[166:169], v[190:193], v[108:111]
	v_mfma_f32_16x16x32_bf16 v[104:107], v[174:177], v[190:193], v[104:107]
	v_mfma_f32_16x16x32_bf16 v[92:95], v[166:169], v[198:201], v[92:95]
	v_mfma_f32_16x16x32_bf16 v[88:91], v[174:177], v[198:201], v[88:91]
	v_mfma_f32_16x16x32_bf16 v[76:79], v[166:169], v[206:209], v[76:79]
	v_mfma_f32_16x16x32_bf16 v[72:75], v[174:177], v[206:209], v[72:75]
	s_setprio 0
	s_barrier
; #define PG8_STAGE(bufoff, gbase, voff) do { _Pragma("unroll") for (int _i = 0; _i < 2; ++_i) \
;         __builtin_amdgcn_global_load_lds((const unsigned*)((const char*)(gbase) + (voff)[_i]), (PG8_LAS unsigned*)(lds + (bufoff) + ldsw + _i * 8192), 16, 0, 0); } while (0)
; #define PG8_LDA(dst, b, h) do { _Pragma("unroll") for (int m = 0; m < 4; ++m) _Pragma("unroll") for (int k = 0; k < 2; ++k) dst[m][k] = *(const PG8_LAS bf16x8*)(lds + PG8_SA(b, h) + aoff + m * 2048 + k * 1024); } while (0)
; #define PG8_LDB(dst, b, h) do { _Pragma("unroll") for (int n = 0; n < 2; ++n) _Pragma("unroll") for (int k = 0; k < 2; ++k) dst[n][k] = *(const PG8_LAS bf16x8*)(lds + PG8_SB(b, h) + boff + n * 2048 + k * 1024); } while (0)
; #define PG8_MMA(ai, bj, At, Bt) do { __builtin_amdgcn_s_setprio(1); _Pragma("unroll") for (int m = 0; m < 4; ++m) _Pragma("unroll") for (int n = 0; n < 2; ++n) _Pragma("unroll") for (int k = 0; k < 2; ++k) \
;         acc[ai][bj][m][n] = __builtin_amdgcn_mfma_f32_16x16x32_bf16(Bt[n][k], At[m][k], acc[ai][bj][m][n], 0, 0, 0); __builtin_amdgcn_s_setprio(0); } while (0)
; #define PG8_WAIT_V(n) asm volatile("s_waitcnt vmcnt(" #n ")" ::: "memory")
; #define PG8_WAIT_L(n) asm volatile("s_waitcnt lgkmcnt(" #n ")" ::: "memory")
; #define PG8_BAR __builtin_amdgcn_s_barrier()
; #define PG8_SCHED __builtin_amdgcn_sched_barrier(0)
; template <class Epi, class Sched, bool STAMP = false>
; __device__ __forceinline__ void gemm_phase(PG8_LAS unsigned char* lds, const Gemm g, const Sched& S, const Epi& E, unsigned long long* stamps) {
;     ...
;             PG8_LDB(B0, 1, 0); PG8_SCHED; PG8_LDA(At, 1, 0); PG8_STAGE(PG8_SA(0, 1), a2 + hstep, voffA);
;             PG8_WAIT_L(8); PG8_BAR; PG8_WAIT_L(0); PG8_MMA(0, 0, At, B0); PG8_BAR; PG8_SCHED;
;             PG8_LDB(B1, 1, 1); PG8_STAGE(PG8_SB(1, 0), b3, voffB);
;             PG8_BAR; PG8_WAIT_L(0); PG8_MMA(0, 1, At, B1); PG8_BAR;
;             PG8_LDA(At, 1, 1); PG8_STAGE(PG8_SA(1, 0), a3, voffA);
;             PG8_BAR; PG8_WAIT_L(0); PG8_MMA(1, 0, At, B0); PG8_BAR; PG8_SCHED;
;             PG8_STAGE(PG8_SB(1, 1), b3 + hstep, voffB);
;             PG8_WAIT_V(6); PG8_BAR; PG8_MMA(1, 1, At, B1); PG8_BAR;
;         }
	s_mov_b32 m0, s61
	s_add_u32 s100, s18, 0x80
	s_addc_u32 s101, s19, 0
	global_load_lds_dwordx4 v130, s[100:101]
	s_mov_b32 m0, s62
	s_nop 0
	global_load_lds_dwordx4 v128, s[100:101]
	s_barrier
	s_waitcnt lgkmcnt(0)
	s_setprio 1
	s_waitcnt lgkmcnt(0)
	s_setprio 0
	s_mov_b32 m0, s63
	s_barrier
	ds_read_b128 v[178:181], v146 offset:49152
	ds_read_b128 v[182:185], v146 offset:50176
	ds_read_b128 v[186:189], v146 offset:51200
	ds_read_b128 v[190:193], v146 offset:52224
	ds_read_b128 v[194:197], v146 offset:53248
	ds_read_b128 v[198:201], v146 offset:54272
	ds_read_b128 v[202:205], v146 offset:55296
	ds_read_b128 v[206:209], v146 offset:56320
	s_add_u32 s100, s28, 0x80
	s_addc_u32 s101, s29, 0
	global_load_lds_dwordx4 v130, s[100:101]
	s_mov_b32 m0, s64
	s_nop 0
	global_load_lds_dwordx4 v128, s[100:101]
	s_barrier
	s_waitcnt lgkmcnt(0)
	s_setprio 1
	s_waitcnt lgkmcnt(0)
	v_mfma_f32_16x16x32_bf16 v[60:63], v[140:143], v[178:181], v[60:63]
	v_mfma_f32_16x16x32_bf16 v[56:59], v[170:173], v[178:181], v[56:59]
	v_mfma_f32_16x16x32_bf16 v[44:47], v[140:143], v[186:189], v[44:47]
	v_mfma_f32_16x16x32_bf16 v[40:43], v[170:173], v[186:189], v[40:43]
	v_mfma_f32_16x16x32_bf16 v[28:31], v[140:143], v[194:197], v[28:31]
	v_mfma_f32_16x16x32_bf16 v[24:27], v[170:173], v[194:197], v[24:27]
	v_mfma_f32_16x16x32_bf16 v[12:15], v[140:143], v[202:205], v[12:15]
	v_mfma_f32_16x16x32_bf16 v[8:11], v[170:173], v[202:205], v[8:11]
	v_mfma_f32_16x16x32_bf16 v[60:63], v[166:169], v[182:185], v[60:63]
	v_mfma_f32_16x16x32_bf16 v[56:59], v[174:177], v[182:185], v[56:59]
	v_mfma_f32_16x16x32_bf16 v[44:47], v[166:169], v[190:193], v[44:47]
	v_mfma_f32_16x16x32_bf16 v[40:43], v[174:177], v[190:193], v[40:43]
	v_mfma_f32_16x16x32_bf16 v[28:31], v[166:169], v[198:201], v[28:31]
	v_mfma_f32_16x16x32_bf16 v[24:27], v[174:177], v[198:201], v[24:27]
	v_mfma_f32_16x16x32_bf16 v[12:15], v[166:169], v[206:209], v[12:15]
	v_mfma_f32_16x16x32_bf16 v[8:11], v[174:177], v[206:209], v[8:11]
	s_setprio 0
	s_barrier
	s_add_u32 s14, s18, 0x44080
	s_addc_u32 s15, s19, 0
	s_mov_b32 m0, s65
	s_nop 0
	global_load_lds_dwordx4 v130, s[14:15]
	s_mov_b32 m0, s66
	s_nop 0
	global_load_lds_dwordx4 v128, s[14:15]
	s_waitcnt vmcnt(6)
	s_barrier
	s_setprio 1
	s_setprio 0
	s_add_i32 s77, s77, 2
	s_add_u32 s75, s75, 0x100
	s_addc_u32 s76, s76, 0
	s_cmp_gt_u32 s77, 13
	s_mov_b64 s[14:15], s[16:17]
	s_barrier
	s_cbranch_scc0 .Lgu1_half_loop
; DI float ex2(float x) { return __builtin_amdgcn_exp2f(x); }
;     DI void operator()(const f32x4 (&acc)[2][2][4][2], const Unit& u, int wr, int wc, int fr, int fq) const {
;     ...
;             for (int m = 0; m < 4; ++m) { u16* rowp = O + (size_t)(row0 + ai * HALF + m * 16) * ldc + hcol0;
; #pragma unroll
;                 for (int bj = 0; bj < 2; ++bj) { const f32x4 g = acc[ai][bj][m][0], up = acc[ai][bj][m][1]; float r[4];
; #pragma unroll
;                     for (int j = 0; j < 4; ++j) r[j] = g[j] * up[j] * __builtin_amdgcn_rcpf(1.f + ex2(-LOG2E * g[j]));
;                     uint2 w = {pack2(r[0], r[1]), pack2(r[2], r[3])}; *(uint2*)(rowp + bj * (HALF / 2)) = w; } }
	v_exp_f32_e64 v168, -v124
	v_exp_f32_e64 v169, -v125
	v_exp_f32_e64 v170, -v126
	v_exp_f32_e64 v171, -v127
	v_add_f32_e32 v168, 1.0, v168
	v_add_f32_e32 v169, 1.0, v169
	v_add_f32_e32 v170, 1.0, v170
	v_add_f32_e32 v171, 1.0, v171
	v_rcp_f32_e32 v168, v168
	v_rcp_f32_e32 v169, v169
	v_rcp_f32_e32 v170, v170
	v_rcp_f32_e32 v171, v171
	s_lshl_b32 s10, s74, 8
	v_pk_mul_f32 v[122:123], v[126:127], v[122:123]
	v_pk_mul_f32 v[120:121], v[124:125], v[120:121]
	s_or_b32 s10, s10, s60
	s_or_b32 s10, s10, s98
	v_pk_mul_f32 v[120:121], v[120:121], v[168:169]
	v_pk_mul_f32 v[122:123], v[122:123], v[170:171]
	s_ashr_i32 s10, s10, 1
	v_cvt_pk_bf16_f32 v120, v120, v121
	v_cvt_pk_bf16_f32 v121, v122, v123
	v_or_b32_e32 v140, s10, v147
	v_lshl_add_u32 v165, s73, 8, v145
	v_ashrrev_i32_e32 v141, 31, v140
	v_mov_b64_e32 v[142:143], s[12:13]
	v_mad_i64_i32 v[166:167], s[14:15], v165, s70, v[142:143]
	v_lshlrev_b64 v[140:141], 1, v[140:141]
	v_lshl_add_u64 v[166:167], v[166:167], 0, v[140:141]
	global_store_dwordx2 v[166:167], v[120:121], off
	v_exp_f32_e64 v114, -v108
	v_exp_f32_e64 v115, -v109
	v_exp_f32_e64 v116, -v110
	v_exp_f32_e64 v117, -v111
	v_add_f32_e32 v114, 1.0, v114
	v_add_f32_e32 v115, 1.0, v115
	v_add_f32_e32 v116, 1.0, v116
	v_add_f32_e32 v117, 1.0, v117
	v_rcp_f32_e32 v114, v114
	v_rcp_f32_e32 v115, v115
	v_rcp_f32_e32 v116, v116
	v_rcp_f32_e32 v117, v117
	v_pk_mul_f32 v[106:107], v[110:111], v[106:107]
	v_pk_mul_f32 v[104:105], v[108:109], v[104:105]
	v_pk_mul_f32 v[104:105], v[104:105], v[114:115]
	v_pk_mul_f32 v[106:107], v[106:107], v[116:117]
	v_cvt_pk_bf16_f32 v104, v104, v105
	v_cvt_pk_bf16_f32 v105, v106, v107
	v_or_b32_e32 v112, 16, v165
	v_mad_i64_i32 v[112:113], s[14:15], v112, s70, v[142:143]
	v_lshl_add_u64 v[112:113], v[112:113], 0, v[140:141]
	global_store_dwordx2 v[112:113], v[104:105], off
	v_exp_f32_e64 v98, -v92
	v_exp_f32_e64 v99, -v93
	v_exp_f32_e64 v100, -v94
	v_exp_f32_e64 v101, -v95
	v_add_f32_e32 v98, 1.0, v98
	v_add_f32_e32 v99, 1.0, v99
	v_add_f32_e32 v100, 1.0, v100
	v_add_f32_e32 v101, 1.0, v101
	v_rcp_f32_e32 v98, v98
	v_rcp_f32_e32 v99, v99
	v_rcp_f32_e32 v100, v100
	v_rcp_f32_e32 v101, v101
	v_pk_mul_f32 v[90:91], v[94:95], v[90:91]
	v_pk_mul_f32 v[88:89], v[92:93], v[88:89]
	v_pk_mul_f32 v[88:89], v[88:89], v[98:99]
	v_pk_mul_f32 v[90:91], v[90:91], v[100:101]
	v_cvt_pk_bf16_f32 v88, v88, v89
	v_cvt_pk_bf16_f32 v89, v90, v91
	v_or_b32_e32 v96, 32, v165
	v_mad_i64_i32 v[96:97], s[14:15], v96, s70, v[142:143]
	v_lshl_add_u64 v[96:97], v[96:97], 0, v[140:141]
	global_store_dwordx2 v[96:97], v[88:89], off
	v_exp_f32_e64 v82, -v76
	v_exp_f32_e64 v83, -v77
	v_exp_f32_e64 v84, -v78
	v_exp_f32_e64 v85, -v79
	v_add_f32_e32 v82, 1.0, v82
	v_add_f32_e32 v83, 1.0, v83
	v_add_f32_e32 v84, 1.0, v84
	v_add_f32_e32 v85, 1.0, v85
	v_rcp_f32_e32 v82, v82
	v_rcp_f32_e32 v83, v83
	v_rcp_f32_e32 v84, v84
	v_rcp_f32_e32 v85, v85
	v_pk_mul_f32 v[74:75], v[78:79], v[74:75]
	v_pk_mul_f32 v[72:73], v[76:77], v[72:73]
	v_pk_mul_f32 v[72:73], v[72:73], v[82:83]
	v_pk_mul_f32 v[74:75], v[74:75], v[84:85]
	v_cvt_pk_bf16_f32 v72, v72, v73
	v_cvt_pk_bf16_f32 v73, v74, v75
	v_or_b32_e32 v80, 48, v165
	v_mad_i64_i32 v[80:81], s[14:15], v80, s70, v[142:143]
	v_lshl_add_u64 v[80:81], v[80:81], 0, v[140:141]
	global_store_dwordx2 v[80:81], v[72:73], off
	v_exp_f32_e64 v66, -v60
	v_exp_f32_e64 v67, -v61
	v_exp_f32_e64 v68, -v62
	v_exp_f32_e64 v69, -v63
	v_add_f32_e32 v66, 1.0, v66
	v_add_f32_e32 v67, 1.0, v67
	v_add_f32_e32 v68, 1.0, v68
	v_add_f32_e32 v69, 1.0, v69
	v_rcp_f32_e32 v66, v66
	v_rcp_f32_e32 v67, v67
	v_rcp_f32_e32 v68, v68
	v_rcp_f32_e32 v69, v69
	v_pk_mul_f32 v[58:59], v[62:63], v[58:59]
	v_pk_mul_f32 v[56:57], v[60:61], v[56:57]
	v_pk_mul_f32 v[56:57], v[56:57], v[66:67]
	v_pk_mul_f32 v[58:59], v[58:59], v[68:69]
	v_cvt_pk_bf16_f32 v56, v56, v57
	v_cvt_pk_bf16_f32 v57, v58, v59
	v_add_u32_e32 v64, 0x80, v165
	v_mad_i64_i32 v[64:65], s[14:15], v64, s70, v[142:143]
	v_lshl_add_u64 v[64:65], v[64:65], 0, v[140:141]
	global_store_dwordx2 v[64:65], v[56:57], off
	v_exp_f32_e64 v50, -v44
	v_exp_f32_e64 v51, -v45
	v_exp_f32_e64 v52, -v46
	v_exp_f32_e64 v53, -v47
	v_add_f32_e32 v50, 1.0, v50
	v_add_f32_e32 v51, 1.0, v51
	v_add_f32_e32 v52, 1.0, v52
	v_add_f32_e32 v53, 1.0, v53
	v_rcp_f32_e32 v50, v50
	v_rcp_f32_e32 v51, v51
	v_rcp_f32_e32 v52, v52
	v_rcp_f32_e32 v53, v53
	v_pk_mul_f32 v[42:43], v[46:47], v[42:43]
	v_pk_mul_f32 v[40:41], v[44:45], v[40:41]
	v_pk_mul_f32 v[40:41], v[40:41], v[50:51]
	v_pk_mul_f32 v[42:43], v[42:43], v[52:53]
	v_cvt_pk_bf16_f32 v40, v40, v41
	v_cvt_pk_bf16_f32 v41, v42, v43
	v_add_u32_e32 v48, 0x90, v165
	v_mad_i64_i32 v[48:49], s[14:15], v48, s70, v[142:143]
	v_lshl_add_u64 v[48:49], v[48:49], 0, v[140:141]
	global_store_dwordx2 v[48:49], v[40:41], off
	v_exp_f32_e64 v34, -v28
	v_exp_f32_e64 v35, -v29
	v_exp_f32_e64 v36, -v30
	v_exp_f32_e64 v37, -v31
	v_add_f32_e32 v34, 1.0, v34
	v_add_f32_e32 v35, 1.0, v35
	v_add_f32_e32 v36, 1.0, v36
	v_add_f32_e32 v37, 1.0, v37
	v_rcp_f32_e32 v34, v34
	v_rcp_f32_e32 v35, v35
	v_rcp_f32_e32 v36, v36
	v_rcp_f32_e32 v37, v37
	v_pk_mul_f32 v[26:27], v[30:31], v[26:27]
	v_pk_mul_f32 v[24:25], v[28:29], v[24:25]
	v_pk_mul_f32 v[24:25], v[24:25], v[34:35]
	v_pk_mul_f32 v[26:27], v[26:27], v[36:37]
	v_cvt_pk_bf16_f32 v24, v24, v25
	v_cvt_pk_bf16_f32 v25, v26, v27
	v_add_u32_e32 v32, 0xa0, v165
	v_mad_i64_i32 v[32:33], s[14:15], v32, s70, v[142:143]
	v_lshl_add_u64 v[32:33], v[32:33], 0, v[140:141]
	global_store_dwordx2 v[32:33], v[24:25], off
	v_exp_f32_e64 v18, -v12
	v_exp_f32_e64 v19, -v13
	v_exp_f32_e64 v20, -v14
	v_exp_f32_e64 v21, -v15
	v_add_f32_e32 v18, 1.0, v18
	v_add_f32_e32 v19, 1.0, v19
	v_add_f32_e32 v20, 1.0, v20
	v_add_f32_e32 v21, 1.0, v21
	v_rcp_f32_e32 v18, v18
	v_rcp_f32_e32 v19, v19
	v_rcp_f32_e32 v20, v20
	v_rcp_f32_e32 v21, v21
	v_pk_mul_f32 v[10:11], v[14:15], v[10:11]
	v_pk_mul_f32 v[8:9], v[12:13], v[8:9]
	v_pk_mul_f32 v[8:9], v[8:9], v[18:19]
	v_pk_mul_f32 v[10:11], v[10:11], v[20:21]
	v_cvt_pk_bf16_f32 v8, v8, v9
	v_cvt_pk_bf16_f32 v9, v10, v11
	v_add_u32_e32 v16, 0xb0, v165
	v_mad_i64_i32 v[16:17], s[14:15], v16, s70, v[142:143]
	v_lshl_add_u64 v[16:17], v[16:17], 0, v[140:141]
	global_store_dwordx2 v[16:17], v[8:9], off
	s_and_b64 vcc, exec, s[2:3]
	s_mov_b32 s74, s71
	s_mov_b32 s73, s72
	s_mov_b64 s[16:17], s[0:1]
	s_mov_b64 s[14:15], s[4:5]

; DI unsigned bar_add(unsigned* p, unsigned v) { return __hip_atomic_fetch_add(p, v, __ATOMIC_RELAXED, __HIP_MEMORY_SCOPE_AGENT); }
; DI void grid_barrier(unsigned* bar, unsigned k, volatile unsigned* meta) {
;     ...
;   if (threadIdx.x == 0) {
;     const unsigned nloc = meta[0], nx = meta[1], x = meta[2];
;     const unsigned old = bar_add(bar + 1024 + 64 * x, 1u);
;     if (old + 1u == k * nloc) {
;       __builtin_amdgcn_fence(__ATOMIC_RELEASE, "agent");
;       asm volatile("s_waitcnt vmcnt(0)" ::: "memory");
;       const unsigned old2 = bar_add(bar + 3072, 1u);
.LBB0_68:
	s_waitcnt vmcnt(0)
	s_waitcnt vmcnt(0) lgkmcnt(0)
	s_barrier
	s_and_saveexec_b64 s[0:1], s[8:9]
	s_cbranch_execz .LBB0_78
	s_mov_b64 s[2:3], src_shared_base
	v_mov_b32_e32 v0, 0x24040
	ds_read_b32 v3, v0
	ds_read_b32 v2, v0 offset:4
	ds_read_b32 v0, v0 offset:8
	v_mov_b32_e32 v1, 0
	v_mov_b32_e32 v6, 1
	s_waitcnt lgkmcnt(0)
	v_lshlrev_b32_e32 v3, 1, v3
	v_lshlrev_b32_e32 v0, 6, v0
	v_lshl_add_u64 v[0:1], v[0:1], 2, s[24:25]
	v_add_co_u32_e32 v4, vcc, 0xef01000, v0
	s_nop 1
	v_addc_co_u32_e32 v5, vcc, 0, v1, vcc
	global_atomic_add v4, v[4:5], v6, off offset:1024 sc0
	s_waitcnt vmcnt(0)
	v_add_u32_e32 v4, 1, v4
	v_cmp_eq_u32_e32 vcc, v4, v3
	s_and_saveexec_b64 s[2:3], vcc
	s_cbranch_execz .LBB0_74
	s_mov_b64 s[4:5], exec
	buffer_wbl2 sc1
	s_waitcnt vmcnt(0)
	v_mbcnt_lo_u32_b32 v3, s4, 0
	v_mbcnt_hi_u32_b32 v3, s5, v3
	v_cmp_eq_u32_e32 vcc, 0, v3
	s_and_saveexec_b64 s[6:7], vcc
	s_cbranch_execz .LBB0_72
	s_bcnt1_i32_b64 s4, s[4:5]
	v_mov_b32_e32 v4, 0xef03000
	v_mov_b32_e32 v5, s4
	global_atomic_add v4, v4, v5, s[24:25] offset:1024 sc0

; DI unsigned bar_add(unsigned* p, unsigned v) { return __hip_atomic_fetch_add(p, v, __ATOMIC_RELAXED, __HIP_MEMORY_SCOPE_AGENT); }
; DI void grid_barrier(unsigned* bar, unsigned k, volatile unsigned* meta) {
;     ...
;   if (threadIdx.x == 0) {
;     const unsigned nloc = meta[0], nx = meta[1], x = meta[2];
;     const unsigned old = bar_add(bar + 1024 + 64 * x, 1u);
;     if (old + 1u == k * nloc) {
;       __builtin_amdgcn_fence(__ATOMIC_RELEASE, "agent");
;       asm volatile("s_waitcnt vmcnt(0)" ::: "memory");
;       const unsigned old2 = bar_add(bar + 3072, 1u);
.LBB0_102:
	s_waitcnt vmcnt(0)
	s_waitcnt vmcnt(0) lgkmcnt(0)
	s_barrier
	s_and_saveexec_b64 s[0:1], s[8:9]
	s_cbranch_execz .LBB0_112
	s_mov_b64 s[2:3], src_shared_base
	v_mov_b32_e32 v0, 0x24040
	ds_read_b32 v3, v0
	ds_read_b32 v2, v0 offset:4
	ds_read_b32 v0, v0 offset:8
	v_mov_b32_e32 v1, 0
	v_mov_b32_e32 v6, 1
	s_waitcnt lgkmcnt(0)
	v_lshl_add_u32 v3, v3, 1, v3
	v_lshlrev_b32_e32 v0, 6, v0
	v_lshl_add_u64 v[0:1], v[0:1], 2, s[24:25]
	v_add_co_u32_e32 v4, vcc, 0xef01000, v0
	s_nop 1
	v_addc_co_u32_e32 v5, vcc, 0, v1, vcc
	global_atomic_add v4, v[4:5], v6, off offset:1024 sc0
	s_waitcnt vmcnt(0)
	v_add_u32_e32 v4, 1, v4
	v_cmp_eq_u32_e32 vcc, v4, v3
	s_and_saveexec_b64 s[2:3], vcc
	s_cbranch_execz .LBB0_108
	s_mov_b64 s[4:5], exec
	buffer_wbl2 sc1
	s_waitcnt vmcnt(0)
	v_mbcnt_lo_u32_b32 v3, s4, 0
	v_mbcnt_hi_u32_b32 v3, s5, v3
	v_cmp_eq_u32_e32 vcc, 0, v3
	s_and_saveexec_b64 s[6:7], vcc
	s_cbranch_execz .LBB0_106
	s_bcnt1_i32_b64 s4, s[4:5]
	v_mov_b32_e32 v4, 0xef03000
	v_mov_b32_e32 v5, s4
	global_atomic_add v4, v4, v5, s[24:25] offset:1024 sc0

; DI unsigned bar_add(unsigned* p, unsigned v) { return __hip_atomic_fetch_add(p, v, __ATOMIC_RELAXED, __HIP_MEMORY_SCOPE_AGENT); }
; DI void grid_barrier(unsigned* bar, unsigned k, volatile unsigned* meta) {
;     ...
;   if (threadIdx.x == 0) {
;     const unsigned nloc = meta[0], nx = meta[1], x = meta[2];
;     const unsigned old = bar_add(bar + 1024 + 64 * x, 1u);
;     if (old + 1u == k * nloc) {
;       __builtin_amdgcn_fence(__ATOMIC_RELEASE, "agent");
;       asm volatile("s_waitcnt vmcnt(0)" ::: "memory");
;       const unsigned old2 = bar_add(bar + 3072, 1u);
.LBB0_115:
	s_or_b64 exec, exec, s[0:1]
	s_waitcnt vmcnt(0)
	s_barrier
	s_and_saveexec_b64 s[0:1], s[8:9]
	s_cbranch_execz .LBB0_125
	s_mov_b64 s[2:3], src_shared_base
	v_mov_b32_e32 v0, 0x24040
	ds_read_b32 v3, v0
	ds_read_b32 v2, v0 offset:4
	ds_read_b32 v0, v0 offset:8
	v_mov_b32_e32 v1, 0
	v_mov_b32_e32 v6, 1
	s_waitcnt lgkmcnt(0)
	v_lshlrev_b32_e32 v3, 2, v3
	v_lshlrev_b32_e32 v0, 6, v0
	v_lshl_add_u64 v[0:1], v[0:1], 2, s[24:25]
	v_add_co_u32_e32 v4, vcc, 0xef01000, v0
	s_nop 1
	v_addc_co_u32_e32 v5, vcc, 0, v1, vcc
	global_atomic_add v4, v[4:5], v6, off offset:1024 sc0
	s_waitcnt vmcnt(0)
	v_add_u32_e32 v4, 1, v4
	v_cmp_eq_u32_e32 vcc, v4, v3
	s_and_saveexec_b64 s[2:3], vcc
	s_cbranch_execz .LBB0_121
	s_mov_b64 s[4:5], exec
	buffer_wbl2 sc1
	s_waitcnt vmcnt(0)
	v_mbcnt_lo_u32_b32 v3, s4, 0
	v_mbcnt_hi_u32_b32 v3, s5, v3
	v_cmp_eq_u32_e32 vcc, 0, v3
	s_and_saveexec_b64 s[6:7], vcc
	s_cbranch_execz .LBB0_119
	s_bcnt1_i32_b64 s4, s[4:5]
	v_mov_b32_e32 v4, 0xef03000
	v_mov_b32_e32 v5, s4
	global_atomic_add v4, v4, v5, s[24:25] offset:1024 sc0

; DI unsigned bar_add(unsigned* p, unsigned v) { return __hip_atomic_fetch_add(p, v, __ATOMIC_RELAXED, __HIP_MEMORY_SCOPE_AGENT); }
; DI void grid_barrier(unsigned* bar, unsigned k, volatile unsigned* meta) {
;     ...
;   if (threadIdx.x == 0) {
;     const unsigned nloc = meta[0], nx = meta[1], x = meta[2];
;     const unsigned old = bar_add(bar + 1024 + 64 * x, 1u);
;     if (old + 1u == k * nloc) {
;       __builtin_amdgcn_fence(__ATOMIC_RELEASE, "agent");
;       asm volatile("s_waitcnt vmcnt(0)" ::: "memory");
;       const unsigned old2 = bar_add(bar + 3072, 1u);
.LBB0_163:
	s_waitcnt vmcnt(0)
	s_waitcnt vmcnt(0) lgkmcnt(0)
	s_barrier
	s_and_saveexec_b64 s[0:1], s[8:9]
	s_cbranch_execz .LBB0_173
	s_mov_b64 s[2:3], src_shared_base
	v_mov_b32_e32 v0, 0x24040
	ds_read_b32 v3, v0
	ds_read_b32 v2, v0 offset:4
	ds_read_b32 v0, v0 offset:8
	v_mov_b32_e32 v1, 0
	v_mov_b32_e32 v6, 1
	s_waitcnt lgkmcnt(0)
	v_lshl_add_u32 v3, v3, 2, v3
	v_lshlrev_b32_e32 v0, 6, v0
	v_lshl_add_u64 v[0:1], v[0:1], 2, s[24:25]
	v_add_co_u32_e32 v4, vcc, 0xef01000, v0
	s_nop 1
	v_addc_co_u32_e32 v5, vcc, 0, v1, vcc
	global_atomic_add v4, v[4:5], v6, off offset:1024 sc0
	s_waitcnt vmcnt(0)
	v_add_u32_e32 v4, 1, v4
	v_cmp_eq_u32_e32 vcc, v4, v3
	s_and_saveexec_b64 s[2:3], vcc
	s_cbranch_execz .LBB0_169
	s_mov_b64 s[4:5], exec
	buffer_wbl2 sc1
	s_waitcnt vmcnt(0)
	v_mbcnt_lo_u32_b32 v3, s4, 0
	v_mbcnt_hi_u32_b32 v3, s5, v3
	v_cmp_eq_u32_e32 vcc, 0, v3
	s_and_saveexec_b64 s[6:7], vcc
	s_cbranch_execz .LBB0_167
	s_bcnt1_i32_b64 s4, s[4:5]
	v_mov_b32_e32 v4, 0xef03000
	v_mov_b32_e32 v5, s4
	global_atomic_add v4, v4, v5, s[24:25] offset:1024 sc0

; DI unsigned bar_add(unsigned* p, unsigned v) { return __hip_atomic_fetch_add(p, v, __ATOMIC_RELAXED, __HIP_MEMORY_SCOPE_AGENT); }
; DI void grid_barrier(unsigned* bar, unsigned k, volatile unsigned* meta) {
;     ...
;   if (threadIdx.x == 0) {
;     const unsigned nloc = meta[0], nx = meta[1], x = meta[2];
;     const unsigned old = bar_add(bar + 1024 + 64 * x, 1u);
;     if (old + 1u == k * nloc) {
;       __builtin_amdgcn_fence(__ATOMIC_RELEASE, "agent");
;       asm volatile("s_waitcnt vmcnt(0)" ::: "memory");
;       const unsigned old2 = bar_add(bar + 3072, 1u);
.LBB0_265:
	s_or_b64 exec, exec, s[6:7]
	s_waitcnt vmcnt(0)
	s_waitcnt lgkmcnt(0)
	s_barrier
	s_and_saveexec_b64 s[0:1], s[8:9]
	s_cbranch_execz .LBB0_275
	s_mov_b64 s[2:3], src_shared_base
	v_mov_b32_e32 v0, 0x24040
	ds_read_b32 v3, v0
	ds_read_b32 v2, v0 offset:4
	ds_read_b32 v0, v0 offset:8
	v_mov_b32_e32 v1, 0
	v_mov_b32_e32 v6, 1
	s_waitcnt lgkmcnt(0)
	v_mul_lo_u32 v3, v3, 6
	v_lshlrev_b32_e32 v0, 6, v0
	v_lshl_add_u64 v[0:1], v[0:1], 2, s[24:25]
	v_add_co_u32_e32 v4, vcc, 0xef01000, v0
	s_nop 1
	v_addc_co_u32_e32 v5, vcc, 0, v1, vcc
	global_atomic_add v4, v[4:5], v6, off offset:1024 sc0
	s_waitcnt vmcnt(0)
	v_add_u32_e32 v4, 1, v4
	v_cmp_eq_u32_e32 vcc, v4, v3
	s_and_saveexec_b64 s[2:3], vcc
	s_cbranch_execz .LBB0_271
	s_mov_b64 s[4:5], exec
	buffer_wbl2 sc1
	s_waitcnt vmcnt(0)
	v_mbcnt_lo_u32_b32 v3, s4, 0
	v_mbcnt_hi_u32_b32 v3, s5, v3
	v_cmp_eq_u32_e32 vcc, 0, v3
	s_and_saveexec_b64 s[6:7], vcc
	s_cbranch_execz .LBB0_269
	s_bcnt1_i32_b64 s4, s[4:5]
	v_mov_b32_e32 v4, 0xef03000
	v_mov_b32_e32 v5, s4
	global_atomic_add v4, v4, v5, s[24:25] offset:1024 sc0

; DI unsigned bar_add(unsigned* p, unsigned v) { return __hip_atomic_fetch_add(p, v, __ATOMIC_RELAXED, __HIP_MEMORY_SCOPE_AGENT); }
; DI void grid_barrier(unsigned* bar, unsigned k, volatile unsigned* meta) {
;     ...
;   if (threadIdx.x == 0) {
;     const unsigned nloc = meta[0], nx = meta[1], x = meta[2];
;     const unsigned old = bar_add(bar + 1024 + 64 * x, 1u);
;     if (old + 1u == k * nloc) {
;       __builtin_amdgcn_fence(__ATOMIC_RELEASE, "agent");
;       asm volatile("s_waitcnt vmcnt(0)" ::: "memory");
;       const unsigned old2 = bar_add(bar + 3072, 1u);
.LBB0_283:
	s_or_b64 exec, exec, s[4:5]
	s_waitcnt vmcnt(0)
	s_waitcnt lgkmcnt(0)
	s_barrier
	s_and_saveexec_b64 s[0:1], s[8:9]
	s_cbranch_execz .LBB0_293
	s_mov_b64 s[2:3], src_shared_base
	s_waitcnt vmcnt(0)
	v_mov_b32_e32 v0, 0x24040
	ds_read_b32 v3, v0
	ds_read_b32 v2, v0 offset:4
	ds_read_b32 v0, v0 offset:8
	v_mov_b32_e32 v1, 0
	v_mov_b32_e32 v6, 1
	s_waitcnt lgkmcnt(0)
	v_mul_lo_u32 v3, v3, 7
	v_lshlrev_b32_e32 v0, 6, v0
	v_lshl_add_u64 v[0:1], v[0:1], 2, s[24:25]
	v_add_co_u32_e32 v4, vcc, 0xef01000, v0
	s_nop 1
	v_addc_co_u32_e32 v5, vcc, 0, v1, vcc
	global_atomic_add v4, v[4:5], v6, off offset:1024 sc0
	s_waitcnt vmcnt(0)
	v_add_u32_e32 v4, 1, v4
	v_cmp_eq_u32_e32 vcc, v4, v3
	s_and_saveexec_b64 s[2:3], vcc
	s_cbranch_execz .LBB0_289
	s_mov_b64 s[4:5], exec
	buffer_wbl2 sc1
	s_waitcnt vmcnt(0)
	v_mbcnt_lo_u32_b32 v3, s4, 0
	v_mbcnt_hi_u32_b32 v3, s5, v3
	v_cmp_eq_u32_e32 vcc, 0, v3
	s_and_saveexec_b64 s[6:7], vcc
	s_cbranch_execz .LBB0_287
	s_bcnt1_i32_b64 s4, s[4:5]
	v_mov_b32_e32 v4, 0xef03000
	v_mov_b32_e32 v5, s4
	global_atomic_add v4, v4, v5, s[24:25] offset:1024 sc0

; DI unsigned bar_add(unsigned* p, unsigned v) { return __hip_atomic_fetch_add(p, v, __ATOMIC_RELAXED, __HIP_MEMORY_SCOPE_AGENT); }
; DI void grid_barrier(unsigned* bar, unsigned k, volatile unsigned* meta) {
;     ...
;   if (threadIdx.x == 0) {
;     const unsigned nloc = meta[0], nx = meta[1], x = meta[2];
;     const unsigned old = bar_add(bar + 1024 + 64 * x, 1u);
;     if (old + 1u == k * nloc) {
;       __builtin_amdgcn_fence(__ATOMIC_RELEASE, "agent");
;       asm volatile("s_waitcnt vmcnt(0)" ::: "memory");
;       const unsigned old2 = bar_add(bar + 3072, 1u);
.LBB0_317:
	s_waitcnt vmcnt(0)
	s_waitcnt vmcnt(0) lgkmcnt(0)
	s_barrier
	s_and_saveexec_b64 s[0:1], s[8:9]
	s_cbranch_execz .LBB0_327
	s_mov_b64 s[2:3], src_shared_base
	v_mov_b32_e32 v0, 0x24040
	ds_read_b32 v3, v0
	ds_read_b32 v2, v0 offset:4
	ds_read_b32 v0, v0 offset:8
	v_mov_b32_e32 v1, 0
	v_mov_b32_e32 v6, 1
	s_waitcnt lgkmcnt(0)
	v_lshlrev_b32_e32 v3, 3, v3
	v_lshlrev_b32_e32 v0, 6, v0
	v_lshl_add_u64 v[0:1], v[0:1], 2, s[24:25]
	v_add_co_u32_e32 v4, vcc, 0xef01000, v0
	s_nop 1
	v_addc_co_u32_e32 v5, vcc, 0, v1, vcc
	global_atomic_add v4, v[4:5], v6, off offset:1024 sc0
	s_waitcnt vmcnt(0)
	v_add_u32_e32 v4, 1, v4
	v_cmp_eq_u32_e32 vcc, v4, v3
	s_and_saveexec_b64 s[2:3], vcc
	s_cbranch_execz .LBB0_323
	s_mov_b64 s[4:5], exec
	buffer_wbl2 sc1
	s_waitcnt vmcnt(0)
	v_mbcnt_lo_u32_b32 v3, s4, 0
	v_mbcnt_hi_u32_b32 v3, s5, v3
	v_cmp_eq_u32_e32 vcc, 0, v3
	s_and_saveexec_b64 s[6:7], vcc
	s_cbranch_execz .LBB0_321
	s_bcnt1_i32_b64 s4, s[4:5]
	v_mov_b32_e32 v4, 0xef03000
	v_mov_b32_e32 v5, s4
	global_atomic_add v4, v4, v5, s[24:25] offset:1024 sc0

; DI unsigned bar_add(unsigned* p, unsigned v) { return __hip_atomic_fetch_add(p, v, __ATOMIC_RELAXED, __HIP_MEMORY_SCOPE_AGENT); }
; DI void grid_barrier(unsigned* bar, unsigned k, volatile unsigned* meta) {
;     ...
;   if (threadIdx.x == 0) {
;     const unsigned nloc = meta[0], nx = meta[1], x = meta[2];
;     const unsigned old = bar_add(bar + 1024 + 64 * x, 1u);
;     if (old + 1u == k * nloc) {
;       __builtin_amdgcn_fence(__ATOMIC_RELEASE, "agent");
;       asm volatile("s_waitcnt vmcnt(0)" ::: "memory");
;       const unsigned old2 = bar_add(bar + 3072, 1u);
.LBB0_330:
	s_or_b64 exec, exec, s[0:1]
	s_waitcnt vmcnt(0)
	s_barrier
	s_and_saveexec_b64 s[0:1], s[8:9]
	s_cbranch_execz .LBB0_340
	s_mov_b64 s[2:3], src_shared_base
	v_mov_b32_e32 v0, 0x24040
	ds_read_b32 v3, v0
	ds_read_b32 v2, v0 offset:4
	ds_read_b32 v0, v0 offset:8
	v_mov_b32_e32 v1, 0
	v_mov_b32_e32 v6, 1
	s_waitcnt lgkmcnt(0)
	v_lshl_add_u32 v3, v3, 3, v3
	v_lshlrev_b32_e32 v0, 6, v0
	v_lshl_add_u64 v[0:1], v[0:1], 2, s[24:25]
	v_add_co_u32_e32 v4, vcc, 0xef01000, v0
	s_nop 1
	v_addc_co_u32_e32 v5, vcc, 0, v1, vcc
	global_atomic_add v4, v[4:5], v6, off offset:1024 sc0
	s_waitcnt vmcnt(0)
	v_add_u32_e32 v4, 1, v4
	v_cmp_eq_u32_e32 vcc, v4, v3
	s_and_saveexec_b64 s[2:3], vcc
	s_cbranch_execz .LBB0_336
	s_mov_b64 s[4:5], exec
	buffer_wbl2 sc1
	s_waitcnt vmcnt(0)
	v_mbcnt_lo_u32_b32 v3, s4, 0
	v_mbcnt_hi_u32_b32 v3, s5, v3
	v_cmp_eq_u32_e32 vcc, 0, v3
	s_and_saveexec_b64 s[6:7], vcc
	s_cbranch_execz .LBB0_334
	s_bcnt1_i32_b64 s4, s[4:5]
	v_mov_b32_e32 v4, 0xef03000
	v_mov_b32_e32 v5, s4
	global_atomic_add v4, v4, v5, s[24:25] offset:1024 sc0

; #define PG8_STAGE(bufoff, gbase, voff) do { _Pragma("unroll") for (int _i = 0; _i < 2; ++_i) \
;         __builtin_amdgcn_global_load_lds((const unsigned*)((const char*)(gbase) + (voff)[_i]), (PG8_LAS unsigned*)(lds + (bufoff) + ldsw + _i * 8192), 16, 0, 0); } while (0)
; #define PG8_LDA(dst, b, h) do { _Pragma("unroll") for (int m = 0; m < 4; ++m) _Pragma("unroll") for (int k = 0; k < 2; ++k) dst[m][k] = *(const PG8_LAS bf16x8*)(lds + PG8_SA(b, h) + aoff + m * 2048 + k * 1024); } while (0)
; #define PG8_LDB(dst, b, h) do { _Pragma("unroll") for (int n = 0; n < 2; ++n) _Pragma("unroll") for (int k = 0; k < 2; ++k) dst[n][k] = *(const PG8_LAS bf16x8*)(lds + PG8_SB(b, h) + boff + n * 2048 + k * 1024); } while (0)
; #define PG8_MMA(ai, bj, At, Bt) do { __builtin_amdgcn_s_setprio(1); _Pragma("unroll") for (int m = 0; m < 4; ++m) _Pragma("unroll") for (int n = 0; n < 2; ++n) _Pragma("unroll") for (int k = 0; k < 2; ++k) \
;         acc[ai][bj][m][n] = __builtin_amdgcn_mfma_f32_16x16x32_bf16(Bt[n][k], At[m][k], acc[ai][bj][m][n], 0, 0, 0); __builtin_amdgcn_s_setprio(0); } while (0)
; #define PG8_WAIT_V(n) asm volatile("s_waitcnt vmcnt(" #n ")" ::: "memory")
; #define PG8_WAIT_L(n) asm volatile("s_waitcnt lgkmcnt(" #n ")" ::: "memory")
; #define PG8_BAR __builtin_amdgcn_s_barrier()
; #define PG8_SCHED __builtin_amdgcn_sched_barrier(0)
; template <class Epi, class Sched, bool STAMP = false>
; __device__ __forceinline__ void gemm_phase(PG8_LAS unsigned char* lds, const Gemm g, const Sched& S, const Epi& E, unsigned long long* stamps) {
;     ...
;             PG8_LDB(B0, 1, 0); PG8_SCHED; PG8_LDA(At, 1, 0); PG8_STAGE(PG8_SA(0, 1), a2 + hstep, voffA);
;             PG8_WAIT_L(8); PG8_BAR; PG8_WAIT_L(0); PG8_MMA(0, 0, At, B0); PG8_BAR; PG8_SCHED;
;             PG8_LDB(B1, 1, 1); PG8_STAGE(PG8_SB(1, 0), b3, voffB);
;             PG8_BAR; PG8_WAIT_L(0); PG8_MMA(0, 1, At, B1); PG8_BAR;
;             PG8_LDA(At, 1, 1); PG8_STAGE(PG8_SA(1, 0), a3, voffA);
;             PG8_BAR; PG8_WAIT_L(0); PG8_MMA(1, 0, At, B0); PG8_BAR; PG8_SCHED;
;             PG8_STAGE(PG8_SB(1, 1), b3 + hstep, voffB);
;             PG8_WAIT_V(6); PG8_BAR; PG8_MMA(1, 1, At, B1); PG8_BAR;
.Lzp5_mid:
	ds_read_b128 v[140:143], v155
	ds_read_b128 v[170:173], v156
	ds_read_b128 v[174:177], v157
	ds_read_b128 v[178:181], v165
	s_add_u32 s34, s54, 0x44000
	s_addc_u32 s35, s55, 0
	s_mov_b32 m0, s66
	ds_read_b128 v[182:185], v145 offset:32768
	ds_read_b128 v[186:189], v145 offset:33792
	ds_read_b128 v[190:193], v145 offset:34816
	ds_read_b128 v[194:197], v145 offset:35840
	ds_read_b128 v[198:201], v145 offset:36864
	ds_read_b128 v[202:205], v145 offset:37888
	ds_read_b128 v[206:209], v145 offset:38912
	ds_read_b128 v[210:213], v145 offset:39936
	global_load_lds_dwordx4 v130, s[34:35]
	s_mov_b32 m0, s67
	s_nop 0
	global_load_lds_dwordx4 v128, s[34:35]
	s_waitcnt lgkmcnt(8)
	s_barrier
	s_waitcnt lgkmcnt(0)
	s_setprio 1
	s_waitcnt lgkmcnt(0)
	v_mfma_f32_16x16x32_bf16 v[124:127], v[140:143], v[182:185], v[124:127]
	v_mfma_f32_16x16x32_bf16 v[120:123], v[174:177], v[182:185], v[120:123]
	v_mfma_f32_16x16x32_bf16 v[108:111], v[140:143], v[190:193], v[108:111]
	v_mfma_f32_16x16x32_bf16 v[104:107], v[174:177], v[190:193], v[104:107]
	v_mfma_f32_16x16x32_bf16 v[92:95], v[140:143], v[198:201], v[92:95]
	v_mfma_f32_16x16x32_bf16 v[88:91], v[174:177], v[198:201], v[88:91]
	v_mfma_f32_16x16x32_bf16 v[76:79], v[140:143], v[206:209], v[76:79]
	v_mfma_f32_16x16x32_bf16 v[72:75], v[174:177], v[206:209], v[72:75]
	v_mfma_f32_16x16x32_bf16 v[124:127], v[170:173], v[186:189], v[124:127]
	v_mfma_f32_16x16x32_bf16 v[120:123], v[178:181], v[186:189], v[120:123]
	v_mfma_f32_16x16x32_bf16 v[108:111], v[170:173], v[194:197], v[108:111]
	v_mfma_f32_16x16x32_bf16 v[104:107], v[178:181], v[194:197], v[104:107]
	v_mfma_f32_16x16x32_bf16 v[92:95], v[170:173], v[202:205], v[92:95]
	v_mfma_f32_16x16x32_bf16 v[88:91], v[178:181], v[202:205], v[88:91]
	v_mfma_f32_16x16x32_bf16 v[76:79], v[170:173], v[210:213], v[76:79]
	v_mfma_f32_16x16x32_bf16 v[72:75], v[178:181], v[210:213], v[72:75]
	s_setprio 0
	s_barrier
	s_mov_b32 m0, s70
	ds_read_b128 v[214:217], v166
	ds_read_b128 v[218:221], v167
	ds_read_b128 v[222:225], v168
	ds_read_b128 v[226:229], v169
	s_add_u32 s100, s52, 0x80
	s_addc_u32 s101, s53, 0
	global_load_lds_dwordx4 v130, s[100:101]
	s_mov_b32 m0, s71
	s_nop 0
	global_load_lds_dwordx4 v128, s[100:101]
	s_barrier
	s_waitcnt lgkmcnt(0)
	s_setprio 1
	s_waitcnt lgkmcnt(0)
	v_mfma_f32_16x16x32_bf16 v[116:119], v[214:217], v[182:185], v[116:119]
	v_mfma_f32_16x16x32_bf16 v[112:115], v[222:225], v[182:185], v[112:115]
	v_mfma_f32_16x16x32_bf16 v[100:103], v[214:217], v[190:193], v[100:103]
	v_mfma_f32_16x16x32_bf16 v[96:99], v[222:225], v[190:193], v[96:99]
	v_mfma_f32_16x16x32_bf16 v[84:87], v[214:217], v[198:201], v[84:87]
	v_mfma_f32_16x16x32_bf16 v[80:83], v[222:225], v[198:201], v[80:83]
	v_mfma_f32_16x16x32_bf16 v[68:71], v[214:217], v[206:209], v[68:71]
	v_mfma_f32_16x16x32_bf16 v[64:67], v[222:225], v[206:209], v[64:67]
	v_mfma_f32_16x16x32_bf16 v[116:119], v[218:221], v[186:189], v[116:119]
	v_mfma_f32_16x16x32_bf16 v[112:115], v[226:229], v[186:189], v[112:115]
	v_mfma_f32_16x16x32_bf16 v[100:103], v[218:221], v[194:197], v[100:103]
	v_mfma_f32_16x16x32_bf16 v[96:99], v[226:229], v[194:197], v[96:99]
	v_mfma_f32_16x16x32_bf16 v[84:87], v[218:221], v[202:205], v[84:87]
	v_mfma_f32_16x16x32_bf16 v[80:83], v[226:229], v[202:205], v[80:83]
	v_mfma_f32_16x16x32_bf16 v[68:71], v[218:221], v[210:213], v[68:71]
	v_mfma_f32_16x16x32_bf16 v[64:67], v[226:229], v[210:213], v[64:67]
	s_setprio 0
	s_mov_b32 m0, s73
	s_barrier
	ds_read_b128 v[182:185], v145 offset:49152
	ds_read_b128 v[186:189], v145 offset:50176
	ds_read_b128 v[190:193], v145 offset:51200
	ds_read_b128 v[194:197], v145 offset:52224
	ds_read_b128 v[198:201], v145 offset:53248
	ds_read_b128 v[202:205], v145 offset:54272
	ds_read_b128 v[206:209], v145 offset:55296
	ds_read_b128 v[210:213], v145 offset:56320
	s_add_u32 s100, s54, 0x80
	s_addc_u32 s101, s55, 0
	global_load_lds_dwordx4 v130, s[100:101]
	s_mov_b32 m0, s74
	s_nop 0
	global_load_lds_dwordx4 v128, s[100:101]
	s_barrier
	s_waitcnt lgkmcnt(0)
	s_setprio 1
	s_waitcnt lgkmcnt(0)
	v_mfma_f32_16x16x32_bf16 v[60:63], v[140:143], v[182:185], v[60:63]
	v_mfma_f32_16x16x32_bf16 v[56:59], v[174:177], v[182:185], v[56:59]
	v_mfma_f32_16x16x32_bf16 v[44:47], v[140:143], v[190:193], v[44:47]
	v_mfma_f32_16x16x32_bf16 v[40:43], v[174:177], v[190:193], v[40:43]
	v_mfma_f32_16x16x32_bf16 v[28:31], v[140:143], v[198:201], v[28:31]
	v_mfma_f32_16x16x32_bf16 v[24:27], v[174:177], v[198:201], v[24:27]
	v_mfma_f32_16x16x32_bf16 v[12:15], v[140:143], v[206:209], v[12:15]
	v_mfma_f32_16x16x32_bf16 v[8:11], v[174:177], v[206:209], v[8:11]
	v_mfma_f32_16x16x32_bf16 v[60:63], v[170:173], v[186:189], v[60:63]
	v_mfma_f32_16x16x32_bf16 v[56:59], v[178:181], v[186:189], v[56:59]
	v_mfma_f32_16x16x32_bf16 v[44:47], v[170:173], v[194:197], v[44:47]
	v_mfma_f32_16x16x32_bf16 v[40:43], v[178:181], v[194:197], v[40:43]
	v_mfma_f32_16x16x32_bf16 v[28:31], v[170:173], v[202:205], v[28:31]
	v_mfma_f32_16x16x32_bf16 v[24:27], v[178:181], v[202:205], v[24:27]
	v_mfma_f32_16x16x32_bf16 v[12:15], v[170:173], v[210:213], v[12:15]
	v_mfma_f32_16x16x32_bf16 v[8:11], v[178:181], v[210:213], v[8:11]
	s_setprio 0
	s_barrier
	s_add_u32 s34, s52, 0x44080
	s_addc_u32 s35, s53, 0
	s_mov_b32 m0, s75
	s_nop 0
	global_load_lds_dwordx4 v130, s[34:35]
	s_mov_b32 m0, s76
	s_nop 0
	global_load_lds_dwordx4 v128, s[34:35]
	s_waitcnt vmcnt(6)
	s_barrier
; DI float ex2(float x) { return __builtin_amdgcn_exp2f(x); }
; #define PG8_STAMP() do { if (STAMP && wid == 0 && nts < 64) { const unsigned long long _c = 0ull; \
;         ts_lo = (lane == nts) ? (int)(unsigned)_c : ts_lo; ts_hi = (lane == nts) ? (int)(unsigned)(_c >> 32) : ts_hi; ++nts; } } while (0)
; #define PG8_MMA(ai, bj, At, Bt) do { __builtin_amdgcn_s_setprio(1); _Pragma("unroll") for (int m = 0; m < 4; ++m) _Pragma("unroll") for (int n = 0; n < 2; ++n) _Pragma("unroll") for (int k = 0; k < 2; ++k) \
;         acc[ai][bj][m][n] = __builtin_amdgcn_mfma_f32_16x16x32_bf16(Bt[n][k], At[m][k], acc[ai][bj][m][n], 0, 0, 0); __builtin_amdgcn_s_setprio(0); } while (0)
; #define PG8_WAIT_V(n) asm volatile("s_waitcnt vmcnt(" #n ")" ::: "memory")
; #define PG8_BAR __builtin_amdgcn_s_barrier()
;     DI void operator()(const f32x4 (&acc)[2][2][4][2], const Unit& u, int wr, int wc, int fr, int fq) const {
;     ...
;             for (int m = 0; m < 4; ++m) { u16* rowp = O + (size_t)(row0 + ai * HALF + m * 16) * ldc + hcol0;
; #pragma unroll
;                 for (int bj = 0; bj < 2; ++bj) { const f32x4 g = acc[ai][bj][m][0], up = acc[ai][bj][m][1]; float r[4];
; #pragma unroll
;                     for (int j = 0; j < 4; ++j) r[j] = g[j] * up[j] * __builtin_amdgcn_rcpf(1.f + ex2(-LOG2E * g[j]));
;                     uint2 w = {pack2(r[0], r[1]), pack2(r[2], r[3])}; *(uint2*)(rowp + bj * (HALF / 2)) = w; } }
; template <class Epi, class Sched, bool STAMP = false>
; __device__ __forceinline__ void gemm_phase(PG8_LAS unsigned char* lds, const Gemm g, const Sched& S, const Epi& E, unsigned long long* stamps) {
;     ...
;             PG8_WAIT_V(6); PG8_BAR; PG8_MMA(1, 1, At, B1); PG8_BAR;
;         }
;         PG8_STAMP();
;         if constexpr (!Epi::AFTER_DRAIN) { E(acc, cur, wr, wc, fr, fq); S.done(cur); }
	s_setprio 1
	v_mfma_f32_16x16x32_bf16 v[52:55], v[214:217], v[182:185], v[52:55]
	v_mfma_f32_16x16x32_bf16 v[48:51], v[222:225], v[182:185], v[48:51]
	v_mfma_f32_16x16x32_bf16 v[36:39], v[214:217], v[190:193], v[36:39]
	v_mfma_f32_16x16x32_bf16 v[32:35], v[222:225], v[190:193], v[32:35]
	v_mfma_f32_16x16x32_bf16 v[20:23], v[214:217], v[198:201], v[20:23]
	v_mfma_f32_16x16x32_bf16 v[16:19], v[222:225], v[198:201], v[16:19]
	v_mfma_f32_16x16x32_bf16 v[4:7], v[214:217], v[206:209], v[4:7]
	v_mfma_f32_16x16x32_bf16 v[0:3], v[222:225], v[206:209], v[0:3]
	v_mfma_f32_16x16x32_bf16 v[52:55], v[218:221], v[186:189], v[52:55]
	v_mfma_f32_16x16x32_bf16 v[48:51], v[226:229], v[186:189], v[48:51]
	v_mfma_f32_16x16x32_bf16 v[36:39], v[218:221], v[194:197], v[36:39]
	v_mfma_f32_16x16x32_bf16 v[32:35], v[226:229], v[194:197], v[32:35]
	v_mfma_f32_16x16x32_bf16 v[20:23], v[218:221], v[202:205], v[20:23]
	v_mfma_f32_16x16x32_bf16 v[16:19], v[226:229], v[202:205], v[16:19]
	v_mfma_f32_16x16x32_bf16 v[4:7], v[218:221], v[210:213], v[4:7]
	v_mfma_f32_16x16x32_bf16 v[0:3], v[226:229], v[210:213], v[0:3]
	s_setprio 0
	s_add_i32 s89, s89, 2
	s_add_u32 s87, s87, 0x100
	s_addc_u32 s88, s88, 0
	s_cmp_gt_u32 s89, 13
	s_mov_b64 s[34:35], s[36:37]
	s_barrier
	s_cbranch_scc0 .LBB0_351
	v_exp_f32_e64 v171, -v124
	v_exp_f32_e64 v175, -v125
	s_lshl_b32 s10, s86, 8
	v_add_f32_e32 v171, 1.0, v171
	v_rcp_f32_e32 v174, v171
	v_add_f32_e32 v171, 1.0, v175
	v_exp_f32_e64 v176, -v126
	v_exp_f32_e64 v177, -v127
	v_rcp_f32_e32 v175, v171
	v_add_f32_e32 v171, 1.0, v176
	v_rcp_f32_e32 v176, v171
	v_add_f32_e32 v171, 1.0, v177
	v_rcp_f32_e32 v177, v171
	v_pk_mul_f32 v[122:123], v[126:127], v[122:123]
	v_pk_mul_f32 v[120:121], v[124:125], v[120:121]
	s_or_b32 s10, s10, s69
	v_pk_mul_f32 v[120:121], v[120:121], v[174:175]
	v_pk_mul_f32 v[122:123], v[122:123], v[176:177]
	s_ashr_i32 s10, s10, 1
	v_cvt_pk_bf16_f32 v120, v120, v121
	v_cvt_pk_bf16_f32 v121, v122, v123
	v_or_b32_e32 v140, s10, v146
	v_exp_f32_e64 v122, -v116
	v_exp_f32_e64 v123, -v117
	v_lshl_add_u32 v170, s85, 8, v144
	v_ashrrev_i32_e32 v141, 31, v140
	v_mov_b64_e32 v[142:143], s[12:13]
	v_mad_i64_i32 v[172:173], s[34:35], v170, s82, v[142:143]
	v_lshlrev_b64 v[140:141], 1, v[140:141]
	v_lshl_add_u64 v[172:173], v[172:173], 0, v[140:141]
	global_store_dwordx2 v[172:173], v[120:121], off
	v_add_f32_e32 v120, 1.0, v122
	v_add_f32_e32 v121, 1.0, v123
	v_exp_f32_e64 v122, -v118
	v_exp_f32_e64 v123, -v119
	v_rcp_f32_e32 v120, v120
	v_rcp_f32_e32 v121, v121
	v_add_f32_e32 v122, 1.0, v122
	v_add_f32_e32 v123, 1.0, v123
	v_rcp_f32_e32 v122, v122
	v_rcp_f32_e32 v123, v123
	v_pk_mul_f32 v[114:115], v[118:119], v[114:115]
	v_pk_mul_f32 v[112:113], v[116:117], v[112:113]
	v_pk_mul_f32 v[112:113], v[112:113], v[120:121]
	v_pk_mul_f32 v[114:115], v[114:115], v[122:123]
	v_cvt_pk_bf16_f32 v112, v112, v113
	v_cvt_pk_bf16_f32 v113, v114, v115
	v_exp_f32_e64 v114, -v108
	v_exp_f32_e64 v115, -v109
	v_exp_f32_e64 v116, -v110
	v_exp_f32_e64 v117, -v111
	v_add_f32_e32 v114, 1.0, v114
	v_add_f32_e32 v115, 1.0, v115
	v_add_f32_e32 v116, 1.0, v116
	v_add_f32_e32 v117, 1.0, v117
	v_rcp_f32_e32 v114, v114
	v_rcp_f32_e32 v115, v115
	v_rcp_f32_e32 v116, v116
	v_rcp_f32_e32 v117, v117
	v_pk_mul_f32 v[106:107], v[110:111], v[106:107]
	v_pk_mul_f32 v[104:105], v[108:109], v[104:105]
	global_store_dwordx2 v[172:173], v[112:113], off offset:128
	v_pk_mul_f32 v[104:105], v[104:105], v[114:115]
	v_pk_mul_f32 v[106:107], v[106:107], v[116:117]
	v_cvt_pk_bf16_f32 v104, v104, v105
	v_cvt_pk_bf16_f32 v105, v106, v107
	v_exp_f32_e64 v106, -v100
	v_exp_f32_e64 v107, -v101
	v_or_b32_e32 v112, 16, v170
	v_mad_i64_i32 v[112:113], s[34:35], v112, s82, v[142:143]
	v_lshl_add_u64 v[112:113], v[112:113], 0, v[140:141]
	global_store_dwordx2 v[112:113], v[104:105], off
	v_add_f32_e32 v104, 1.0, v106
	v_add_f32_e32 v105, 1.0, v107
	v_exp_f32_e64 v106, -v102
	v_exp_f32_e64 v107, -v103
	v_rcp_f32_e32 v104, v104
	v_rcp_f32_e32 v105, v105
	v_add_f32_e32 v106, 1.0, v106
	v_add_f32_e32 v107, 1.0, v107
	v_rcp_f32_e32 v106, v106
	v_rcp_f32_e32 v107, v107
	v_pk_mul_f32 v[98:99], v[102:103], v[98:99]
	v_pk_mul_f32 v[96:97], v[100:101], v[96:97]
	v_pk_mul_f32 v[96:97], v[96:97], v[104:105]
	v_pk_mul_f32 v[98:99], v[98:99], v[106:107]
	v_cvt_pk_bf16_f32 v96, v96, v97
	v_cvt_pk_bf16_f32 v97, v98, v99
	v_exp_f32_e64 v98, -v92
	v_exp_f32_e64 v99, -v93
	v_exp_f32_e64 v100, -v94
	v_exp_f32_e64 v101, -v95
	v_add_f32_e32 v98, 1.0, v98
	v_add_f32_e32 v99, 1.0, v99
	v_add_f32_e32 v100, 1.0, v100
	v_add_f32_e32 v101, 1.0, v101
	v_rcp_f32_e32 v98, v98
	v_rcp_f32_e32 v99, v99
	v_rcp_f32_e32 v100, v100
	v_rcp_f32_e32 v101, v101
	v_pk_mul_f32 v[90:91], v[94:95], v[90:91]
	v_pk_mul_f32 v[88:89], v[92:93], v[88:89]
	global_store_dwordx2 v[112:113], v[96:97], off offset:128
	v_pk_mul_f32 v[88:89], v[88:89], v[98:99]
	v_pk_mul_f32 v[90:91], v[90:91], v[100:101]
	v_cvt_pk_bf16_f32 v88, v88, v89
	v_cvt_pk_bf16_f32 v89, v90, v91
	v_exp_f32_e64 v90, -v84
	v_exp_f32_e64 v91, -v85
	v_or_b32_e32 v96, 32, v170
	v_mad_i64_i32 v[96:97], s[34:35], v96, s82, v[142:143]
	v_lshl_add_u64 v[96:97], v[96:97], 0, v[140:141]
	global_store_dwordx2 v[96:97], v[88:89], off
	v_add_f32_e32 v88, 1.0, v90
	v_add_f32_e32 v89, 1.0, v91
	v_exp_f32_e64 v90, -v86
	v_exp_f32_e64 v91, -v87
	v_rcp_f32_e32 v88, v88
	v_rcp_f32_e32 v89, v89
	v_add_f32_e32 v90, 1.0, v90
	v_add_f32_e32 v91, 1.0, v91
	v_rcp_f32_e32 v90, v90
	v_rcp_f32_e32 v91, v91
	v_pk_mul_f32 v[82:83], v[86:87], v[82:83]
	v_pk_mul_f32 v[80:81], v[84:85], v[80:81]
	v_pk_mul_f32 v[80:81], v[80:81], v[88:89]
	v_pk_mul_f32 v[82:83], v[82:83], v[90:91]
	v_cvt_pk_bf16_f32 v80, v80, v81
; DI float ex2(float x) { return __builtin_amdgcn_exp2f(x); }
;     DI void operator()(const f32x4 (&acc)[2][2][4][2], const Unit& u, int wr, int wc, int fr, int fq) const {
;     ...
;             for (int m = 0; m < 4; ++m) { u16* rowp = O + (size_t)(row0 + ai * HALF + m * 16) * ldc + hcol0;
; #pragma unroll
;                 for (int bj = 0; bj < 2; ++bj) { const f32x4 g = acc[ai][bj][m][0], up = acc[ai][bj][m][1]; float r[4];
; #pragma unroll
;                     for (int j = 0; j < 4; ++j) r[j] = g[j] * up[j] * __builtin_amdgcn_rcpf(1.f + ex2(-LOG2E * g[j]));
;                     uint2 w = {pack2(r[0], r[1]), pack2(r[2], r[3])}; *(uint2*)(rowp + bj * (HALF / 2)) = w; } }
	v_cvt_pk_bf16_f32 v81, v82, v83
	v_exp_f32_e64 v82, -v76
	v_exp_f32_e64 v83, -v77
	v_exp_f32_e64 v84, -v78
	v_exp_f32_e64 v85, -v79
	v_add_f32_e32 v82, 1.0, v82
	v_add_f32_e32 v83, 1.0, v83
	v_add_f32_e32 v84, 1.0, v84
	v_add_f32_e32 v85, 1.0, v85
	v_rcp_f32_e32 v82, v82
	v_rcp_f32_e32 v83, v83
	v_rcp_f32_e32 v84, v84
	v_rcp_f32_e32 v85, v85
	v_pk_mul_f32 v[74:75], v[78:79], v[74:75]
	v_pk_mul_f32 v[72:73], v[76:77], v[72:73]
	global_store_dwordx2 v[96:97], v[80:81], off offset:128
	v_pk_mul_f32 v[72:73], v[72:73], v[82:83]
	v_pk_mul_f32 v[74:75], v[74:75], v[84:85]
	v_cvt_pk_bf16_f32 v72, v72, v73
	v_cvt_pk_bf16_f32 v73, v74, v75
	v_exp_f32_e64 v74, -v68
	v_exp_f32_e64 v75, -v69
	v_or_b32_e32 v80, 48, v170
	v_mad_i64_i32 v[80:81], s[34:35], v80, s82, v[142:143]
	v_lshl_add_u64 v[80:81], v[80:81], 0, v[140:141]
	global_store_dwordx2 v[80:81], v[72:73], off
	v_add_f32_e32 v72, 1.0, v74
	v_add_f32_e32 v73, 1.0, v75
	v_exp_f32_e64 v74, -v70
	v_exp_f32_e64 v75, -v71
	v_rcp_f32_e32 v72, v72
	v_rcp_f32_e32 v73, v73
	v_add_f32_e32 v74, 1.0, v74
	v_add_f32_e32 v75, 1.0, v75
	v_rcp_f32_e32 v74, v74
	v_rcp_f32_e32 v75, v75
	v_pk_mul_f32 v[66:67], v[70:71], v[66:67]
	v_pk_mul_f32 v[64:65], v[68:69], v[64:65]
	v_pk_mul_f32 v[64:65], v[64:65], v[72:73]
	v_pk_mul_f32 v[66:67], v[66:67], v[74:75]
	v_cvt_pk_bf16_f32 v64, v64, v65
	v_cvt_pk_bf16_f32 v65, v66, v67
	v_exp_f32_e64 v66, -v60
	v_exp_f32_e64 v67, -v61
	v_exp_f32_e64 v68, -v62
	v_exp_f32_e64 v69, -v63
	v_add_f32_e32 v66, 1.0, v66
	v_add_f32_e32 v67, 1.0, v67
	v_add_f32_e32 v68, 1.0, v68
	v_add_f32_e32 v69, 1.0, v69
	v_rcp_f32_e32 v66, v66
	v_rcp_f32_e32 v67, v67
	v_rcp_f32_e32 v68, v68
	v_rcp_f32_e32 v69, v69
	v_pk_mul_f32 v[58:59], v[62:63], v[58:59]
	v_pk_mul_f32 v[56:57], v[60:61], v[56:57]
	global_store_dwordx2 v[80:81], v[64:65], off offset:128
	v_pk_mul_f32 v[56:57], v[56:57], v[66:67]
	v_pk_mul_f32 v[58:59], v[58:59], v[68:69]
	v_cvt_pk_bf16_f32 v56, v56, v57
	v_cvt_pk_bf16_f32 v57, v58, v59
	v_exp_f32_e64 v58, -v52
	v_exp_f32_e64 v59, -v53
	v_add_u32_e32 v64, 0x80, v170
	v_mad_i64_i32 v[64:65], s[34:35], v64, s82, v[142:143]
	v_lshl_add_u64 v[64:65], v[64:65], 0, v[140:141]
	global_store_dwordx2 v[64:65], v[56:57], off
	v_add_f32_e32 v56, 1.0, v58
	v_add_f32_e32 v57, 1.0, v59
	v_exp_f32_e64 v58, -v54
	v_exp_f32_e64 v59, -v55
	v_rcp_f32_e32 v56, v56
	v_rcp_f32_e32 v57, v57
	v_add_f32_e32 v58, 1.0, v58
	v_add_f32_e32 v59, 1.0, v59
	v_rcp_f32_e32 v58, v58
	v_rcp_f32_e32 v59, v59
	v_pk_mul_f32 v[50:51], v[54:55], v[50:51]
	v_pk_mul_f32 v[48:49], v[52:53], v[48:49]
	v_pk_mul_f32 v[48:49], v[48:49], v[56:57]
	v_pk_mul_f32 v[50:51], v[50:51], v[58:59]
	v_cvt_pk_bf16_f32 v48, v48, v49
	v_cvt_pk_bf16_f32 v49, v50, v51
	v_exp_f32_e64 v50, -v44
	v_exp_f32_e64 v51, -v45
	v_exp_f32_e64 v52, -v46
	v_exp_f32_e64 v53, -v47
	v_add_f32_e32 v50, 1.0, v50
	v_add_f32_e32 v51, 1.0, v51
	v_add_f32_e32 v52, 1.0, v52
	v_add_f32_e32 v53, 1.0, v53
	v_rcp_f32_e32 v50, v50
	v_rcp_f32_e32 v51, v51
	v_rcp_f32_e32 v52, v52
	v_rcp_f32_e32 v53, v53
	v_pk_mul_f32 v[42:43], v[46:47], v[42:43]
	v_pk_mul_f32 v[40:41], v[44:45], v[40:41]
	global_store_dwordx2 v[64:65], v[48:49], off offset:128
	v_pk_mul_f32 v[40:41], v[40:41], v[50:51]
	v_pk_mul_f32 v[42:43], v[42:43], v[52:53]
	v_cvt_pk_bf16_f32 v40, v40, v41
	v_cvt_pk_bf16_f32 v41, v42, v43
	v_exp_f32_e64 v42, -v36
	v_exp_f32_e64 v43, -v37
	v_add_u32_e32 v48, 0x90, v170
	v_mad_i64_i32 v[48:49], s[34:35], v48, s82, v[142:143]
	v_lshl_add_u64 v[48:49], v[48:49], 0, v[140:141]
	global_store_dwordx2 v[48:49], v[40:41], off
	v_add_f32_e32 v40, 1.0, v42
	v_add_f32_e32 v41, 1.0, v43
	v_exp_f32_e64 v42, -v38
	v_exp_f32_e64 v43, -v39
	v_rcp_f32_e32 v40, v40
	v_rcp_f32_e32 v41, v41
	v_add_f32_e32 v42, 1.0, v42
	v_add_f32_e32 v43, 1.0, v43
	v_rcp_f32_e32 v42, v42
	v_rcp_f32_e32 v43, v43
	v_pk_mul_f32 v[34:35], v[38:39], v[34:35]
	v_pk_mul_f32 v[32:33], v[36:37], v[32:33]
	v_pk_mul_f32 v[32:33], v[32:33], v[40:41]
	v_pk_mul_f32 v[34:35], v[34:35], v[42:43]
	v_cvt_pk_bf16_f32 v32, v32, v33
	v_cvt_pk_bf16_f32 v33, v34, v35
	v_exp_f32_e64 v34, -v28
	v_exp_f32_e64 v35, -v29
	v_exp_f32_e64 v36, -v30
	v_exp_f32_e64 v37, -v31
	v_add_f32_e32 v34, 1.0, v34
	v_add_f32_e32 v35, 1.0, v35
	v_add_f32_e32 v36, 1.0, v36
	v_add_f32_e32 v37, 1.0, v37
	v_rcp_f32_e32 v34, v34
	v_rcp_f32_e32 v35, v35
	v_rcp_f32_e32 v36, v36
	v_rcp_f32_e32 v37, v37
	v_pk_mul_f32 v[26:27], v[30:31], v[26:27]
	v_pk_mul_f32 v[24:25], v[28:29], v[24:25]
	global_store_dwordx2 v[48:49], v[32:33], off offset:128
	v_pk_mul_f32 v[24:25], v[24:25], v[34:35]
	v_pk_mul_f32 v[26:27], v[26:27], v[36:37]
	v_cvt_pk_bf16_f32 v24, v24, v25
	v_cvt_pk_bf16_f32 v25, v26, v27
	v_exp_f32_e64 v26, -v20
	v_exp_f32_e64 v27, -v21
	v_add_u32_e32 v32, 0xa0, v170
	v_mad_i64_i32 v[32:33], s[34:35], v32, s82, v[142:143]
	v_lshl_add_u64 v[32:33], v[32:33], 0, v[140:141]
	global_store_dwordx2 v[32:33], v[24:25], off
	v_add_f32_e32 v24, 1.0, v26
	v_add_f32_e32 v25, 1.0, v27
	v_exp_f32_e64 v26, -v22
	v_exp_f32_e64 v27, -v23
	v_rcp_f32_e32 v24, v24
	v_rcp_f32_e32 v25, v25
	v_add_f32_e32 v26, 1.0, v26
	v_add_f32_e32 v27, 1.0, v27
	v_rcp_f32_e32 v26, v26
	v_rcp_f32_e32 v27, v27
	v_pk_mul_f32 v[18:19], v[22:23], v[18:19]
	v_pk_mul_f32 v[16:17], v[20:21], v[16:17]
	v_pk_mul_f32 v[16:17], v[16:17], v[24:25]
	v_pk_mul_f32 v[18:19], v[18:19], v[26:27]
	v_cvt_pk_bf16_f32 v16, v16, v17
	v_cvt_pk_bf16_f32 v17, v18, v19
	v_exp_f32_e64 v18, -v12
	v_exp_f32_e64 v19, -v13
	v_exp_f32_e64 v20, -v14
	v_exp_f32_e64 v21, -v15
	v_add_f32_e32 v18, 1.0, v18
	v_add_f32_e32 v19, 1.0, v19
	v_add_f32_e32 v20, 1.0, v20
	v_add_f32_e32 v21, 1.0, v21
	v_rcp_f32_e32 v18, v18
	v_rcp_f32_e32 v19, v19
	v_rcp_f32_e32 v20, v20
	v_rcp_f32_e32 v21, v21
	v_pk_mul_f32 v[10:11], v[14:15], v[10:11]
	v_pk_mul_f32 v[8:9], v[12:13], v[8:9]
	global_store_dwordx2 v[32:33], v[16:17], off offset:128
	v_pk_mul_f32 v[8:9], v[8:9], v[18:19]
	v_pk_mul_f32 v[10:11], v[10:11], v[20:21]
	v_cvt_pk_bf16_f32 v8, v8, v9
	v_cvt_pk_bf16_f32 v9, v10, v11
	v_exp_f32_e64 v10, -v4
	v_exp_f32_e64 v11, -v5
	v_add_u32_e32 v16, 0xb0, v170
	v_mad_i64_i32 v[16:17], s[34:35], v16, s82, v[142:143]
	v_lshl_add_u64 v[16:17], v[16:17], 0, v[140:141]
	global_store_dwordx2 v[16:17], v[8:9], off
	v_add_f32_e32 v8, 1.0, v10
	v_add_f32_e32 v9, 1.0, v11
	v_exp_f32_e64 v10, -v6
	v_exp_f32_e64 v11, -v7
	v_rcp_f32_e32 v8, v8
	v_rcp_f32_e32 v9, v9
	v_add_f32_e32 v10, 1.0, v10
	v_add_f32_e32 v11, 1.0, v11
	v_rcp_f32_e32 v10, v10
	v_rcp_f32_e32 v11, v11
	v_pk_mul_f32 v[2:3], v[6:7], v[2:3]
	v_pk_mul_f32 v[0:1], v[4:5], v[0:1]
	s_and_b64 vcc, exec, s[2:3]
	v_pk_mul_f32 v[0:1], v[0:1], v[8:9]
	v_pk_mul_f32 v[2:3], v[2:3], v[10:11]
	v_cvt_pk_bf16_f32 v0, v0, v1
	v_cvt_pk_bf16_f32 v1, v2, v3
	s_mov_b32 s86, s83
	s_mov_b32 s85, s84
	s_mov_b64 s[36:37], s[0:1]
	s_mov_b64 s[34:35], s[4:5]
	global_store_dwordx2 v[16:17], v[0:1], off offset:128
	s_cbranch_vccz .LBB0_344
	s_branch .Lgu2_done

; #define PG8_STAGE(bufoff, gbase, voff) do { _Pragma("unroll") for (int _i = 0; _i < 2; ++_i) \
;         __builtin_amdgcn_global_load_lds((const unsigned*)((const char*)(gbase) + (voff)[_i]), (PG8_LAS unsigned*)(lds + (bufoff) + ldsw + _i * 8192), 16, 0, 0); } while (0)
; #define PG8_LDA(dst, b, h) do { _Pragma("unroll") for (int m = 0; m < 4; ++m) _Pragma("unroll") for (int k = 0; k < 2; ++k) dst[m][k] = *(const PG8_LAS bf16x8*)(lds + PG8_SA(b, h) + aoff + m * 2048 + k * 1024); } while (0)
; #define PG8_LDB(dst, b, h) do { _Pragma("unroll") for (int n = 0; n < 2; ++n) _Pragma("unroll") for (int k = 0; k < 2; ++k) dst[n][k] = *(const PG8_LAS bf16x8*)(lds + PG8_SB(b, h) + boff + n * 2048 + k * 1024); } while (0)
; #define PG8_WAIT_V(n) asm volatile("s_waitcnt vmcnt(" #n ")" ::: "memory")
; #define PG8_WAIT_L(n) asm volatile("s_waitcnt lgkmcnt(" #n ")" ::: "memory")
; #define PG8_BAR __builtin_amdgcn_s_barrier()
; template <class Epi, class Sched, bool STAMP = false>
; __device__ __forceinline__ void gemm_phase(PG8_LAS unsigned char* lds, const Gemm g, const Sched& S, const Epi& E, unsigned long long* stamps) {
;     ...
;             PG8_LDB(B0, 0, 0); PG8_SCHED; PG8_LDA(At, 0, 0); PG8_STAGE(PG8_SA(1, 1), a1 + hstep, voffA);
;             PG8_WAIT_L(8); PG8_BAR; PG8_WAIT_L(0); PG8_MMA(0, 0, At, B0); PG8_BAR; PG8_SCHED;
;             PG8_LDB(B1, 0, 1); PG8_STAGE(PG8_SB(0, 0), b2, voffB);
;             PG8_BAR; PG8_WAIT_L(0); PG8_MMA(0, 1, At, B1); PG8_BAR;
;             PG8_LDA(At, 0, 1); PG8_STAGE(PG8_SA(0, 0), a2, voffA);
;             PG8_BAR; PG8_WAIT_L(0); PG8_MMA(1, 0, At, B0); PG8_BAR; PG8_SCHED;
;             PG8_STAGE(PG8_SB(0, 1), b2 + hstep, voffB);
;             PG8_WAIT_V(6); PG8_BAR; PG8_MMA(1, 1, At, B1); PG8_BAR;
;             PG8_LDB(B0, 1, 0); PG8_SCHED; PG8_LDA(At, 1, 0); PG8_STAGE(PG8_SA(0, 1), a2 + hstep, voffA);
;             PG8_WAIT_L(8); PG8_BAR; PG8_WAIT_L(0); PG8_MMA(0, 0, At, B0); PG8_BAR; PG8_SCHED;
;             PG8_LDB(B1, 1, 1); PG8_STAGE(PG8_SB(1, 0), b3, voffB);
;             PG8_BAR; PG8_WAIT_L(0); PG8_MMA(0, 1, At, B1); PG8_BAR;
;             PG8_LDA(At, 1, 1); PG8_STAGE(PG8_SA(1, 0), a3, voffA);
;             PG8_BAR; PG8_WAIT_L(0); PG8_MMA(1, 0, At, B0); PG8_BAR; PG8_SCHED;
;             PG8_STAGE(PG8_SB(1, 1), b3 + hstep, voffB);
;             PG8_WAIT_V(6); PG8_BAR; PG8_MMA(1, 1, At, B1); PG8_BAR;
.Lgu2_half_loop:
	ds_read_b128 v[140:143], v147
	ds_read_b128 v[170:173], v148
	ds_read_b128 v[174:177], v149
	ds_read_b128 v[178:181], v150
	s_add_u32 s36, s34, 0x100
	s_addc_u32 s37, s35, 0
	s_cmp_eq_u32 s89, 12
	s_cselect_b32 s55, s5, s37
	s_cselect_b32 s54, s4, s36
	s_cselect_b32 s53, s1, s88
	s_cselect_b32 s52, s0, s87
	s_mov_b32 m0, s78
	ds_read_b128 v[182:185], v145
	ds_read_b128 v[186:189], v145 offset:1024
	ds_read_b128 v[190:193], v145 offset:2048
	ds_read_b128 v[194:197], v145 offset:3072
	ds_read_b128 v[198:201], v145 offset:4096
	ds_read_b128 v[202:205], v145 offset:5120
	ds_read_b128 v[206:209], v145 offset:6144
	ds_read_b128 v[210:213], v145 offset:7168
	global_load_lds_dwordx4 v132, s[34:35]
	s_mov_b32 m0, s79
	s_nop 0
	global_load_lds_dwordx4 v134, s[34:35]
	s_waitcnt lgkmcnt(8)
	s_barrier
	s_waitcnt lgkmcnt(0)
	s_setprio 1
	s_waitcnt lgkmcnt(0)
	v_mfma_f32_16x16x32_bf16 v[124:127], v[140:143], v[182:185], v[124:127]
	v_mfma_f32_16x16x32_bf16 v[120:123], v[174:177], v[182:185], v[120:123]
	v_mfma_f32_16x16x32_bf16 v[108:111], v[140:143], v[190:193], v[108:111]
	v_mfma_f32_16x16x32_bf16 v[104:107], v[174:177], v[190:193], v[104:107]
	v_mfma_f32_16x16x32_bf16 v[92:95], v[140:143], v[198:201], v[92:95]
	v_mfma_f32_16x16x32_bf16 v[88:91], v[174:177], v[198:201], v[88:91]
	v_mfma_f32_16x16x32_bf16 v[76:79], v[140:143], v[206:209], v[76:79]
	v_mfma_f32_16x16x32_bf16 v[72:75], v[174:177], v[206:209], v[72:75]
	v_mfma_f32_16x16x32_bf16 v[124:127], v[170:173], v[186:189], v[124:127]
	v_mfma_f32_16x16x32_bf16 v[120:123], v[178:181], v[186:189], v[120:123]
	v_mfma_f32_16x16x32_bf16 v[108:111], v[170:173], v[194:197], v[108:111]
	v_mfma_f32_16x16x32_bf16 v[104:107], v[178:181], v[194:197], v[104:107]
	v_mfma_f32_16x16x32_bf16 v[92:95], v[170:173], v[202:205], v[92:95]
	v_mfma_f32_16x16x32_bf16 v[88:91], v[178:181], v[202:205], v[88:91]
	v_mfma_f32_16x16x32_bf16 v[76:79], v[170:173], v[210:213], v[76:79]
	v_mfma_f32_16x16x32_bf16 v[72:75], v[178:181], v[210:213], v[72:75]
	s_setprio 0
	s_barrier
	s_mov_b32 m0, s61
	s_nop 0
	global_load_lds_dwordx4 v130, s[52:53]
	s_mov_b32 m0, s62
	s_nop 0
	global_load_lds_dwordx4 v128, s[52:53]
	s_barrier
	s_waitcnt lgkmcnt(0)
	s_setprio 1
	s_waitcnt lgkmcnt(0)
	s_setprio 0
	s_mov_b32 m0, s58
	s_barrier
	ds_read_b128 v[182:185], v145 offset:16384
	ds_read_b128 v[186:189], v145 offset:17408
	ds_read_b128 v[190:193], v145 offset:18432
	ds_read_b128 v[194:197], v145 offset:19456
	ds_read_b128 v[198:201], v145 offset:20480
	ds_read_b128 v[202:205], v145 offset:21504
	ds_read_b128 v[206:209], v145 offset:22528
	ds_read_b128 v[210:213], v145 offset:23552
	global_load_lds_dwordx4 v130, s[54:55]
	s_mov_b32 m0, s63
	s_nop 0
	global_load_lds_dwordx4 v128, s[54:55]
	s_barrier
	s_waitcnt lgkmcnt(0)
	s_setprio 1
	s_waitcnt lgkmcnt(0)
	v_mfma_f32_16x16x32_bf16 v[60:63], v[140:143], v[182:185], v[60:63]
	v_mfma_f32_16x16x32_bf16 v[56:59], v[174:177], v[182:185], v[56:59]
	v_mfma_f32_16x16x32_bf16 v[44:47], v[140:143], v[190:193], v[44:47]
	v_mfma_f32_16x16x32_bf16 v[40:43], v[174:177], v[190:193], v[40:43]
	v_mfma_f32_16x16x32_bf16 v[28:31], v[140:143], v[198:201], v[28:31]
	v_mfma_f32_16x16x32_bf16 v[24:27], v[174:177], v[198:201], v[24:27]
	v_mfma_f32_16x16x32_bf16 v[12:15], v[140:143], v[206:209], v[12:15]
	v_mfma_f32_16x16x32_bf16 v[8:11], v[174:177], v[206:209], v[8:11]
	v_mfma_f32_16x16x32_bf16 v[60:63], v[170:173], v[186:189], v[60:63]
	v_mfma_f32_16x16x32_bf16 v[56:59], v[178:181], v[186:189], v[56:59]
	v_mfma_f32_16x16x32_bf16 v[44:47], v[170:173], v[194:197], v[44:47]
	v_mfma_f32_16x16x32_bf16 v[40:43], v[178:181], v[194:197], v[40:43]
	v_mfma_f32_16x16x32_bf16 v[28:31], v[170:173], v[202:205], v[28:31]
	v_mfma_f32_16x16x32_bf16 v[24:27], v[178:181], v[202:205], v[24:27]
	v_mfma_f32_16x16x32_bf16 v[12:15], v[170:173], v[210:213], v[12:15]
	v_mfma_f32_16x16x32_bf16 v[8:11], v[178:181], v[210:213], v[8:11]
	s_setprio 0
	s_barrier
	s_add_u32 s34, s52, 0x44000
	s_addc_u32 s35, s53, 0
	s_mov_b32 m0, s64
	s_nop 0
	global_load_lds_dwordx4 v130, s[34:35]
	s_mov_b32 m0, s65
	s_nop 0
	global_load_lds_dwordx4 v128, s[34:35]
	s_waitcnt vmcnt(6)
	s_barrier
	s_setprio 1
	s_setprio 0
	s_barrier
	ds_read_b128 v[140:143], v155
	ds_read_b128 v[170:173], v156
	ds_read_b128 v[174:177], v157
	ds_read_b128 v[178:181], v165
	s_add_u32 s34, s54, 0x44000
	s_addc_u32 s35, s55, 0
	s_mov_b32 m0, s66
	ds_read_b128 v[182:185], v145 offset:32768
	ds_read_b128 v[186:189], v145 offset:33792
	ds_read_b128 v[190:193], v145 offset:34816
	ds_read_b128 v[194:197], v145 offset:35840
	ds_read_b128 v[198:201], v145 offset:36864
	ds_read_b128 v[202:205], v145 offset:37888
	ds_read_b128 v[206:209], v145 offset:38912
	ds_read_b128 v[210:213], v145 offset:39936
	global_load_lds_dwordx4 v130, s[34:35]
	s_mov_b32 m0, s67
	s_nop 0
	global_load_lds_dwordx4 v128, s[34:35]
	s_waitcnt lgkmcnt(8)
	s_barrier
	s_waitcnt lgkmcnt(0)
	s_setprio 1
	s_waitcnt lgkmcnt(0)
	v_mfma_f32_16x16x32_bf16 v[124:127], v[140:143], v[182:185], v[124:127]
	v_mfma_f32_16x16x32_bf16 v[120:123], v[174:177], v[182:185], v[120:123]
	v_mfma_f32_16x16x32_bf16 v[108:111], v[140:143], v[190:193], v[108:111]
	v_mfma_f32_16x16x32_bf16 v[104:107], v[174:177], v[190:193], v[104:107]
	v_mfma_f32_16x16x32_bf16 v[92:95], v[140:143], v[198:201], v[92:95]
	v_mfma_f32_16x16x32_bf16 v[88:91], v[174:177], v[198:201], v[88:91]
	v_mfma_f32_16x16x32_bf16 v[76:79], v[140:143], v[206:209], v[76:79]
	v_mfma_f32_16x16x32_bf16 v[72:75], v[174:177], v[206:209], v[72:75]
	v_mfma_f32_16x16x32_bf16 v[124:127], v[170:173], v[186:189], v[124:127]
	v_mfma_f32_16x16x32_bf16 v[120:123], v[178:181], v[186:189], v[120:123]
	v_mfma_f32_16x16x32_bf16 v[108:111], v[170:173], v[194:197], v[108:111]
	v_mfma_f32_16x16x32_bf16 v[104:107], v[178:181], v[194:197], v[104:107]
	v_mfma_f32_16x16x32_bf16 v[92:95], v[170:173], v[202:205], v[92:95]
	v_mfma_f32_16x16x32_bf16 v[88:91], v[178:181], v[202:205], v[88:91]
	v_mfma_f32_16x16x32_bf16 v[76:79], v[170:173], v[210:213], v[76:79]
	v_mfma_f32_16x16x32_bf16 v[72:75], v[178:181], v[210:213], v[72:75]
	s_setprio 0
	s_barrier
; #define PG8_STAGE(bufoff, gbase, voff) do { _Pragma("unroll") for (int _i = 0; _i < 2; ++_i) \
;         __builtin_amdgcn_global_load_lds((const unsigned*)((const char*)(gbase) + (voff)[_i]), (PG8_LAS unsigned*)(lds + (bufoff) + ldsw + _i * 8192), 16, 0, 0); } while (0)
; #define PG8_LDA(dst, b, h) do { _Pragma("unroll") for (int m = 0; m < 4; ++m) _Pragma("unroll") for (int k = 0; k < 2; ++k) dst[m][k] = *(const PG8_LAS bf16x8*)(lds + PG8_SA(b, h) + aoff + m * 2048 + k * 1024); } while (0)
; #define PG8_LDB(dst, b, h) do { _Pragma("unroll") for (int n = 0; n < 2; ++n) _Pragma("unroll") for (int k = 0; k < 2; ++k) dst[n][k] = *(const PG8_LAS bf16x8*)(lds + PG8_SB(b, h) + boff + n * 2048 + k * 1024); } while (0)
; #define PG8_MMA(ai, bj, At, Bt) do { __builtin_amdgcn_s_setprio(1); _Pragma("unroll") for (int m = 0; m < 4; ++m) _Pragma("unroll") for (int n = 0; n < 2; ++n) _Pragma("unroll") for (int k = 0; k < 2; ++k) \
;         acc[ai][bj][m][n] = __builtin_amdgcn_mfma_f32_16x16x32_bf16(Bt[n][k], At[m][k], acc[ai][bj][m][n], 0, 0, 0); __builtin_amdgcn_s_setprio(0); } while (0)
; #define PG8_WAIT_V(n) asm volatile("s_waitcnt vmcnt(" #n ")" ::: "memory")
; #define PG8_WAIT_L(n) asm volatile("s_waitcnt lgkmcnt(" #n ")" ::: "memory")
; #define PG8_BAR __builtin_amdgcn_s_barrier()
; #define PG8_SCHED __builtin_amdgcn_sched_barrier(0)
; template <class Epi, class Sched, bool STAMP = false>
; __device__ __forceinline__ void gemm_phase(PG8_LAS unsigned char* lds, const Gemm g, const Sched& S, const Epi& E, unsigned long long* stamps) {
;     ...
;             PG8_LDB(B0, 1, 0); PG8_SCHED; PG8_LDA(At, 1, 0); PG8_STAGE(PG8_SA(0, 1), a2 + hstep, voffA);
;             PG8_WAIT_L(8); PG8_BAR; PG8_WAIT_L(0); PG8_MMA(0, 0, At, B0); PG8_BAR; PG8_SCHED;
;             PG8_LDB(B1, 1, 1); PG8_STAGE(PG8_SB(1, 0), b3, voffB);
;             PG8_BAR; PG8_WAIT_L(0); PG8_MMA(0, 1, At, B1); PG8_BAR;
;             PG8_LDA(At, 1, 1); PG8_STAGE(PG8_SA(1, 0), a3, voffA);
;             PG8_BAR; PG8_WAIT_L(0); PG8_MMA(1, 0, At, B0); PG8_BAR; PG8_SCHED;
;             PG8_STAGE(PG8_SB(1, 1), b3 + hstep, voffB);
;             PG8_WAIT_V(6); PG8_BAR; PG8_MMA(1, 1, At, B1); PG8_BAR;
;         }
	s_mov_b32 m0, s70
	s_add_u32 s100, s52, 0x80
	s_addc_u32 s101, s53, 0
	global_load_lds_dwordx4 v130, s[100:101]
	s_mov_b32 m0, s71
	s_nop 0
	global_load_lds_dwordx4 v128, s[100:101]
	s_barrier
	s_waitcnt lgkmcnt(0)
	s_setprio 1
	s_waitcnt lgkmcnt(0)
	s_setprio 0
	s_mov_b32 m0, s73
	s_barrier
	ds_read_b128 v[182:185], v145 offset:49152
	ds_read_b128 v[186:189], v145 offset:50176
	ds_read_b128 v[190:193], v145 offset:51200
	ds_read_b128 v[194:197], v145 offset:52224
	ds_read_b128 v[198:201], v145 offset:53248
	ds_read_b128 v[202:205], v145 offset:54272
	ds_read_b128 v[206:209], v145 offset:55296
	ds_read_b128 v[210:213], v145 offset:56320
	s_add_u32 s100, s54, 0x80
	s_addc_u32 s101, s55, 0
	global_load_lds_dwordx4 v130, s[100:101]
	s_mov_b32 m0, s74
	s_nop 0
	global_load_lds_dwordx4 v128, s[100:101]
	s_barrier
	s_waitcnt lgkmcnt(0)
	s_setprio 1
	s_waitcnt lgkmcnt(0)
	v_mfma_f32_16x16x32_bf16 v[60:63], v[140:143], v[182:185], v[60:63]
	v_mfma_f32_16x16x32_bf16 v[56:59], v[174:177], v[182:185], v[56:59]
	v_mfma_f32_16x16x32_bf16 v[44:47], v[140:143], v[190:193], v[44:47]
	v_mfma_f32_16x16x32_bf16 v[40:43], v[174:177], v[190:193], v[40:43]
	v_mfma_f32_16x16x32_bf16 v[28:31], v[140:143], v[198:201], v[28:31]
	v_mfma_f32_16x16x32_bf16 v[24:27], v[174:177], v[198:201], v[24:27]
	v_mfma_f32_16x16x32_bf16 v[12:15], v[140:143], v[206:209], v[12:15]
	v_mfma_f32_16x16x32_bf16 v[8:11], v[174:177], v[206:209], v[8:11]
	v_mfma_f32_16x16x32_bf16 v[60:63], v[170:173], v[186:189], v[60:63]
	v_mfma_f32_16x16x32_bf16 v[56:59], v[178:181], v[186:189], v[56:59]
	v_mfma_f32_16x16x32_bf16 v[44:47], v[170:173], v[194:197], v[44:47]
	v_mfma_f32_16x16x32_bf16 v[40:43], v[178:181], v[194:197], v[40:43]
	v_mfma_f32_16x16x32_bf16 v[28:31], v[170:173], v[202:205], v[28:31]
	v_mfma_f32_16x16x32_bf16 v[24:27], v[178:181], v[202:205], v[24:27]
	v_mfma_f32_16x16x32_bf16 v[12:15], v[170:173], v[210:213], v[12:15]
	v_mfma_f32_16x16x32_bf16 v[8:11], v[178:181], v[210:213], v[8:11]
	s_setprio 0
	s_barrier
	s_add_u32 s34, s52, 0x44080
	s_addc_u32 s35, s53, 0
	s_mov_b32 m0, s75
	s_nop 0
	global_load_lds_dwordx4 v130, s[34:35]
	s_mov_b32 m0, s76
	s_nop 0
	global_load_lds_dwordx4 v128, s[34:35]
	s_waitcnt vmcnt(6)
	s_barrier
	s_setprio 1
	s_setprio 0
	s_add_i32 s89, s89, 2
	s_add_u32 s87, s87, 0x100
	s_addc_u32 s88, s88, 0
	s_cmp_gt_u32 s89, 13
	s_mov_b64 s[34:35], s[36:37]
	s_barrier
	s_cbranch_scc0 .Lgu2_half_loop
; DI float ex2(float x) { return __builtin_amdgcn_exp2f(x); }
;     DI void operator()(const f32x4 (&acc)[2][2][4][2], const Unit& u, int wr, int wc, int fr, int fq) const {
;     ...
;             for (int m = 0; m < 4; ++m) { u16* rowp = O + (size_t)(row0 + ai * HALF + m * 16) * ldc + hcol0;
; #pragma unroll
;                 for (int bj = 0; bj < 2; ++bj) { const f32x4 g = acc[ai][bj][m][0], up = acc[ai][bj][m][1]; float r[4];
; #pragma unroll
;                     for (int j = 0; j < 4; ++j) r[j] = g[j] * up[j] * __builtin_amdgcn_rcpf(1.f + ex2(-LOG2E * g[j]));
;                     uint2 w = {pack2(r[0], r[1]), pack2(r[2], r[3])}; *(uint2*)(rowp + bj * (HALF / 2)) = w; } }
	v_exp_f32_e64 v171, -v124
	v_exp_f32_e64 v175, -v125
	s_lshl_b32 s10, s86, 8
	v_add_f32_e32 v171, 1.0, v171
	v_rcp_f32_e32 v174, v171
	v_add_f32_e32 v171, 1.0, v175
	v_exp_f32_e64 v176, -v126
	v_exp_f32_e64 v177, -v127
	v_rcp_f32_e32 v175, v171
	v_add_f32_e32 v171, 1.0, v176
	v_rcp_f32_e32 v176, v171
	v_add_f32_e32 v171, 1.0, v177
	v_rcp_f32_e32 v177, v171
	v_pk_mul_f32 v[122:123], v[126:127], v[122:123]
	v_pk_mul_f32 v[120:121], v[124:125], v[120:121]
	s_or_b32 s10, s10, s69
	s_or_b32 s10, s10, s98
	v_pk_mul_f32 v[120:121], v[120:121], v[174:175]
	v_pk_mul_f32 v[122:123], v[122:123], v[176:177]
	s_ashr_i32 s10, s10, 1
	v_cvt_pk_bf16_f32 v120, v120, v121
	v_cvt_pk_bf16_f32 v121, v122, v123
	v_or_b32_e32 v140, s10, v146
	v_lshl_add_u32 v170, s85, 8, v144
	v_ashrrev_i32_e32 v141, 31, v140
	v_mov_b64_e32 v[142:143], s[12:13]
	v_mad_i64_i32 v[172:173], s[34:35], v170, s82, v[142:143]
	v_lshlrev_b64 v[140:141], 1, v[140:141]
	v_lshl_add_u64 v[172:173], v[172:173], 0, v[140:141]
	global_store_dwordx2 v[172:173], v[120:121], off
	v_exp_f32_e64 v114, -v108
	v_exp_f32_e64 v115, -v109
	v_exp_f32_e64 v116, -v110
	v_exp_f32_e64 v117, -v111
	v_add_f32_e32 v114, 1.0, v114
	v_add_f32_e32 v115, 1.0, v115
	v_add_f32_e32 v116, 1.0, v116
	v_add_f32_e32 v117, 1.0, v117
	v_rcp_f32_e32 v114, v114
	v_rcp_f32_e32 v115, v115
	v_rcp_f32_e32 v116, v116
	v_rcp_f32_e32 v117, v117
	v_pk_mul_f32 v[106:107], v[110:111], v[106:107]
	v_pk_mul_f32 v[104:105], v[108:109], v[104:105]
	v_pk_mul_f32 v[104:105], v[104:105], v[114:115]
	v_pk_mul_f32 v[106:107], v[106:107], v[116:117]
	v_cvt_pk_bf16_f32 v104, v104, v105
	v_cvt_pk_bf16_f32 v105, v106, v107
	v_or_b32_e32 v112, 16, v170
	v_mad_i64_i32 v[112:113], s[34:35], v112, s82, v[142:143]
	v_lshl_add_u64 v[112:113], v[112:113], 0, v[140:141]
	global_store_dwordx2 v[112:113], v[104:105], off
	v_exp_f32_e64 v98, -v92
	v_exp_f32_e64 v99, -v93
	v_exp_f32_e64 v100, -v94
	v_exp_f32_e64 v101, -v95
	v_add_f32_e32 v98, 1.0, v98
	v_add_f32_e32 v99, 1.0, v99
	v_add_f32_e32 v100, 1.0, v100
	v_add_f32_e32 v101, 1.0, v101
	v_rcp_f32_e32 v98, v98
	v_rcp_f32_e32 v99, v99
	v_rcp_f32_e32 v100, v100
	v_rcp_f32_e32 v101, v101
	v_pk_mul_f32 v[90:91], v[94:95], v[90:91]
	v_pk_mul_f32 v[88:89], v[92:93], v[88:89]
	v_pk_mul_f32 v[88:89], v[88:89], v[98:99]
	v_pk_mul_f32 v[90:91], v[90:91], v[100:101]
	v_cvt_pk_bf16_f32 v88, v88, v89
	v_cvt_pk_bf16_f32 v89, v90, v91
	v_or_b32_e32 v96, 32, v170
	v_mad_i64_i32 v[96:97], s[34:35], v96, s82, v[142:143]
	v_lshl_add_u64 v[96:97], v[96:97], 0, v[140:141]
	global_store_dwordx2 v[96:97], v[88:89], off
	v_exp_f32_e64 v82, -v76
	v_exp_f32_e64 v83, -v77
	v_exp_f32_e64 v84, -v78
	v_exp_f32_e64 v85, -v79
	v_add_f32_e32 v82, 1.0, v82
	v_add_f32_e32 v83, 1.0, v83
	v_add_f32_e32 v84, 1.0, v84
	v_add_f32_e32 v85, 1.0, v85
	v_rcp_f32_e32 v82, v82
	v_rcp_f32_e32 v83, v83
	v_rcp_f32_e32 v84, v84
	v_rcp_f32_e32 v85, v85
	v_pk_mul_f32 v[74:75], v[78:79], v[74:75]
	v_pk_mul_f32 v[72:73], v[76:77], v[72:73]
	v_pk_mul_f32 v[72:73], v[72:73], v[82:83]
	v_pk_mul_f32 v[74:75], v[74:75], v[84:85]
	v_cvt_pk_bf16_f32 v72, v72, v73
	v_cvt_pk_bf16_f32 v73, v74, v75
	v_or_b32_e32 v80, 48, v170
	v_mad_i64_i32 v[80:81], s[34:35], v80, s82, v[142:143]
	v_lshl_add_u64 v[80:81], v[80:81], 0, v[140:141]
	global_store_dwordx2 v[80:81], v[72:73], off
	v_exp_f32_e64 v66, -v60
	v_exp_f32_e64 v67, -v61
	v_exp_f32_e64 v68, -v62
	v_exp_f32_e64 v69, -v63
	v_add_f32_e32 v66, 1.0, v66
	v_add_f32_e32 v67, 1.0, v67
	v_add_f32_e32 v68, 1.0, v68
	v_add_f32_e32 v69, 1.0, v69
	v_rcp_f32_e32 v66, v66
	v_rcp_f32_e32 v67, v67
	v_rcp_f32_e32 v68, v68
	v_rcp_f32_e32 v69, v69
	v_pk_mul_f32 v[58:59], v[62:63], v[58:59]
	v_pk_mul_f32 v[56:57], v[60:61], v[56:57]
	v_pk_mul_f32 v[56:57], v[56:57], v[66:67]
	v_pk_mul_f32 v[58:59], v[58:59], v[68:69]
	v_cvt_pk_bf16_f32 v56, v56, v57
	v_cvt_pk_bf16_f32 v57, v58, v59
	v_add_u32_e32 v64, 0x80, v170
	v_mad_i64_i32 v[64:65], s[34:35], v64, s82, v[142:143]
	v_lshl_add_u64 v[64:65], v[64:65], 0, v[140:141]
	global_store_dwordx2 v[64:65], v[56:57], off
	v_exp_f32_e64 v50, -v44
	v_exp_f32_e64 v51, -v45
	v_exp_f32_e64 v52, -v46
	v_exp_f32_e64 v53, -v47
	v_add_f32_e32 v50, 1.0, v50
	v_add_f32_e32 v51, 1.0, v51
	v_add_f32_e32 v52, 1.0, v52
	v_add_f32_e32 v53, 1.0, v53
	v_rcp_f32_e32 v50, v50
	v_rcp_f32_e32 v51, v51
	v_rcp_f32_e32 v52, v52
	v_rcp_f32_e32 v53, v53
	v_pk_mul_f32 v[42:43], v[46:47], v[42:43]
	v_pk_mul_f32 v[40:41], v[44:45], v[40:41]
	v_pk_mul_f32 v[40:41], v[40:41], v[50:51]
	v_pk_mul_f32 v[42:43], v[42:43], v[52:53]
	v_cvt_pk_bf16_f32 v40, v40, v41
	v_cvt_pk_bf16_f32 v41, v42, v43
	v_add_u32_e32 v48, 0x90, v170
	v_mad_i64_i32 v[48:49], s[34:35], v48, s82, v[142:143]
	v_lshl_add_u64 v[48:49], v[48:49], 0, v[140:141]
	global_store_dwordx2 v[48:49], v[40:41], off
	v_exp_f32_e64 v34, -v28
	v_exp_f32_e64 v35, -v29
	v_exp_f32_e64 v36, -v30
	v_exp_f32_e64 v37, -v31
	v_add_f32_e32 v34, 1.0, v34
	v_add_f32_e32 v35, 1.0, v35
	v_add_f32_e32 v36, 1.0, v36
	v_add_f32_e32 v37, 1.0, v37
	v_rcp_f32_e32 v34, v34
	v_rcp_f32_e32 v35, v35
	v_rcp_f32_e32 v36, v36
	v_rcp_f32_e32 v37, v37
	v_pk_mul_f32 v[26:27], v[30:31], v[26:27]
	v_pk_mul_f32 v[24:25], v[28:29], v[24:25]
	v_pk_mul_f32 v[24:25], v[24:25], v[34:35]
	v_pk_mul_f32 v[26:27], v[26:27], v[36:37]
	v_cvt_pk_bf16_f32 v24, v24, v25
	v_cvt_pk_bf16_f32 v25, v26, v27
	v_add_u32_e32 v32, 0xa0, v170
	v_mad_i64_i32 v[32:33], s[34:35], v32, s82, v[142:143]
	v_lshl_add_u64 v[32:33], v[32:33], 0, v[140:141]
	global_store_dwordx2 v[32:33], v[24:25], off
	v_exp_f32_e64 v18, -v12
	v_exp_f32_e64 v19, -v13
	v_exp_f32_e64 v20, -v14
	v_exp_f32_e64 v21, -v15
	v_add_f32_e32 v18, 1.0, v18
	v_add_f32_e32 v19, 1.0, v19
	v_add_f32_e32 v20, 1.0, v20
	v_add_f32_e32 v21, 1.0, v21
	v_rcp_f32_e32 v18, v18
	v_rcp_f32_e32 v19, v19
	v_rcp_f32_e32 v20, v20
	v_rcp_f32_e32 v21, v21
	v_pk_mul_f32 v[10:11], v[14:15], v[10:11]
	v_pk_mul_f32 v[8:9], v[12:13], v[8:9]
	v_pk_mul_f32 v[8:9], v[8:9], v[18:19]
	v_pk_mul_f32 v[10:11], v[10:11], v[20:21]
	v_cvt_pk_bf16_f32 v8, v8, v9
	v_cvt_pk_bf16_f32 v9, v10, v11
	v_add_u32_e32 v16, 0xb0, v170
	v_mad_i64_i32 v[16:17], s[34:35], v16, s82, v[142:143]
	v_lshl_add_u64 v[16:17], v[16:17], 0, v[140:141]
	global_store_dwordx2 v[16:17], v[8:9], off
	s_and_b64 vcc, exec, s[2:3]
	s_mov_b32 s86, s83
	s_mov_b32 s85, s84
	s_mov_b64 s[36:37], s[0:1]
	s_mov_b64 s[34:35], s[4:5]

; DI unsigned bar_add(unsigned* p, unsigned v) { return __hip_atomic_fetch_add(p, v, __ATOMIC_RELAXED, __HIP_MEMORY_SCOPE_AGENT); }
; DI void grid_barrier(unsigned* bar, unsigned k, volatile unsigned* meta) {
;     ...
;   if (threadIdx.x == 0) {
;     const unsigned nloc = meta[0], nx = meta[1], x = meta[2];
;     const unsigned old = bar_add(bar + 1024 + 64 * x, 1u);
;     if (old + 1u == k * nloc) {
;       __builtin_amdgcn_fence(__ATOMIC_RELEASE, "agent");
;       asm volatile("s_waitcnt vmcnt(0)" ::: "memory");
;       const unsigned old2 = bar_add(bar + 3072, 1u);
.LBB0_356:
	s_waitcnt vmcnt(0)
	s_waitcnt vmcnt(0) lgkmcnt(0)
	s_barrier
	s_and_saveexec_b64 s[0:1], s[8:9]
	s_cbranch_execz .LBB0_366
	s_mov_b64 s[2:3], src_shared_base
	v_mov_b32_e32 v0, 0x24040
	ds_read_b32 v3, v0
	ds_read_b32 v2, v0 offset:4
	ds_read_b32 v0, v0 offset:8
	v_mov_b32_e32 v1, 0
	v_mov_b32_e32 v6, 1
	s_waitcnt lgkmcnt(0)
	v_mul_lo_u32 v3, v3, 10
	v_lshlrev_b32_e32 v0, 6, v0
	v_lshl_add_u64 v[0:1], v[0:1], 2, s[24:25]
	v_add_co_u32_e32 v4, vcc, 0xef01000, v0
	s_nop 1
	v_addc_co_u32_e32 v5, vcc, 0, v1, vcc
	global_atomic_add v4, v[4:5], v6, off offset:1024 sc0
	s_waitcnt vmcnt(0)
	v_add_u32_e32 v4, 1, v4
	v_cmp_eq_u32_e32 vcc, v4, v3
	s_and_saveexec_b64 s[2:3], vcc
	s_cbranch_execz .LBB0_362
	s_mov_b64 s[4:5], exec
	buffer_wbl2 sc1
	s_waitcnt vmcnt(0)
	v_mbcnt_lo_u32_b32 v3, s4, 0
	v_mbcnt_hi_u32_b32 v3, s5, v3
	v_cmp_eq_u32_e32 vcc, 0, v3
	s_and_saveexec_b64 s[6:7], vcc
	s_cbranch_execz .LBB0_360
	s_bcnt1_i32_b64 s4, s[4:5]
	v_mov_b32_e32 v4, 0xef03000
	v_mov_b32_e32 v5, s4
	global_atomic_add v4, v4, v5, s[24:25] offset:1024 sc0

; DI unsigned bar_add(unsigned* p, unsigned v) { return __hip_atomic_fetch_add(p, v, __ATOMIC_RELAXED, __HIP_MEMORY_SCOPE_AGENT); }
; DI void grid_barrier(unsigned* bar, unsigned k, volatile unsigned* meta) {
;     ...
;   if (threadIdx.x == 0) {
;     const unsigned nloc = meta[0], nx = meta[1], x = meta[2];
;     const unsigned old = bar_add(bar + 1024 + 64 * x, 1u);
;     if (old + 1u == k * nloc) {
;       __builtin_amdgcn_fence(__ATOMIC_RELEASE, "agent");
;       asm volatile("s_waitcnt vmcnt(0)" ::: "memory");
;       const unsigned old2 = bar_add(bar + 3072, 1u);
.LBB0_390:
	s_waitcnt vmcnt(0)
	s_waitcnt vmcnt(0) lgkmcnt(0)
	s_barrier
	s_and_saveexec_b64 s[0:1], s[8:9]
	s_cbranch_execz .LBB0_400
	s_mov_b64 s[2:3], src_shared_base
	v_mov_b32_e32 v0, 0x24040
	ds_read_b32 v3, v0
	ds_read_b32 v2, v0 offset:4
	ds_read_b32 v0, v0 offset:8
	v_mov_b32_e32 v1, 0
	v_mov_b32_e32 v6, 1
	s_waitcnt lgkmcnt(0)
	v_mul_lo_u32 v3, v3, 11
	v_lshlrev_b32_e32 v0, 6, v0
	v_lshl_add_u64 v[0:1], v[0:1], 2, s[24:25]
	v_add_co_u32_e32 v4, vcc, 0xef01000, v0
	s_nop 1
	v_addc_co_u32_e32 v5, vcc, 0, v1, vcc
	global_atomic_add v4, v[4:5], v6, off offset:1024 sc0
	s_waitcnt vmcnt(0)
	v_add_u32_e32 v4, 1, v4
	v_cmp_eq_u32_e32 vcc, v4, v3
	s_and_saveexec_b64 s[2:3], vcc
	s_cbranch_execz .LBB0_396
	s_mov_b64 s[4:5], exec
	buffer_wbl2 sc1
	s_waitcnt vmcnt(0)
	v_mbcnt_lo_u32_b32 v3, s4, 0
	v_mbcnt_hi_u32_b32 v3, s5, v3
	v_cmp_eq_u32_e32 vcc, 0, v3
	s_and_saveexec_b64 s[6:7], vcc
	s_cbranch_execz .LBB0_394
	s_bcnt1_i32_b64 s4, s[4:5]
	v_mov_b32_e32 v4, 0xef03000
	v_mov_b32_e32 v5, s4
	global_atomic_add v4, v4, v5, s[24:25] offset:1024 sc0

; DI int ltid() { int t = threadIdx.x; asm volatile("" : "+v"(t)); return t; }
; DI unsigned bar_add(unsigned* p, unsigned v) { return __hip_atomic_fetch_add(p, v, __ATOMIC_RELAXED, __HIP_MEMORY_SCOPE_AGENT); }
; DI void conv_tile(const float* __restrict__ src, int K, int N, u16* __restrict__ dst, int ldd, int mode, int tile, float* tl) {
;   const int tid = ltid();
;   const int nNt = N >> 6;
;   const int kt = tile / nNt, nt = tile - kt * nNt;
;   const int k0 = kt << 6, n0 = nt << 6;
;   {
;     const int kl = tid >> 4, n4 = (tid & 15) * 4;
;     const float* sp = src + (size_t)(k0 + kl) * N + n0 + n4;
;     const f32x4 v0 = __builtin_nontemporal_load((const f32x4*)(sp));
;     const f32x4 v1 = __builtin_nontemporal_load((const f32x4*)(sp + (size_t)32 * N));
;     __builtin_amdgcn_sched_barrier(0);
;     float* d = tl + kl * 65 + n4;
;     d[0] = v0[0]; d[1] = v0[1]; d[2] = v0[2]; d[3] = v0[3];
;     d += 32 * 65;
;     d[0] = v1[0]; d[1] = v1[1]; d[2] = v1[2]; d[3] = v1[3];
;   }
;   __syncthreads();
;   {
;     const int nl = tid >> 3, k8 = (tid & 7) * 8;
;     const int n = n0 + nl;
;     float sc = 1.f;
;     int row = n;
;     if (mode == 1) row = ((n >> 4) << 5) + (n & 15);
;     else if (mode == 2) row = ((n >> 4) << 5) + 16 + (n & 15);
;     else if (mode == 3) {
;       if (n < 384) sc = 0.125f * LOG2E;
;       else if (n >= 1152 && n < 1408) sc = 0.17677669529663687f * LOG2E;
;       else if (n >= 1920 && n < 2304) sc = 0.125f * LOG2E;
;     }
;     const float* t = tl + k8 * 65 + nl;
;     uint4 o = {pack2(t[0] * sc, t[65] * sc), pack2(t[130] * sc, t[195] * sc), pack2(t[260] * sc, t[325] * sc),
;                pack2(t[390] * sc, t[455] * sc)};
;     *(uint4*)(dst + (size_t)row * ldd + k0 + k8) = o;
; DI void grid_barrier(unsigned* bar, unsigned k, volatile unsigned* meta) {
;   asm volatile("s_waitcnt vmcnt(0)" ::: "memory");
;   __syncthreads();
;   if (threadIdx.x == 0) {
;     const unsigned nloc = meta[0], nx = meta[1], x = meta[2];
;     const unsigned old = bar_add(bar + 1024 + 64 * x, 1u);
;     if (old + 1u == k * nloc) {
;       __builtin_amdgcn_fence(__ATOMIC_RELEASE, "agent");
;       asm volatile("s_waitcnt vmcnt(0)" ::: "memory");
;       const unsigned old2 = bar_add(bar + 3072, 1u);
.LBB0_416:
	s_andn2_b64 vcc, exec, s[6:7]
	s_cbranch_vccnz .LBB0_405
	s_mul_hi_i32 s4, s61, 0x2e8ba2e9
	s_lshr_b32 s6, s4, 31
	s_ashr_i32 s4, s4, 7
	s_add_i32 s4, s4, s6
	s_mul_i32 s6, s4, 0xfffffd40
	s_add_i32 s6, s10, s6
	s_add_i32 s61, s6, 0x1380
	s_ashr_i32 s6, s4, 1
	s_and_b32 s65, s4, 1
	s_cmp_eq_u32 s65, 0
	s_cselect_b32 s7, s41, s43
	s_cselect_b32 s62, s40, s42
	s_add_i32 s6, s6, 2
	s_mul_hi_i32 s63, s6, 0xb00000
	s_mul_i32 s6, s6, 0xb00000
	s_add_u32 s6, s62, s6
	s_addc_u32 s7, s7, s63
	s_cmp_lt_u32 s4, 2
	s_cselect_b32 s62, 0, 0xbb0000
	s_add_u32 s62, s24, s62
	s_mul_hi_i32 s61, s61, 0x2e8ba2e9
	s_addc_u32 s63, s25, 0
	s_lshr_b32 s64, s61, 31
	s_ashr_i32 s61, s61, 3
	s_add_i32 s61, s61, s64
	s_mul_i32 s64, s61, 0x3ffffd4
	s_mulk_i32 s4, 0x2c0
	s_sub_i32 s4, s64, s4
	v_mov_b32_e32 v14, v158
	s_add_i32 s4, s10, s4
	s_lshl_b32 s4, s4, 6
	s_lshl_b32 s64, s61, 6
	v_ashrrev_i32_e32 v12, 4, v14
	s_add_i32 s66, s4, 0x4e000
	v_add_u32_e32 v0, s64, v12
	v_mov_b64_e32 v[4:5], s[6:7]
	v_mad_i64_i32 v[4:5], s[6:7], v0, s59, v[4:5]
	s_ashr_i32 s67, s66, 31
	v_lshlrev_b32_e32 v0, 4, v14
	v_lshl_add_u64 v[4:5], s[66:67], 2, v[4:5]
	v_and_b32_e32 v0, 0xf0, v0
	v_lshl_add_u64 v[4:5], v[4:5], 0, v[0:1]
	v_add_co_u32_e32 v8, vcc, s60, v4
	s_nop 1
	v_addc_co_u32_e32 v9, vcc, 0, v5, vcc
	global_load_dwordx4 v[4:7], v[4:5], off nt
	s_nop 0
	global_load_dwordx4 v[8:11], v[8:9], off nt
	v_mad_u64_u32 v[12:13], s[6:7], v12, s46, v[0:1]
	v_add_u32_e32 v0, 0x2080, v12
	s_waitcnt vmcnt(1)
	ds_write2_b32 v12, v4, v5 offset1:1
	ds_write2_b32 v12, v6, v7 offset0:2 offset1:3
	s_waitcnt vmcnt(0)
	ds_write2_b32 v0, v8, v9 offset1:1
	v_add_u32_e32 v0, 0x2088, v12
	ds_write2_b32 v0, v10, v11 offset1:1
	v_ashrrev_i32_e32 v0, 3, v14
	v_add_lshl_u32 v4, v0, s66, 1
	v_and_b32_e32 v12, 0xffffffe0, v4
	v_lshlrev_b32_e32 v4, 3, v14
	v_and_b32_e32 v13, 15, v0
	v_and_b32_e32 v14, 56, v4
	v_lshlrev_b32_e32 v0, 2, v0
	v_mad_u32_u24 v0, v14, s46, v0
	s_waitcnt lgkmcnt(0)
	s_barrier
	ds_read2_b32 v[4:5], v0 offset1:65
	ds_read2_b32 v[6:7], v0 offset0:130 offset1:195
	v_add_u32_e32 v0, 0x400, v0
	ds_read2_b32 v[8:9], v0 offset0:4 offset1:69
	ds_read2_b32 v[10:11], v0 offset0:134 offset1:199
	s_lshl_b32 s4, s65, 4
	v_or3_b32 v0, v13, v12, s4
	s_mov_b32 s100, 0x3f317218
	s_cmp_eq_u32 s65, 0
	s_cselect_b32 s100, 0x3fb8aa3b, s100
	v_mov_b32_e32 v20, s100
	s_waitcnt lgkmcnt(3)
	v_pk_mul_f32 v[4:5], v[20:21], v[4:5] op_sel_hi:[0,1]
	v_cvt_pk_bf16_f32 v4, v4, v5
	s_waitcnt lgkmcnt(2)
	v_pk_mul_f32 v[6:7], v[20:21], v[6:7] op_sel_hi:[0,1]
	v_cvt_pk_bf16_f32 v5, v6, v7
	s_waitcnt lgkmcnt(1)
	v_pk_mul_f32 v[8:9], v[20:21], v[8:9] op_sel_hi:[0,1]
	v_cvt_pk_bf16_f32 v6, v8, v9
	v_mov_b64_e32 v[8:9], s[62:63]
	v_mad_i64_i32 v[8:9], s[6:7], v0, s47, v[8:9]
	s_ashr_i32 s65, s64, 31
	v_lshl_add_u64 v[8:9], s[64:65], 1, v[8:9]
	v_lshlrev_b32_e32 v0, 1, v14
	s_waitcnt lgkmcnt(0)
	v_pk_mul_f32 v[10:11], v[20:21], v[10:11] op_sel_hi:[0,1]
	v_cvt_pk_bf16_f32 v7, v10, v11
	v_lshl_add_u64 v[8:9], v[8:9], 0, v[0:1]
	global_store_dwordx4 v[8:9], v[4:7], off
	s_barrier
	s_branch .LBB0_405
.LBB0_418:
	s_waitcnt vmcnt(0)
	s_barrier
	s_and_saveexec_b64 s[0:1], s[8:9]
	s_cbranch_execz .LBB0_428
	s_mov_b64 s[2:3], src_shared_base
	v_mov_b32_e32 v0, 0x24040
	ds_read_b32 v3, v0
	ds_read_b32 v2, v0 offset:4
	ds_read_b32 v0, v0 offset:8
	v_mov_b32_e32 v1, 0
	v_mov_b32_e32 v6, 1
	s_waitcnt lgkmcnt(0)
	v_mul_lo_u32 v3, v3, 12
	v_lshlrev_b32_e32 v0, 6, v0
	v_lshl_add_u64 v[0:1], v[0:1], 2, s[24:25]
	v_add_co_u32_e32 v4, vcc, 0xef01000, v0
	s_nop 1
	v_addc_co_u32_e32 v5, vcc, 0, v1, vcc
	global_atomic_add v4, v[4:5], v6, off offset:1024 sc0
	s_waitcnt vmcnt(0)
	v_add_u32_e32 v4, 1, v4
	v_cmp_eq_u32_e32 vcc, v4, v3
	s_and_saveexec_b64 s[2:3], vcc
	s_cbranch_execz .LBB0_424
	s_mov_b64 s[4:5], exec
	buffer_wbl2 sc1
	s_waitcnt vmcnt(0)
	v_mbcnt_lo_u32_b32 v3, s4, 0
	v_mbcnt_hi_u32_b32 v3, s5, v3
	v_cmp_eq_u32_e32 vcc, 0, v3
	s_and_saveexec_b64 s[6:7], vcc
	s_cbranch_execz .LBB0_422
	s_bcnt1_i32_b64 s4, s[4:5]
	v_mov_b32_e32 v4, 0xef03000
	v_mov_b32_e32 v5, s4
	global_atomic_add v4, v4, v5, s[24:25] offset:1024 sc0

; #define PG8_STAGE(bufoff, gbase, voff) do { _Pragma("unroll") for (int _i = 0; _i < 2; ++_i) \
;         __builtin_amdgcn_global_load_lds((const unsigned*)((const char*)(gbase) + (voff)[_i]), (PG8_LAS unsigned*)(lds + (bufoff) + ldsw + _i * 8192), 16, 0, 0); } while (0)
; #define PG8_LDA(dst, b, h) do { _Pragma("unroll") for (int m = 0; m < 4; ++m) _Pragma("unroll") for (int k = 0; k < 2; ++k) dst[m][k] = *(const PG8_LAS bf16x8*)(lds + PG8_SA(b, h) + aoff + m * 2048 + k * 1024); } while (0)
; #define PG8_LDB(dst, b, h) do { _Pragma("unroll") for (int n = 0; n < 2; ++n) _Pragma("unroll") for (int k = 0; k < 2; ++k) dst[n][k] = *(const PG8_LAS bf16x8*)(lds + PG8_SB(b, h) + boff + n * 2048 + k * 1024); } while (0)
; #define PG8_MMA(ai, bj, At, Bt) do { __builtin_amdgcn_s_setprio(1); _Pragma("unroll") for (int m = 0; m < 4; ++m) _Pragma("unroll") for (int n = 0; n < 2; ++n) _Pragma("unroll") for (int k = 0; k < 2; ++k) \
;         acc[ai][bj][m][n] = __builtin_amdgcn_mfma_f32_16x16x32_bf16(Bt[n][k], At[m][k], acc[ai][bj][m][n], 0, 0, 0); __builtin_amdgcn_s_setprio(0); } while (0)
; #define PG8_WAIT_V(n) asm volatile("s_waitcnt vmcnt(" #n ")" ::: "memory")
; #define PG8_WAIT_L(n) asm volatile("s_waitcnt lgkmcnt(" #n ")" ::: "memory")
; #define PG8_BAR __builtin_amdgcn_s_barrier()
; #define PG8_SCHED __builtin_amdgcn_sched_barrier(0)
; template <class Epi, class Sched, bool STAMP = false>
; __device__ __forceinline__ void gemm_phase(PG8_LAS unsigned char* lds, const Gemm g, const Sched& S, const Epi& E, unsigned long long* stamps) {
;     ...
;             PG8_LDB(B0, 1, 0); PG8_SCHED; PG8_LDA(At, 1, 0); PG8_STAGE(PG8_SA(0, 1), a2 + hstep, voffA);
;             PG8_WAIT_L(8); PG8_BAR; PG8_WAIT_L(0); PG8_MMA(0, 0, At, B0); PG8_BAR; PG8_SCHED;
;             PG8_LDB(B1, 1, 1); PG8_STAGE(PG8_SB(1, 0), b3, voffB);
;             PG8_BAR; PG8_WAIT_L(0); PG8_MMA(0, 1, At, B1); PG8_BAR;
;             PG8_LDA(At, 1, 1); PG8_STAGE(PG8_SA(1, 0), a3, voffA);
;             PG8_BAR; PG8_WAIT_L(0); PG8_MMA(1, 0, At, B0); PG8_BAR; PG8_SCHED;
;             PG8_STAGE(PG8_SB(1, 1), b3 + hstep, voffB);
;             PG8_WAIT_V(6); PG8_BAR; PG8_MMA(1, 1, At, B1); PG8_BAR;
.Lzp7_mid:
	ds_read_b128 v[140:143], v155
	ds_read_b128 v[170:173], v156
	ds_read_b128 v[174:177], v157
	ds_read_b128 v[178:181], v165
	s_add_u32 s34, s42, 0x44000
	s_addc_u32 s35, s43, 0
	s_mov_b32 m0, s56
	ds_read_b128 v[182:185], v145 offset:32768
	ds_read_b128 v[186:189], v145 offset:33792
	ds_read_b128 v[190:193], v145 offset:34816
	ds_read_b128 v[194:197], v145 offset:35840
	ds_read_b128 v[198:201], v145 offset:36864
	ds_read_b128 v[202:205], v145 offset:37888
	ds_read_b128 v[206:209], v145 offset:38912
	ds_read_b128 v[210:213], v145 offset:39936
	global_load_lds_dwordx4 v130, s[34:35]
	s_mov_b32 m0, s57
	s_nop 0
	global_load_lds_dwordx4 v128, s[34:35]
	s_waitcnt lgkmcnt(8)
	s_barrier
	s_waitcnt lgkmcnt(0)
	s_setprio 1
	s_waitcnt lgkmcnt(0)
	v_mfma_f32_16x16x32_bf16 v[124:127], v[140:143], v[182:185], v[124:127]
	v_mfma_f32_16x16x32_bf16 v[120:123], v[174:177], v[182:185], v[120:123]
	v_mfma_f32_16x16x32_bf16 v[108:111], v[140:143], v[190:193], v[108:111]
	v_mfma_f32_16x16x32_bf16 v[104:107], v[174:177], v[190:193], v[104:107]
	v_mfma_f32_16x16x32_bf16 v[92:95], v[140:143], v[198:201], v[92:95]
	v_mfma_f32_16x16x32_bf16 v[88:91], v[174:177], v[198:201], v[88:91]
	v_mfma_f32_16x16x32_bf16 v[76:79], v[140:143], v[206:209], v[76:79]
	v_mfma_f32_16x16x32_bf16 v[72:75], v[174:177], v[206:209], v[72:75]
	v_mfma_f32_16x16x32_bf16 v[124:127], v[170:173], v[186:189], v[124:127]
	v_mfma_f32_16x16x32_bf16 v[120:123], v[178:181], v[186:189], v[120:123]
	v_mfma_f32_16x16x32_bf16 v[108:111], v[170:173], v[194:197], v[108:111]
	v_mfma_f32_16x16x32_bf16 v[104:107], v[178:181], v[194:197], v[104:107]
	v_mfma_f32_16x16x32_bf16 v[92:95], v[170:173], v[202:205], v[92:95]
	v_mfma_f32_16x16x32_bf16 v[88:91], v[178:181], v[202:205], v[88:91]
	v_mfma_f32_16x16x32_bf16 v[76:79], v[170:173], v[210:213], v[76:79]
	v_mfma_f32_16x16x32_bf16 v[72:75], v[178:181], v[210:213], v[72:75]
	s_setprio 0
	s_barrier
	s_mov_b32 m0, s60
	ds_read_b128 v[214:217], v166
	ds_read_b128 v[218:221], v167
	ds_read_b128 v[222:225], v168
	ds_read_b128 v[226:229], v169
	s_add_u32 s100, s40, 0x80
	s_addc_u32 s101, s41, 0
	global_load_lds_dwordx4 v130, s[100:101]
	s_mov_b32 m0, s61
	s_nop 0
	global_load_lds_dwordx4 v128, s[100:101]
	s_barrier
	s_waitcnt lgkmcnt(0)
	s_setprio 1
	s_waitcnt lgkmcnt(0)
	v_mfma_f32_16x16x32_bf16 v[116:119], v[214:217], v[182:185], v[116:119]
	v_mfma_f32_16x16x32_bf16 v[112:115], v[222:225], v[182:185], v[112:115]
	v_mfma_f32_16x16x32_bf16 v[100:103], v[214:217], v[190:193], v[100:103]
	v_mfma_f32_16x16x32_bf16 v[96:99], v[222:225], v[190:193], v[96:99]
	v_mfma_f32_16x16x32_bf16 v[84:87], v[214:217], v[198:201], v[84:87]
	v_mfma_f32_16x16x32_bf16 v[80:83], v[222:225], v[198:201], v[80:83]
	v_mfma_f32_16x16x32_bf16 v[68:71], v[214:217], v[206:209], v[68:71]
	v_mfma_f32_16x16x32_bf16 v[64:67], v[222:225], v[206:209], v[64:67]
	v_mfma_f32_16x16x32_bf16 v[116:119], v[218:221], v[186:189], v[116:119]
	v_mfma_f32_16x16x32_bf16 v[112:115], v[226:229], v[186:189], v[112:115]
	v_mfma_f32_16x16x32_bf16 v[100:103], v[218:221], v[194:197], v[100:103]
	v_mfma_f32_16x16x32_bf16 v[96:99], v[226:229], v[194:197], v[96:99]
	v_mfma_f32_16x16x32_bf16 v[84:87], v[218:221], v[202:205], v[84:87]
	v_mfma_f32_16x16x32_bf16 v[80:83], v[226:229], v[202:205], v[80:83]
	v_mfma_f32_16x16x32_bf16 v[68:71], v[218:221], v[210:213], v[68:71]
	v_mfma_f32_16x16x32_bf16 v[64:67], v[226:229], v[210:213], v[64:67]
	s_setprio 0
	s_mov_b32 m0, s62
	s_barrier
	ds_read_b128 v[182:185], v145 offset:49152
	ds_read_b128 v[186:189], v145 offset:50176
	ds_read_b128 v[190:193], v145 offset:51200
	ds_read_b128 v[194:197], v145 offset:52224
	ds_read_b128 v[198:201], v145 offset:53248
	ds_read_b128 v[202:205], v145 offset:54272
	ds_read_b128 v[206:209], v145 offset:55296
	ds_read_b128 v[210:213], v145 offset:56320
	s_add_u32 s100, s42, 0x80
	s_addc_u32 s101, s43, 0
	global_load_lds_dwordx4 v130, s[100:101]
	s_mov_b32 m0, s63
	s_nop 0
	global_load_lds_dwordx4 v128, s[100:101]
	s_barrier
	s_waitcnt lgkmcnt(0)
	s_setprio 1
	s_waitcnt lgkmcnt(0)
	v_mfma_f32_16x16x32_bf16 v[60:63], v[140:143], v[182:185], v[60:63]
	v_mfma_f32_16x16x32_bf16 v[56:59], v[174:177], v[182:185], v[56:59]
	v_mfma_f32_16x16x32_bf16 v[44:47], v[140:143], v[190:193], v[44:47]
	v_mfma_f32_16x16x32_bf16 v[40:43], v[174:177], v[190:193], v[40:43]
	v_mfma_f32_16x16x32_bf16 v[28:31], v[140:143], v[198:201], v[28:31]
	v_mfma_f32_16x16x32_bf16 v[24:27], v[174:177], v[198:201], v[24:27]
	v_mfma_f32_16x16x32_bf16 v[12:15], v[140:143], v[206:209], v[12:15]
	v_mfma_f32_16x16x32_bf16 v[8:11], v[174:177], v[206:209], v[8:11]
	v_mfma_f32_16x16x32_bf16 v[60:63], v[170:173], v[186:189], v[60:63]
	v_mfma_f32_16x16x32_bf16 v[56:59], v[178:181], v[186:189], v[56:59]
	v_mfma_f32_16x16x32_bf16 v[44:47], v[170:173], v[194:197], v[44:47]
	v_mfma_f32_16x16x32_bf16 v[40:43], v[178:181], v[194:197], v[40:43]
	v_mfma_f32_16x16x32_bf16 v[28:31], v[170:173], v[202:205], v[28:31]
	v_mfma_f32_16x16x32_bf16 v[24:27], v[178:181], v[202:205], v[24:27]
	v_mfma_f32_16x16x32_bf16 v[12:15], v[170:173], v[210:213], v[12:15]
	v_mfma_f32_16x16x32_bf16 v[8:11], v[178:181], v[210:213], v[8:11]
	s_setprio 0
	s_barrier
	s_add_u32 s34, s40, 0x44080
	s_addc_u32 s35, s41, 0
	s_mov_b32 m0, s64
	s_nop 0
	global_load_lds_dwordx4 v130, s[34:35]
	s_mov_b32 m0, s65
	s_nop 0
	global_load_lds_dwordx4 v128, s[34:35]
	s_waitcnt vmcnt(6)
	s_barrier
; DI float ex2(float x) { return __builtin_amdgcn_exp2f(x); }
; #define PG8_STAMP() do { if (STAMP && wid == 0 && nts < 64) { const unsigned long long _c = 0ull; \
;         ts_lo = (lane == nts) ? (int)(unsigned)_c : ts_lo; ts_hi = (lane == nts) ? (int)(unsigned)(_c >> 32) : ts_hi; ++nts; } } while (0)
; #define PG8_STAGE(bufoff, gbase, voff) do { _Pragma("unroll") for (int _i = 0; _i < 2; ++_i) \
;         __builtin_amdgcn_global_load_lds((const unsigned*)((const char*)(gbase) + (voff)[_i]), (PG8_LAS unsigned*)(lds + (bufoff) + ldsw + _i * 8192), 16, 0, 0); } while (0)
;     DI void operator()(const f32x4 (&acc)[2][2][4][2], const Unit& u, int wr, int wc, int fr, int fq) const {
;         const int row0 = u.pm * BM + wr * 64 + fr, hcol0 = ((u.pn * BM + wc * 32) >> 1) + 4 * fq;
; #pragma unroll
;         for (int ai = 0; ai < 2; ++ai)
; #pragma unroll
;             for (int m = 0; m < 4; ++m) { u16* rowp = O + (size_t)(row0 + ai * HALF + m * 16) * ldc + hcol0;
; #pragma unroll
;                 for (int bj = 0; bj < 2; ++bj) { const f32x4 g = acc[ai][bj][m][0], up = acc[ai][bj][m][1]; float r[4];
; #pragma unroll
;                     for (int j = 0; j < 4; ++j) r[j] = g[j] * up[j] * __builtin_amdgcn_rcpf(1.f + ex2(-LOG2E * g[j]));
;                     uint2 w = {pack2(r[0], r[1]), pack2(r[2], r[3])}; *(uint2*)(rowp + bj * (HALF / 2)) = w; } }
; template <class Epi, class Sched, bool STAMP = false>
; __device__ __forceinline__ void gemm_phase(PG8_LAS unsigned char* lds, const Gemm g, const Sched& S, const Epi& E, unsigned long long* stamps) {
;     ...
;             PG8_WAIT_V(6); PG8_BAR; PG8_MMA(1, 1, At, B1); PG8_BAR;
;             PG8_LDB(B0, 1, 0); PG8_SCHED; PG8_LDA(At, 1, 0); PG8_STAGE(PG8_SA(0, 1), a2 + hstep, voffA);
;             PG8_WAIT_L(8); PG8_BAR; PG8_WAIT_L(0); PG8_MMA(0, 0, At, B0); PG8_BAR; PG8_SCHED;
;             PG8_LDB(B1, 1, 1); PG8_STAGE(PG8_SB(1, 0), b3, voffB);
;             PG8_BAR; PG8_WAIT_L(0); PG8_MMA(0, 1, At, B1); PG8_BAR;
;             PG8_LDA(At, 1, 1); PG8_STAGE(PG8_SA(1, 0), a3, voffA);
;             PG8_BAR; PG8_WAIT_L(0); PG8_MMA(1, 0, At, B0); PG8_BAR; PG8_SCHED;
;             PG8_STAGE(PG8_SB(1, 1), b3 + hstep, voffB);
;             PG8_WAIT_V(6); PG8_BAR; PG8_MMA(1, 1, At, B1); PG8_BAR;
;         }
;         PG8_STAMP();
;         if constexpr (!Epi::AFTER_DRAIN) { E(acc, cur, wr, wc, fr, fq); S.done(cur); }
	s_setprio 1
	v_mfma_f32_16x16x32_bf16 v[52:55], v[214:217], v[182:185], v[52:55]
	v_mfma_f32_16x16x32_bf16 v[48:51], v[222:225], v[182:185], v[48:51]
	v_mfma_f32_16x16x32_bf16 v[36:39], v[214:217], v[190:193], v[36:39]
	v_mfma_f32_16x16x32_bf16 v[32:35], v[222:225], v[190:193], v[32:35]
	v_mfma_f32_16x16x32_bf16 v[20:23], v[214:217], v[198:201], v[20:23]
	v_mfma_f32_16x16x32_bf16 v[16:19], v[222:225], v[198:201], v[16:19]
	v_mfma_f32_16x16x32_bf16 v[4:7], v[214:217], v[206:209], v[4:7]
	v_mfma_f32_16x16x32_bf16 v[0:3], v[222:225], v[206:209], v[0:3]
	v_mfma_f32_16x16x32_bf16 v[52:55], v[218:221], v[186:189], v[52:55]
	v_mfma_f32_16x16x32_bf16 v[48:51], v[226:229], v[186:189], v[48:51]
	v_mfma_f32_16x16x32_bf16 v[36:39], v[218:221], v[194:197], v[36:39]
	v_mfma_f32_16x16x32_bf16 v[32:35], v[226:229], v[194:197], v[32:35]
	v_mfma_f32_16x16x32_bf16 v[20:23], v[218:221], v[202:205], v[20:23]
	v_mfma_f32_16x16x32_bf16 v[16:19], v[226:229], v[202:205], v[16:19]
	v_mfma_f32_16x16x32_bf16 v[4:7], v[218:221], v[210:213], v[4:7]
	v_mfma_f32_16x16x32_bf16 v[0:3], v[226:229], v[210:213], v[0:3]
	s_setprio 0
	s_add_i32 s10, s10, 2
	s_add_u32 s77, s77, 0x100
	s_addc_u32 s78, s78, 0
	s_cmp_gt_u32 s10, 13
	s_mov_b64 s[34:35], s[36:37]
	s_barrier
	s_cbranch_scc0 .LBB0_439
	v_exp_f32_e64 v171, -v124
	v_exp_f32_e64 v175, -v125
	s_lshl_b32 s10, s76, 8
	v_add_f32_e32 v171, 1.0, v171
	v_rcp_f32_e32 v174, v171
	v_add_f32_e32 v171, 1.0, v175
	v_exp_f32_e64 v176, -v126
	v_exp_f32_e64 v177, -v127
	v_rcp_f32_e32 v175, v171
	v_add_f32_e32 v171, 1.0, v176
	v_rcp_f32_e32 v176, v171
	v_add_f32_e32 v171, 1.0, v177
	v_rcp_f32_e32 v177, v171
	v_pk_mul_f32 v[122:123], v[126:127], v[122:123]
	v_pk_mul_f32 v[120:121], v[124:125], v[120:121]
	s_or_b32 s10, s10, s59
	v_pk_mul_f32 v[120:121], v[120:121], v[174:175]
	v_pk_mul_f32 v[122:123], v[122:123], v[176:177]
	s_ashr_i32 s10, s10, 1
	v_cvt_pk_bf16_f32 v120, v120, v121
	v_cvt_pk_bf16_f32 v121, v122, v123
	v_or_b32_e32 v140, s10, v146
	v_exp_f32_e64 v122, -v116
	v_exp_f32_e64 v123, -v117
	v_lshl_add_u32 v170, s75, 8, v144
	v_ashrrev_i32_e32 v141, 31, v140
	v_mov_b64_e32 v[142:143], s[12:13]
	v_mad_i64_i32 v[172:173], s[34:35], v170, s69, v[142:143]
	v_lshlrev_b64 v[140:141], 1, v[140:141]
	v_lshl_add_u64 v[172:173], v[172:173], 0, v[140:141]
	global_store_dwordx2 v[172:173], v[120:121], off
	v_add_f32_e32 v120, 1.0, v122
	v_add_f32_e32 v121, 1.0, v123
	v_exp_f32_e64 v122, -v118
	v_exp_f32_e64 v123, -v119
	v_rcp_f32_e32 v120, v120
	v_rcp_f32_e32 v121, v121
	v_add_f32_e32 v122, 1.0, v122
	v_add_f32_e32 v123, 1.0, v123
	v_rcp_f32_e32 v122, v122
	v_rcp_f32_e32 v123, v123
	v_pk_mul_f32 v[114:115], v[118:119], v[114:115]
	v_pk_mul_f32 v[112:113], v[116:117], v[112:113]
	v_pk_mul_f32 v[112:113], v[112:113], v[120:121]
	v_pk_mul_f32 v[114:115], v[114:115], v[122:123]
	v_cvt_pk_bf16_f32 v112, v112, v113
	v_cvt_pk_bf16_f32 v113, v114, v115
	v_exp_f32_e64 v114, -v108
	v_exp_f32_e64 v115, -v109
	v_exp_f32_e64 v116, -v110
	v_exp_f32_e64 v117, -v111
	v_add_f32_e32 v114, 1.0, v114
	v_add_f32_e32 v115, 1.0, v115
	v_add_f32_e32 v116, 1.0, v116
	v_add_f32_e32 v117, 1.0, v117
	v_rcp_f32_e32 v114, v114
	v_rcp_f32_e32 v115, v115
	v_rcp_f32_e32 v116, v116
	v_rcp_f32_e32 v117, v117
	v_pk_mul_f32 v[106:107], v[110:111], v[106:107]
	v_pk_mul_f32 v[104:105], v[108:109], v[104:105]
	global_store_dwordx2 v[172:173], v[112:113], off offset:128
	v_pk_mul_f32 v[104:105], v[104:105], v[114:115]
	v_pk_mul_f32 v[106:107], v[106:107], v[116:117]
	v_cvt_pk_bf16_f32 v104, v104, v105
	v_cvt_pk_bf16_f32 v105, v106, v107
	v_exp_f32_e64 v106, -v100
	v_exp_f32_e64 v107, -v101
	v_or_b32_e32 v112, 16, v170
	v_mad_i64_i32 v[112:113], s[34:35], v112, s69, v[142:143]
	v_lshl_add_u64 v[112:113], v[112:113], 0, v[140:141]
	global_store_dwordx2 v[112:113], v[104:105], off
	v_add_f32_e32 v104, 1.0, v106
	v_add_f32_e32 v105, 1.0, v107
	v_exp_f32_e64 v106, -v102
	v_exp_f32_e64 v107, -v103
	v_rcp_f32_e32 v104, v104
	v_rcp_f32_e32 v105, v105
	v_add_f32_e32 v106, 1.0, v106
	v_add_f32_e32 v107, 1.0, v107
	v_rcp_f32_e32 v106, v106
	v_rcp_f32_e32 v107, v107
	v_pk_mul_f32 v[98:99], v[102:103], v[98:99]
	v_pk_mul_f32 v[96:97], v[100:101], v[96:97]
	v_pk_mul_f32 v[96:97], v[96:97], v[104:105]
	v_pk_mul_f32 v[98:99], v[98:99], v[106:107]
	v_cvt_pk_bf16_f32 v96, v96, v97
	v_cvt_pk_bf16_f32 v97, v98, v99
	v_exp_f32_e64 v98, -v92
	v_exp_f32_e64 v99, -v93
	v_exp_f32_e64 v100, -v94
	v_exp_f32_e64 v101, -v95
	v_add_f32_e32 v98, 1.0, v98
	v_add_f32_e32 v99, 1.0, v99
	v_add_f32_e32 v100, 1.0, v100
	v_add_f32_e32 v101, 1.0, v101
	v_rcp_f32_e32 v98, v98
	v_rcp_f32_e32 v99, v99
	v_rcp_f32_e32 v100, v100
	v_rcp_f32_e32 v101, v101
	v_pk_mul_f32 v[90:91], v[94:95], v[90:91]
	v_pk_mul_f32 v[88:89], v[92:93], v[88:89]
	global_store_dwordx2 v[112:113], v[96:97], off offset:128
	v_pk_mul_f32 v[88:89], v[88:89], v[98:99]
	v_pk_mul_f32 v[90:91], v[90:91], v[100:101]
	v_cvt_pk_bf16_f32 v88, v88, v89
	v_cvt_pk_bf16_f32 v89, v90, v91
	v_exp_f32_e64 v90, -v84
	v_exp_f32_e64 v91, -v85
	v_or_b32_e32 v96, 32, v170
	v_mad_i64_i32 v[96:97], s[34:35], v96, s69, v[142:143]
	v_lshl_add_u64 v[96:97], v[96:97], 0, v[140:141]
	global_store_dwordx2 v[96:97], v[88:89], off
	v_add_f32_e32 v88, 1.0, v90
	v_add_f32_e32 v89, 1.0, v91
	v_exp_f32_e64 v90, -v86
	v_exp_f32_e64 v91, -v87
	v_rcp_f32_e32 v88, v88
	v_rcp_f32_e32 v89, v89
	v_add_f32_e32 v90, 1.0, v90
	v_add_f32_e32 v91, 1.0, v91
	v_rcp_f32_e32 v90, v90
	v_rcp_f32_e32 v91, v91
	v_pk_mul_f32 v[82:83], v[86:87], v[82:83]
	v_pk_mul_f32 v[80:81], v[84:85], v[80:81]
	v_pk_mul_f32 v[80:81], v[80:81], v[88:89]
	v_pk_mul_f32 v[82:83], v[82:83], v[90:91]
	v_cvt_pk_bf16_f32 v80, v80, v81
; DI float ex2(float x) { return __builtin_amdgcn_exp2f(x); }
;     DI void operator()(const f32x4 (&acc)[2][2][4][2], const Unit& u, int wr, int wc, int fr, int fq) const {
;         const int row0 = u.pm * BM + wr * 64 + fr, hcol0 = ((u.pn * BM + wc * 32) >> 1) + 4 * fq;
; #pragma unroll
;         for (int ai = 0; ai < 2; ++ai)
; #pragma unroll
;             for (int m = 0; m < 4; ++m) { u16* rowp = O + (size_t)(row0 + ai * HALF + m * 16) * ldc + hcol0;
; #pragma unroll
;                 for (int bj = 0; bj < 2; ++bj) { const f32x4 g = acc[ai][bj][m][0], up = acc[ai][bj][m][1]; float r[4];
; #pragma unroll
;                     for (int j = 0; j < 4; ++j) r[j] = g[j] * up[j] * __builtin_amdgcn_rcpf(1.f + ex2(-LOG2E * g[j]));
;                     uint2 w = {pack2(r[0], r[1]), pack2(r[2], r[3])}; *(uint2*)(rowp + bj * (HALF / 2)) = w; } }
; template <class Epi, class Sched, bool STAMP = false>
; __device__ __forceinline__ void gemm_phase(PG8_LAS unsigned char* lds, const Gemm g, const Sched& S, const Epi& E, unsigned long long* stamps) {
;     ...
;         if (!has_next) break;
; #pragma unroll
;         for (int a = 0; a < 2; ++a)
; #pragma unroll
;             for (int b = 0; b < 2; ++b)
; #pragma unroll
;                 for (int m = 0; m < 4; ++m)
; #pragma unroll
;                     for (int n = 0; n < 2; ++n) acc[a][b][m][n] = (f32x4){0.f, 0.f, 0.f, 0.f};
;         cur = nxt; cA = nA; cB = nB; ++ui;
	v_cvt_pk_bf16_f32 v81, v82, v83
	v_exp_f32_e64 v82, -v76
	v_exp_f32_e64 v83, -v77
	v_exp_f32_e64 v84, -v78
	v_exp_f32_e64 v85, -v79
	v_add_f32_e32 v82, 1.0, v82
	v_add_f32_e32 v83, 1.0, v83
	v_add_f32_e32 v84, 1.0, v84
	v_add_f32_e32 v85, 1.0, v85
	v_rcp_f32_e32 v82, v82
	v_rcp_f32_e32 v83, v83
	v_rcp_f32_e32 v84, v84
	v_rcp_f32_e32 v85, v85
	v_pk_mul_f32 v[74:75], v[78:79], v[74:75]
	v_pk_mul_f32 v[72:73], v[76:77], v[72:73]
	global_store_dwordx2 v[96:97], v[80:81], off offset:128
	v_pk_mul_f32 v[72:73], v[72:73], v[82:83]
	v_pk_mul_f32 v[74:75], v[74:75], v[84:85]
	v_cvt_pk_bf16_f32 v72, v72, v73
	v_cvt_pk_bf16_f32 v73, v74, v75
	v_exp_f32_e64 v74, -v68
	v_exp_f32_e64 v75, -v69
	v_or_b32_e32 v80, 48, v170
	v_mad_i64_i32 v[80:81], s[34:35], v80, s69, v[142:143]
	v_lshl_add_u64 v[80:81], v[80:81], 0, v[140:141]
	global_store_dwordx2 v[80:81], v[72:73], off
	v_add_f32_e32 v72, 1.0, v74
	v_add_f32_e32 v73, 1.0, v75
	v_exp_f32_e64 v74, -v70
	v_exp_f32_e64 v75, -v71
	v_rcp_f32_e32 v72, v72
	v_rcp_f32_e32 v73, v73
	v_add_f32_e32 v74, 1.0, v74
	v_add_f32_e32 v75, 1.0, v75
	v_rcp_f32_e32 v74, v74
	v_rcp_f32_e32 v75, v75
	v_pk_mul_f32 v[66:67], v[70:71], v[66:67]
	v_pk_mul_f32 v[64:65], v[68:69], v[64:65]
	v_pk_mul_f32 v[64:65], v[64:65], v[72:73]
	v_pk_mul_f32 v[66:67], v[66:67], v[74:75]
	v_cvt_pk_bf16_f32 v64, v64, v65
	v_cvt_pk_bf16_f32 v65, v66, v67
	v_exp_f32_e64 v66, -v60
	v_exp_f32_e64 v67, -v61
	v_exp_f32_e64 v68, -v62
	v_exp_f32_e64 v69, -v63
	v_add_f32_e32 v66, 1.0, v66
	v_add_f32_e32 v67, 1.0, v67
	v_add_f32_e32 v68, 1.0, v68
	v_add_f32_e32 v69, 1.0, v69
	v_rcp_f32_e32 v66, v66
	v_rcp_f32_e32 v67, v67
	v_rcp_f32_e32 v68, v68
	v_rcp_f32_e32 v69, v69
	v_pk_mul_f32 v[58:59], v[62:63], v[58:59]
	v_pk_mul_f32 v[56:57], v[60:61], v[56:57]
	global_store_dwordx2 v[80:81], v[64:65], off offset:128
	v_pk_mul_f32 v[56:57], v[56:57], v[66:67]
	v_pk_mul_f32 v[58:59], v[58:59], v[68:69]
	v_cvt_pk_bf16_f32 v56, v56, v57
	v_cvt_pk_bf16_f32 v57, v58, v59
	v_exp_f32_e64 v58, -v52
	v_exp_f32_e64 v59, -v53
	v_add_u32_e32 v64, 0x80, v170
	v_mad_i64_i32 v[64:65], s[34:35], v64, s69, v[142:143]
	v_lshl_add_u64 v[64:65], v[64:65], 0, v[140:141]
	global_store_dwordx2 v[64:65], v[56:57], off
	v_add_f32_e32 v56, 1.0, v58
	v_add_f32_e32 v57, 1.0, v59
	v_exp_f32_e64 v58, -v54
	v_exp_f32_e64 v59, -v55
	v_rcp_f32_e32 v56, v56
	v_rcp_f32_e32 v57, v57
	v_add_f32_e32 v58, 1.0, v58
	v_add_f32_e32 v59, 1.0, v59
	v_rcp_f32_e32 v58, v58
	v_rcp_f32_e32 v59, v59
	v_pk_mul_f32 v[50:51], v[54:55], v[50:51]
	v_pk_mul_f32 v[48:49], v[52:53], v[48:49]
	v_pk_mul_f32 v[48:49], v[48:49], v[56:57]
	v_pk_mul_f32 v[50:51], v[50:51], v[58:59]
	v_cvt_pk_bf16_f32 v48, v48, v49
	v_cvt_pk_bf16_f32 v49, v50, v51
	v_exp_f32_e64 v50, -v44
	v_exp_f32_e64 v51, -v45
	v_exp_f32_e64 v52, -v46
	v_exp_f32_e64 v53, -v47
	v_add_f32_e32 v50, 1.0, v50
	v_add_f32_e32 v51, 1.0, v51
	v_add_f32_e32 v52, 1.0, v52
	v_add_f32_e32 v53, 1.0, v53
	v_rcp_f32_e32 v50, v50
	v_rcp_f32_e32 v51, v51
	v_rcp_f32_e32 v52, v52
	v_rcp_f32_e32 v53, v53
	v_pk_mul_f32 v[42:43], v[46:47], v[42:43]
	v_pk_mul_f32 v[40:41], v[44:45], v[40:41]
	global_store_dwordx2 v[64:65], v[48:49], off offset:128
	v_pk_mul_f32 v[40:41], v[40:41], v[50:51]
	v_pk_mul_f32 v[42:43], v[42:43], v[52:53]
	v_cvt_pk_bf16_f32 v40, v40, v41
	v_cvt_pk_bf16_f32 v41, v42, v43
	v_exp_f32_e64 v42, -v36
	v_exp_f32_e64 v43, -v37
	v_add_u32_e32 v48, 0x90, v170
	v_mad_i64_i32 v[48:49], s[34:35], v48, s69, v[142:143]
	v_lshl_add_u64 v[48:49], v[48:49], 0, v[140:141]
	global_store_dwordx2 v[48:49], v[40:41], off
	v_add_f32_e32 v40, 1.0, v42
	v_add_f32_e32 v41, 1.0, v43
	v_exp_f32_e64 v42, -v38
	v_exp_f32_e64 v43, -v39
	v_rcp_f32_e32 v40, v40
	v_rcp_f32_e32 v41, v41
	v_add_f32_e32 v42, 1.0, v42
	v_add_f32_e32 v43, 1.0, v43
	v_rcp_f32_e32 v42, v42
	v_rcp_f32_e32 v43, v43
	v_pk_mul_f32 v[34:35], v[38:39], v[34:35]
	v_pk_mul_f32 v[32:33], v[36:37], v[32:33]
	v_pk_mul_f32 v[32:33], v[32:33], v[40:41]
	v_pk_mul_f32 v[34:35], v[34:35], v[42:43]
	v_cvt_pk_bf16_f32 v32, v32, v33
	v_cvt_pk_bf16_f32 v33, v34, v35
	v_exp_f32_e64 v34, -v28
	v_exp_f32_e64 v35, -v29
	v_exp_f32_e64 v36, -v30
	v_exp_f32_e64 v37, -v31
	v_add_f32_e32 v34, 1.0, v34
	v_add_f32_e32 v35, 1.0, v35
	v_add_f32_e32 v36, 1.0, v36
	v_add_f32_e32 v37, 1.0, v37
	v_rcp_f32_e32 v34, v34
	v_rcp_f32_e32 v35, v35
	v_rcp_f32_e32 v36, v36
	v_rcp_f32_e32 v37, v37
	v_pk_mul_f32 v[26:27], v[30:31], v[26:27]
	v_pk_mul_f32 v[24:25], v[28:29], v[24:25]
	global_store_dwordx2 v[48:49], v[32:33], off offset:128
	v_pk_mul_f32 v[24:25], v[24:25], v[34:35]
	v_pk_mul_f32 v[26:27], v[26:27], v[36:37]
	v_cvt_pk_bf16_f32 v24, v24, v25
	v_cvt_pk_bf16_f32 v25, v26, v27
	v_exp_f32_e64 v26, -v20
	v_exp_f32_e64 v27, -v21
	v_add_u32_e32 v32, 0xa0, v170
	v_mad_i64_i32 v[32:33], s[34:35], v32, s69, v[142:143]
	v_lshl_add_u64 v[32:33], v[32:33], 0, v[140:141]
	global_store_dwordx2 v[32:33], v[24:25], off
	v_add_f32_e32 v24, 1.0, v26
	v_add_f32_e32 v25, 1.0, v27
	v_exp_f32_e64 v26, -v22
	v_exp_f32_e64 v27, -v23
	v_rcp_f32_e32 v24, v24
	v_rcp_f32_e32 v25, v25
	v_add_f32_e32 v26, 1.0, v26
	v_add_f32_e32 v27, 1.0, v27
	v_rcp_f32_e32 v26, v26
	v_rcp_f32_e32 v27, v27
	v_pk_mul_f32 v[18:19], v[22:23], v[18:19]
	v_pk_mul_f32 v[16:17], v[20:21], v[16:17]
	v_pk_mul_f32 v[16:17], v[16:17], v[24:25]
	v_pk_mul_f32 v[18:19], v[18:19], v[26:27]
	v_cvt_pk_bf16_f32 v16, v16, v17
	v_cvt_pk_bf16_f32 v17, v18, v19
	v_exp_f32_e64 v18, -v12
	v_exp_f32_e64 v19, -v13
	v_exp_f32_e64 v20, -v14
	v_exp_f32_e64 v21, -v15
	v_add_f32_e32 v18, 1.0, v18
	v_add_f32_e32 v19, 1.0, v19
	v_add_f32_e32 v20, 1.0, v20
	v_add_f32_e32 v21, 1.0, v21
	v_rcp_f32_e32 v18, v18
	v_rcp_f32_e32 v19, v19
	v_rcp_f32_e32 v20, v20
	v_rcp_f32_e32 v21, v21
	v_pk_mul_f32 v[10:11], v[14:15], v[10:11]
	v_pk_mul_f32 v[8:9], v[12:13], v[8:9]
	global_store_dwordx2 v[32:33], v[16:17], off offset:128
	v_pk_mul_f32 v[8:9], v[8:9], v[18:19]
	v_pk_mul_f32 v[10:11], v[10:11], v[20:21]
	v_cvt_pk_bf16_f32 v8, v8, v9
	v_cvt_pk_bf16_f32 v9, v10, v11
	v_exp_f32_e64 v10, -v4
	v_exp_f32_e64 v11, -v5
	v_add_u32_e32 v16, 0xb0, v170
	v_mad_i64_i32 v[16:17], s[34:35], v16, s69, v[142:143]
	v_lshl_add_u64 v[16:17], v[16:17], 0, v[140:141]
	global_store_dwordx2 v[16:17], v[8:9], off
	v_add_f32_e32 v8, 1.0, v10
	v_add_f32_e32 v9, 1.0, v11
	v_exp_f32_e64 v10, -v6
	v_exp_f32_e64 v11, -v7
	v_rcp_f32_e32 v8, v8
	v_rcp_f32_e32 v9, v9
	v_add_f32_e32 v10, 1.0, v10
	v_add_f32_e32 v11, 1.0, v11
	v_rcp_f32_e32 v10, v10
	v_rcp_f32_e32 v11, v11
	v_pk_mul_f32 v[2:3], v[6:7], v[2:3]
	v_pk_mul_f32 v[0:1], v[4:5], v[0:1]
	s_and_b64 vcc, exec, s[2:3]
	v_pk_mul_f32 v[0:1], v[0:1], v[8:9]
	v_pk_mul_f32 v[2:3], v[2:3], v[10:11]
	v_cvt_pk_bf16_f32 v0, v0, v1
	v_cvt_pk_bf16_f32 v1, v2, v3
	s_mov_b32 s76, s70
	s_mov_b32 s75, s71
	s_mov_b64 s[36:37], s[0:1]
	s_mov_b64 s[34:35], s[4:5]
	global_store_dwordx2 v[16:17], v[0:1], off offset:128
	s_cbranch_vccz .LBB0_432
	s_branch .Lgu3_done

; #define PG8_STAGE(bufoff, gbase, voff) do { _Pragma("unroll") for (int _i = 0; _i < 2; ++_i) \
;         __builtin_amdgcn_global_load_lds((const unsigned*)((const char*)(gbase) + (voff)[_i]), (PG8_LAS unsigned*)(lds + (bufoff) + ldsw + _i * 8192), 16, 0, 0); } while (0)
; #define PG8_LDA(dst, b, h) do { _Pragma("unroll") for (int m = 0; m < 4; ++m) _Pragma("unroll") for (int k = 0; k < 2; ++k) dst[m][k] = *(const PG8_LAS bf16x8*)(lds + PG8_SA(b, h) + aoff + m * 2048 + k * 1024); } while (0)
; #define PG8_WAIT_V(n) asm volatile("s_waitcnt vmcnt(" #n ")" ::: "memory")
; #define PG8_WAIT_L(n) asm volatile("s_waitcnt lgkmcnt(" #n ")" ::: "memory")
; template <class Epi, class Sched, bool STAMP = false>
; __device__ __forceinline__ void gemm_phase(PG8_LAS unsigned char* lds, const Gemm g, const Sched& S, const Epi& E, unsigned long long* stamps) {
;     ...
;         for (int t = 0; t < nt; t += 2) {
;             const bool last = (t == nt - 2);
;             const char* a1 = cA + (size_t)(t + 1) * kstep;
;             const char* a2 = last ? nA : cA + (size_t)(t + 2) * kstep; const char* b2 = last ? nB : cB + (size_t)(t + 2) * kstep;
;             const char* a3 = a2 + kstep; const char* b3 = b2 + kstep;
;             if (last && has_next) S.a_ready(nxt);
;             PG8_LDB(B0, 0, 0); PG8_SCHED; PG8_LDA(At, 0, 0); PG8_STAGE(PG8_SA(1, 1), a1 + hstep, voffA);
;             PG8_WAIT_L(8); PG8_BAR; PG8_WAIT_L(0); PG8_MMA(0, 0, At, B0); PG8_BAR; PG8_SCHED;
;             PG8_LDB(B1, 0, 1); PG8_STAGE(PG8_SB(0, 0), b2, voffB);
;             PG8_BAR; PG8_WAIT_L(0); PG8_MMA(0, 1, At, B1); PG8_BAR;
;             PG8_LDA(At, 0, 1); PG8_STAGE(PG8_SA(0, 0), a2, voffA);
;             PG8_BAR; PG8_WAIT_L(0); PG8_MMA(1, 0, At, B0); PG8_BAR; PG8_SCHED;
;             PG8_STAGE(PG8_SB(0, 1), b2 + hstep, voffB);
;             PG8_WAIT_V(6); PG8_BAR; PG8_MMA(1, 1, At, B1); PG8_BAR;
;             PG8_LDB(B0, 1, 0); PG8_SCHED; PG8_LDA(At, 1, 0); PG8_STAGE(PG8_SA(0, 1), a2 + hstep, voffA);
;             PG8_WAIT_L(8); PG8_BAR; PG8_WAIT_L(0); PG8_MMA(0, 0, At, B0); PG8_BAR; PG8_SCHED;
;             PG8_LDB(B1, 1, 1); PG8_STAGE(PG8_SB(1, 0), b3, voffB);
;             PG8_BAR; PG8_WAIT_L(0); PG8_MMA(0, 1, At, B1); PG8_BAR;
;             PG8_LDA(At, 1, 1); PG8_STAGE(PG8_SA(1, 0), a3, voffA);
;             PG8_BAR; PG8_WAIT_L(0); PG8_MMA(1, 0, At, B0); PG8_BAR; PG8_SCHED;
.Lgu3_half_loop:
	ds_read_b128 v[140:143], v147
	ds_read_b128 v[170:173], v148
	ds_read_b128 v[174:177], v149
	ds_read_b128 v[178:181], v150
	s_add_u32 s36, s34, 0x100
	s_addc_u32 s37, s35, 0
	s_cmp_eq_u32 s10, 12
	s_cselect_b32 s43, s5, s37
	s_cselect_b32 s42, s4, s36
	s_cselect_b32 s41, s1, s78
	s_cselect_b32 s40, s0, s77
	s_mov_b32 m0, s67
	ds_read_b128 v[182:185], v145
	ds_read_b128 v[186:189], v145 offset:1024
	ds_read_b128 v[190:193], v145 offset:2048
	ds_read_b128 v[194:197], v145 offset:3072
	ds_read_b128 v[198:201], v145 offset:4096
	ds_read_b128 v[202:205], v145 offset:5120
	ds_read_b128 v[206:209], v145 offset:6144
	ds_read_b128 v[210:213], v145 offset:7168
	global_load_lds_dwordx4 v132, s[34:35]
	s_mov_b32 m0, s68
	s_nop 0
	global_load_lds_dwordx4 v134, s[34:35]
	s_waitcnt lgkmcnt(8)
	s_barrier
	s_waitcnt lgkmcnt(0)
	s_setprio 1
	s_waitcnt lgkmcnt(0)
	v_mfma_f32_16x16x32_bf16 v[124:127], v[140:143], v[182:185], v[124:127]
	v_mfma_f32_16x16x32_bf16 v[120:123], v[174:177], v[182:185], v[120:123]
	v_mfma_f32_16x16x32_bf16 v[108:111], v[140:143], v[190:193], v[108:111]
	v_mfma_f32_16x16x32_bf16 v[104:107], v[174:177], v[190:193], v[104:107]
	v_mfma_f32_16x16x32_bf16 v[92:95], v[140:143], v[198:201], v[92:95]
	v_mfma_f32_16x16x32_bf16 v[88:91], v[174:177], v[198:201], v[88:91]
	v_mfma_f32_16x16x32_bf16 v[76:79], v[140:143], v[206:209], v[76:79]
	v_mfma_f32_16x16x32_bf16 v[72:75], v[174:177], v[206:209], v[72:75]
	v_mfma_f32_16x16x32_bf16 v[124:127], v[170:173], v[186:189], v[124:127]
	v_mfma_f32_16x16x32_bf16 v[120:123], v[178:181], v[186:189], v[120:123]
	v_mfma_f32_16x16x32_bf16 v[108:111], v[170:173], v[194:197], v[108:111]
	v_mfma_f32_16x16x32_bf16 v[104:107], v[178:181], v[194:197], v[104:107]
	v_mfma_f32_16x16x32_bf16 v[92:95], v[170:173], v[202:205], v[92:95]
	v_mfma_f32_16x16x32_bf16 v[88:91], v[178:181], v[202:205], v[88:91]
	v_mfma_f32_16x16x32_bf16 v[76:79], v[170:173], v[210:213], v[76:79]
	v_mfma_f32_16x16x32_bf16 v[72:75], v[178:181], v[210:213], v[72:75]
	s_setprio 0
	s_barrier
	s_mov_b32 m0, s49
	s_nop 0
	global_load_lds_dwordx4 v130, s[40:41]
	s_mov_b32 m0, s52
	s_nop 0
	global_load_lds_dwordx4 v128, s[40:41]
	s_barrier
	s_waitcnt lgkmcnt(0)
	s_setprio 1
	s_waitcnt lgkmcnt(0)
	s_setprio 0
	s_mov_b32 m0, s46
	s_barrier
	ds_read_b128 v[182:185], v145 offset:16384
	ds_read_b128 v[186:189], v145 offset:17408
	ds_read_b128 v[190:193], v145 offset:18432
	ds_read_b128 v[194:197], v145 offset:19456
	ds_read_b128 v[198:201], v145 offset:20480
	ds_read_b128 v[202:205], v145 offset:21504
	ds_read_b128 v[206:209], v145 offset:22528
	ds_read_b128 v[210:213], v145 offset:23552
	global_load_lds_dwordx4 v130, s[42:43]
	s_mov_b32 m0, s53
	s_nop 0
	global_load_lds_dwordx4 v128, s[42:43]
	s_barrier
	s_waitcnt lgkmcnt(0)
	s_setprio 1
	s_waitcnt lgkmcnt(0)
	v_mfma_f32_16x16x32_bf16 v[60:63], v[140:143], v[182:185], v[60:63]
	v_mfma_f32_16x16x32_bf16 v[56:59], v[174:177], v[182:185], v[56:59]
	v_mfma_f32_16x16x32_bf16 v[44:47], v[140:143], v[190:193], v[44:47]
	v_mfma_f32_16x16x32_bf16 v[40:43], v[174:177], v[190:193], v[40:43]
	v_mfma_f32_16x16x32_bf16 v[28:31], v[140:143], v[198:201], v[28:31]
	v_mfma_f32_16x16x32_bf16 v[24:27], v[174:177], v[198:201], v[24:27]
	v_mfma_f32_16x16x32_bf16 v[12:15], v[140:143], v[206:209], v[12:15]
	v_mfma_f32_16x16x32_bf16 v[8:11], v[174:177], v[206:209], v[8:11]
	v_mfma_f32_16x16x32_bf16 v[60:63], v[170:173], v[186:189], v[60:63]
	v_mfma_f32_16x16x32_bf16 v[56:59], v[178:181], v[186:189], v[56:59]
	v_mfma_f32_16x16x32_bf16 v[44:47], v[170:173], v[194:197], v[44:47]
	v_mfma_f32_16x16x32_bf16 v[40:43], v[178:181], v[194:197], v[40:43]
	v_mfma_f32_16x16x32_bf16 v[28:31], v[170:173], v[202:205], v[28:31]
	v_mfma_f32_16x16x32_bf16 v[24:27], v[178:181], v[202:205], v[24:27]
	v_mfma_f32_16x16x32_bf16 v[12:15], v[170:173], v[210:213], v[12:15]
	v_mfma_f32_16x16x32_bf16 v[8:11], v[178:181], v[210:213], v[8:11]
	s_setprio 0
	s_barrier
	s_add_u32 s34, s40, 0x44000
	s_addc_u32 s35, s41, 0
	s_mov_b32 m0, s54
	s_nop 0
	global_load_lds_dwordx4 v130, s[34:35]
	s_mov_b32 m0, s55
	s_nop 0
	global_load_lds_dwordx4 v128, s[34:35]
	s_waitcnt vmcnt(6)
	s_barrier
	s_setprio 1
	s_setprio 0
	s_barrier
	ds_read_b128 v[140:143], v155
	ds_read_b128 v[170:173], v156
	ds_read_b128 v[174:177], v157
	ds_read_b128 v[178:181], v165
	s_add_u32 s34, s42, 0x44000
	s_addc_u32 s35, s43, 0
	s_mov_b32 m0, s56
	ds_read_b128 v[182:185], v145 offset:32768
	ds_read_b128 v[186:189], v145 offset:33792
	ds_read_b128 v[190:193], v145 offset:34816
	ds_read_b128 v[194:197], v145 offset:35840
	ds_read_b128 v[198:201], v145 offset:36864
	ds_read_b128 v[202:205], v145 offset:37888
	ds_read_b128 v[206:209], v145 offset:38912
	ds_read_b128 v[210:213], v145 offset:39936
	global_load_lds_dwordx4 v130, s[34:35]
	s_mov_b32 m0, s57
	s_nop 0
	global_load_lds_dwordx4 v128, s[34:35]
	s_waitcnt lgkmcnt(8)
	s_barrier
	s_waitcnt lgkmcnt(0)
	s_setprio 1
	s_waitcnt lgkmcnt(0)
	v_mfma_f32_16x16x32_bf16 v[124:127], v[140:143], v[182:185], v[124:127]
	v_mfma_f32_16x16x32_bf16 v[120:123], v[174:177], v[182:185], v[120:123]
	v_mfma_f32_16x16x32_bf16 v[108:111], v[140:143], v[190:193], v[108:111]
	v_mfma_f32_16x16x32_bf16 v[104:107], v[174:177], v[190:193], v[104:107]
	v_mfma_f32_16x16x32_bf16 v[92:95], v[140:143], v[198:201], v[92:95]
	v_mfma_f32_16x16x32_bf16 v[88:91], v[174:177], v[198:201], v[88:91]
	v_mfma_f32_16x16x32_bf16 v[76:79], v[140:143], v[206:209], v[76:79]
	v_mfma_f32_16x16x32_bf16 v[72:75], v[174:177], v[206:209], v[72:75]
	v_mfma_f32_16x16x32_bf16 v[124:127], v[170:173], v[186:189], v[124:127]
	v_mfma_f32_16x16x32_bf16 v[120:123], v[178:181], v[186:189], v[120:123]
	v_mfma_f32_16x16x32_bf16 v[108:111], v[170:173], v[194:197], v[108:111]
	v_mfma_f32_16x16x32_bf16 v[104:107], v[178:181], v[194:197], v[104:107]
	v_mfma_f32_16x16x32_bf16 v[92:95], v[170:173], v[202:205], v[92:95]
	v_mfma_f32_16x16x32_bf16 v[88:91], v[178:181], v[202:205], v[88:91]
	v_mfma_f32_16x16x32_bf16 v[76:79], v[170:173], v[210:213], v[76:79]
	v_mfma_f32_16x16x32_bf16 v[72:75], v[178:181], v[210:213], v[72:75]
	s_setprio 0
	s_barrier
; #define PG8_STAGE(bufoff, gbase, voff) do { _Pragma("unroll") for (int _i = 0; _i < 2; ++_i) \
;         __builtin_amdgcn_global_load_lds((const unsigned*)((const char*)(gbase) + (voff)[_i]), (PG8_LAS unsigned*)(lds + (bufoff) + ldsw + _i * 8192), 16, 0, 0); } while (0)
; #define PG8_LDA(dst, b, h) do { _Pragma("unroll") for (int m = 0; m < 4; ++m) _Pragma("unroll") for (int k = 0; k < 2; ++k) dst[m][k] = *(const PG8_LAS bf16x8*)(lds + PG8_SA(b, h) + aoff + m * 2048 + k * 1024); } while (0)
; #define PG8_LDB(dst, b, h) do { _Pragma("unroll") for (int n = 0; n < 2; ++n) _Pragma("unroll") for (int k = 0; k < 2; ++k) dst[n][k] = *(const PG8_LAS bf16x8*)(lds + PG8_SB(b, h) + boff + n * 2048 + k * 1024); } while (0)
; #define PG8_MMA(ai, bj, At, Bt) do { __builtin_amdgcn_s_setprio(1); _Pragma("unroll") for (int m = 0; m < 4; ++m) _Pragma("unroll") for (int n = 0; n < 2; ++n) _Pragma("unroll") for (int k = 0; k < 2; ++k) \
;         acc[ai][bj][m][n] = __builtin_amdgcn_mfma_f32_16x16x32_bf16(Bt[n][k], At[m][k], acc[ai][bj][m][n], 0, 0, 0); __builtin_amdgcn_s_setprio(0); } while (0)
; #define PG8_WAIT_V(n) asm volatile("s_waitcnt vmcnt(" #n ")" ::: "memory")
; #define PG8_WAIT_L(n) asm volatile("s_waitcnt lgkmcnt(" #n ")" ::: "memory")
; #define PG8_BAR __builtin_amdgcn_s_barrier()
; #define PG8_SCHED __builtin_amdgcn_sched_barrier(0)
; template <class Epi, class Sched, bool STAMP = false>
; __device__ __forceinline__ void gemm_phase(PG8_LAS unsigned char* lds, const Gemm g, const Sched& S, const Epi& E, unsigned long long* stamps) {
;     ...
;             PG8_LDB(B1, 1, 1); PG8_STAGE(PG8_SB(1, 0), b3, voffB);
;             PG8_BAR; PG8_WAIT_L(0); PG8_MMA(0, 1, At, B1); PG8_BAR;
;             PG8_LDA(At, 1, 1); PG8_STAGE(PG8_SA(1, 0), a3, voffA);
;             PG8_BAR; PG8_WAIT_L(0); PG8_MMA(1, 0, At, B0); PG8_BAR; PG8_SCHED;
;             PG8_STAGE(PG8_SB(1, 1), b3 + hstep, voffB);
;             PG8_WAIT_V(6); PG8_BAR; PG8_MMA(1, 1, At, B1); PG8_BAR;
;         }
	s_mov_b32 m0, s60
	s_add_u32 s100, s40, 0x80
	s_addc_u32 s101, s41, 0
	global_load_lds_dwordx4 v130, s[100:101]
	s_mov_b32 m0, s61
	s_nop 0
	global_load_lds_dwordx4 v128, s[100:101]
	s_barrier
	s_waitcnt lgkmcnt(0)
	s_setprio 1
	s_waitcnt lgkmcnt(0)
	s_setprio 0
	s_mov_b32 m0, s62
	s_barrier
	ds_read_b128 v[182:185], v145 offset:49152
	ds_read_b128 v[186:189], v145 offset:50176
	ds_read_b128 v[190:193], v145 offset:51200
	ds_read_b128 v[194:197], v145 offset:52224
	ds_read_b128 v[198:201], v145 offset:53248
	ds_read_b128 v[202:205], v145 offset:54272
	ds_read_b128 v[206:209], v145 offset:55296
	ds_read_b128 v[210:213], v145 offset:56320
	s_add_u32 s100, s42, 0x80
	s_addc_u32 s101, s43, 0
	global_load_lds_dwordx4 v130, s[100:101]
	s_mov_b32 m0, s63
	s_nop 0
	global_load_lds_dwordx4 v128, s[100:101]
	s_barrier
	s_waitcnt lgkmcnt(0)
	s_setprio 1
	s_waitcnt lgkmcnt(0)
	v_mfma_f32_16x16x32_bf16 v[60:63], v[140:143], v[182:185], v[60:63]
	v_mfma_f32_16x16x32_bf16 v[56:59], v[174:177], v[182:185], v[56:59]
	v_mfma_f32_16x16x32_bf16 v[44:47], v[140:143], v[190:193], v[44:47]
	v_mfma_f32_16x16x32_bf16 v[40:43], v[174:177], v[190:193], v[40:43]
	v_mfma_f32_16x16x32_bf16 v[28:31], v[140:143], v[198:201], v[28:31]
	v_mfma_f32_16x16x32_bf16 v[24:27], v[174:177], v[198:201], v[24:27]
	v_mfma_f32_16x16x32_bf16 v[12:15], v[140:143], v[206:209], v[12:15]
	v_mfma_f32_16x16x32_bf16 v[8:11], v[174:177], v[206:209], v[8:11]
	v_mfma_f32_16x16x32_bf16 v[60:63], v[170:173], v[186:189], v[60:63]
	v_mfma_f32_16x16x32_bf16 v[56:59], v[178:181], v[186:189], v[56:59]
	v_mfma_f32_16x16x32_bf16 v[44:47], v[170:173], v[194:197], v[44:47]
	v_mfma_f32_16x16x32_bf16 v[40:43], v[178:181], v[194:197], v[40:43]
	v_mfma_f32_16x16x32_bf16 v[28:31], v[170:173], v[202:205], v[28:31]
	v_mfma_f32_16x16x32_bf16 v[24:27], v[178:181], v[202:205], v[24:27]
	v_mfma_f32_16x16x32_bf16 v[12:15], v[170:173], v[210:213], v[12:15]
	v_mfma_f32_16x16x32_bf16 v[8:11], v[178:181], v[210:213], v[8:11]
	s_setprio 0
	s_barrier
	s_add_u32 s34, s40, 0x44080
	s_addc_u32 s35, s41, 0
	s_mov_b32 m0, s64
	s_nop 0
	global_load_lds_dwordx4 v130, s[34:35]
	s_mov_b32 m0, s65
	s_nop 0
	global_load_lds_dwordx4 v128, s[34:35]
	s_waitcnt vmcnt(6)
	s_barrier
	s_setprio 1
	s_setprio 0
	s_add_i32 s10, s10, 2
	s_add_u32 s77, s77, 0x100
	s_addc_u32 s78, s78, 0
	s_cmp_gt_u32 s10, 13
	s_mov_b64 s[34:35], s[36:37]
	s_barrier
	s_cbranch_scc0 .Lgu3_half_loop
; DI float ex2(float x) { return __builtin_amdgcn_exp2f(x); }
;     DI void operator()(const f32x4 (&acc)[2][2][4][2], const Unit& u, int wr, int wc, int fr, int fq) const {
;         const int row0 = u.pm * BM + wr * 64 + fr, hcol0 = ((u.pn * BM + wc * 32) >> 1) + 4 * fq;
; #pragma unroll
;         for (int ai = 0; ai < 2; ++ai)
; #pragma unroll
;             for (int m = 0; m < 4; ++m) { u16* rowp = O + (size_t)(row0 + ai * HALF + m * 16) * ldc + hcol0;
; #pragma unroll
;                 for (int bj = 0; bj < 2; ++bj) { const f32x4 g = acc[ai][bj][m][0], up = acc[ai][bj][m][1]; float r[4];
; #pragma unroll
;                     for (int j = 0; j < 4; ++j) r[j] = g[j] * up[j] * __builtin_amdgcn_rcpf(1.f + ex2(-LOG2E * g[j]));
;                     uint2 w = {pack2(r[0], r[1]), pack2(r[2], r[3])}; *(uint2*)(rowp + bj * (HALF / 2)) = w; } }
	v_exp_f32_e64 v171, -v124
	v_exp_f32_e64 v175, -v125
	s_lshl_b32 s10, s76, 8
	v_add_f32_e32 v171, 1.0, v171
	v_rcp_f32_e32 v174, v171
	v_add_f32_e32 v171, 1.0, v175
	v_exp_f32_e64 v176, -v126
	v_exp_f32_e64 v177, -v127
	v_rcp_f32_e32 v175, v171
	v_add_f32_e32 v171, 1.0, v176
	v_rcp_f32_e32 v176, v171
	v_add_f32_e32 v171, 1.0, v177
	v_rcp_f32_e32 v177, v171
	v_pk_mul_f32 v[122:123], v[126:127], v[122:123]
	v_pk_mul_f32 v[120:121], v[124:125], v[120:121]
	s_or_b32 s10, s10, s59
	s_or_b32 s10, s10, s98
	v_pk_mul_f32 v[120:121], v[120:121], v[174:175]
	v_pk_mul_f32 v[122:123], v[122:123], v[176:177]
	s_ashr_i32 s10, s10, 1
	v_cvt_pk_bf16_f32 v120, v120, v121
	v_cvt_pk_bf16_f32 v121, v122, v123
	v_or_b32_e32 v140, s10, v146
	v_lshl_add_u32 v170, s75, 8, v144
	v_ashrrev_i32_e32 v141, 31, v140
	v_mov_b64_e32 v[142:143], s[12:13]
	v_mad_i64_i32 v[172:173], s[34:35], v170, s69, v[142:143]
	v_lshlrev_b64 v[140:141], 1, v[140:141]
	v_lshl_add_u64 v[172:173], v[172:173], 0, v[140:141]
	global_store_dwordx2 v[172:173], v[120:121], off
	v_exp_f32_e64 v114, -v108
	v_exp_f32_e64 v115, -v109
	v_exp_f32_e64 v116, -v110
	v_exp_f32_e64 v117, -v111
	v_add_f32_e32 v114, 1.0, v114
	v_add_f32_e32 v115, 1.0, v115
	v_add_f32_e32 v116, 1.0, v116
	v_add_f32_e32 v117, 1.0, v117
	v_rcp_f32_e32 v114, v114
	v_rcp_f32_e32 v115, v115
	v_rcp_f32_e32 v116, v116
	v_rcp_f32_e32 v117, v117
	v_pk_mul_f32 v[106:107], v[110:111], v[106:107]
	v_pk_mul_f32 v[104:105], v[108:109], v[104:105]
	v_pk_mul_f32 v[104:105], v[104:105], v[114:115]
	v_pk_mul_f32 v[106:107], v[106:107], v[116:117]
	v_cvt_pk_bf16_f32 v104, v104, v105
	v_cvt_pk_bf16_f32 v105, v106, v107
	v_or_b32_e32 v112, 16, v170
	v_mad_i64_i32 v[112:113], s[34:35], v112, s69, v[142:143]
	v_lshl_add_u64 v[112:113], v[112:113], 0, v[140:141]
	global_store_dwordx2 v[112:113], v[104:105], off
	v_exp_f32_e64 v98, -v92
	v_exp_f32_e64 v99, -v93
	v_exp_f32_e64 v100, -v94
	v_exp_f32_e64 v101, -v95
	v_add_f32_e32 v98, 1.0, v98
	v_add_f32_e32 v99, 1.0, v99
	v_add_f32_e32 v100, 1.0, v100
	v_add_f32_e32 v101, 1.0, v101
	v_rcp_f32_e32 v98, v98
	v_rcp_f32_e32 v99, v99
	v_rcp_f32_e32 v100, v100
	v_rcp_f32_e32 v101, v101
	v_pk_mul_f32 v[90:91], v[94:95], v[90:91]
	v_pk_mul_f32 v[88:89], v[92:93], v[88:89]
	v_pk_mul_f32 v[88:89], v[88:89], v[98:99]
	v_pk_mul_f32 v[90:91], v[90:91], v[100:101]
	v_cvt_pk_bf16_f32 v88, v88, v89
	v_cvt_pk_bf16_f32 v89, v90, v91
	v_or_b32_e32 v96, 32, v170
	v_mad_i64_i32 v[96:97], s[34:35], v96, s69, v[142:143]
	v_lshl_add_u64 v[96:97], v[96:97], 0, v[140:141]
	global_store_dwordx2 v[96:97], v[88:89], off
	v_exp_f32_e64 v82, -v76
	v_exp_f32_e64 v83, -v77
	v_exp_f32_e64 v84, -v78
	v_exp_f32_e64 v85, -v79
	v_add_f32_e32 v82, 1.0, v82
	v_add_f32_e32 v83, 1.0, v83
	v_add_f32_e32 v84, 1.0, v84
	v_add_f32_e32 v85, 1.0, v85
	v_rcp_f32_e32 v82, v82
	v_rcp_f32_e32 v83, v83
	v_rcp_f32_e32 v84, v84
	v_rcp_f32_e32 v85, v85
	v_pk_mul_f32 v[74:75], v[78:79], v[74:75]
	v_pk_mul_f32 v[72:73], v[76:77], v[72:73]
	v_pk_mul_f32 v[72:73], v[72:73], v[82:83]
	v_pk_mul_f32 v[74:75], v[74:75], v[84:85]
	v_cvt_pk_bf16_f32 v72, v72, v73
	v_cvt_pk_bf16_f32 v73, v74, v75
	v_or_b32_e32 v80, 48, v170
	v_mad_i64_i32 v[80:81], s[34:35], v80, s69, v[142:143]
	v_lshl_add_u64 v[80:81], v[80:81], 0, v[140:141]
	global_store_dwordx2 v[80:81], v[72:73], off
	v_exp_f32_e64 v66, -v60
	v_exp_f32_e64 v67, -v61
	v_exp_f32_e64 v68, -v62
	v_exp_f32_e64 v69, -v63
	v_add_f32_e32 v66, 1.0, v66
	v_add_f32_e32 v67, 1.0, v67
	v_add_f32_e32 v68, 1.0, v68
	v_add_f32_e32 v69, 1.0, v69
	v_rcp_f32_e32 v66, v66
	v_rcp_f32_e32 v67, v67
	v_rcp_f32_e32 v68, v68
	v_rcp_f32_e32 v69, v69
	v_pk_mul_f32 v[58:59], v[62:63], v[58:59]
	v_pk_mul_f32 v[56:57], v[60:61], v[56:57]
	v_pk_mul_f32 v[56:57], v[56:57], v[66:67]
	v_pk_mul_f32 v[58:59], v[58:59], v[68:69]
	v_cvt_pk_bf16_f32 v56, v56, v57
	v_cvt_pk_bf16_f32 v57, v58, v59
	v_add_u32_e32 v64, 0x80, v170
	v_mad_i64_i32 v[64:65], s[34:35], v64, s69, v[142:143]
	v_lshl_add_u64 v[64:65], v[64:65], 0, v[140:141]
	global_store_dwordx2 v[64:65], v[56:57], off
	v_exp_f32_e64 v50, -v44
	v_exp_f32_e64 v51, -v45
	v_exp_f32_e64 v52, -v46
	v_exp_f32_e64 v53, -v47
	v_add_f32_e32 v50, 1.0, v50
	v_add_f32_e32 v51, 1.0, v51
	v_add_f32_e32 v52, 1.0, v52
	v_add_f32_e32 v53, 1.0, v53
	v_rcp_f32_e32 v50, v50
	v_rcp_f32_e32 v51, v51
	v_rcp_f32_e32 v52, v52
	v_rcp_f32_e32 v53, v53
	v_pk_mul_f32 v[42:43], v[46:47], v[42:43]
	v_pk_mul_f32 v[40:41], v[44:45], v[40:41]
	v_pk_mul_f32 v[40:41], v[40:41], v[50:51]
	v_pk_mul_f32 v[42:43], v[42:43], v[52:53]
	v_cvt_pk_bf16_f32 v40, v40, v41
	v_cvt_pk_bf16_f32 v41, v42, v43
	v_add_u32_e32 v48, 0x90, v170
	v_mad_i64_i32 v[48:49], s[34:35], v48, s69, v[142:143]
	v_lshl_add_u64 v[48:49], v[48:49], 0, v[140:141]
	global_store_dwordx2 v[48:49], v[40:41], off
	v_exp_f32_e64 v34, -v28
	v_exp_f32_e64 v35, -v29
	v_exp_f32_e64 v36, -v30
	v_exp_f32_e64 v37, -v31
	v_add_f32_e32 v34, 1.0, v34
	v_add_f32_e32 v35, 1.0, v35
	v_add_f32_e32 v36, 1.0, v36
	v_add_f32_e32 v37, 1.0, v37
	v_rcp_f32_e32 v34, v34
	v_rcp_f32_e32 v35, v35
	v_rcp_f32_e32 v36, v36
	v_rcp_f32_e32 v37, v37
	v_pk_mul_f32 v[26:27], v[30:31], v[26:27]
	v_pk_mul_f32 v[24:25], v[28:29], v[24:25]
	v_pk_mul_f32 v[24:25], v[24:25], v[34:35]
	v_pk_mul_f32 v[26:27], v[26:27], v[36:37]
	v_cvt_pk_bf16_f32 v24, v24, v25
	v_cvt_pk_bf16_f32 v25, v26, v27
	v_add_u32_e32 v32, 0xa0, v170
	v_mad_i64_i32 v[32:33], s[34:35], v32, s69, v[142:143]
	v_lshl_add_u64 v[32:33], v[32:33], 0, v[140:141]
	global_store_dwordx2 v[32:33], v[24:25], off
	v_exp_f32_e64 v18, -v12
	v_exp_f32_e64 v19, -v13
	v_exp_f32_e64 v20, -v14
	v_exp_f32_e64 v21, -v15
	v_add_f32_e32 v18, 1.0, v18
	v_add_f32_e32 v19, 1.0, v19
	v_add_f32_e32 v20, 1.0, v20
	v_add_f32_e32 v21, 1.0, v21
	v_rcp_f32_e32 v18, v18
	v_rcp_f32_e32 v19, v19
	v_rcp_f32_e32 v20, v20
	v_rcp_f32_e32 v21, v21
	v_pk_mul_f32 v[10:11], v[14:15], v[10:11]
	v_pk_mul_f32 v[8:9], v[12:13], v[8:9]
	v_pk_mul_f32 v[8:9], v[8:9], v[18:19]
	v_pk_mul_f32 v[10:11], v[10:11], v[20:21]
	v_cvt_pk_bf16_f32 v8, v8, v9
	v_cvt_pk_bf16_f32 v9, v10, v11
	v_add_u32_e32 v16, 0xb0, v170
	v_mad_i64_i32 v[16:17], s[34:35], v16, s69, v[142:143]
	v_lshl_add_u64 v[16:17], v[16:17], 0, v[140:141]
	global_store_dwordx2 v[16:17], v[8:9], off
	s_and_b64 vcc, exec, s[2:3]
	s_mov_b32 s76, s70
	s_mov_b32 s75, s71
	s_mov_b64 s[36:37], s[0:1]
	s_mov_b64 s[34:35], s[4:5]

; DI unsigned bar_add(unsigned* p, unsigned v) { return __hip_atomic_fetch_add(p, v, __ATOMIC_RELAXED, __HIP_MEMORY_SCOPE_AGENT); }
; DI void grid_barrier(unsigned* bar, unsigned k, volatile unsigned* meta) {
;   asm volatile("s_waitcnt vmcnt(0)" ::: "memory");
;   __syncthreads();
;   if (threadIdx.x == 0) {
;     const unsigned nloc = meta[0], nx = meta[1], x = meta[2];
;     const unsigned old = bar_add(bar + 1024 + 64 * x, 1u);
;     if (old + 1u == k * nloc) {
;       __builtin_amdgcn_fence(__ATOMIC_RELEASE, "agent");
;       asm volatile("s_waitcnt vmcnt(0)" ::: "memory");
;       const unsigned old2 = bar_add(bar + 3072, 1u);
;       if (old2 + 1u == k * nx) {
;         for (int j = 0; j < 16; ++j) __hip_atomic_store(bar + 2048 + 64 * j, k, __ATOMIC_RELAXED, __HIP_MEMORY_SCOPE_AGENT);
.LBB0_444:
	s_waitcnt vmcnt(0)
	s_waitcnt vmcnt(0) lgkmcnt(0)
	s_barrier
	s_and_saveexec_b64 s[0:1], s[8:9]
	s_cbranch_execz .LBB0_454
	s_mov_b64 s[2:3], src_shared_base
	v_mov_b32_e32 v0, 0x24040
	ds_read_b32 v3, v0
	ds_read_b32 v2, v0 offset:4
	ds_read_b32 v0, v0 offset:8
	v_mov_b32_e32 v1, 0
	v_mov_b32_e32 v6, 1
	s_waitcnt lgkmcnt(0)
	v_mul_lo_u32 v3, v3, 13
	v_lshlrev_b32_e32 v0, 6, v0
	v_lshl_add_u64 v[0:1], v[0:1], 2, s[24:25]
	v_add_co_u32_e32 v4, vcc, 0xef01000, v0
	s_nop 1
	v_addc_co_u32_e32 v5, vcc, 0, v1, vcc
	global_atomic_add v4, v[4:5], v6, off offset:1024 sc0
	s_waitcnt vmcnt(0)
	v_add_u32_e32 v4, 1, v4
	v_cmp_eq_u32_e32 vcc, v4, v3
	s_and_saveexec_b64 s[2:3], vcc
	s_cbranch_execz .LBB0_450
	s_mov_b64 s[4:5], exec
	buffer_wbl2 sc1
	s_waitcnt vmcnt(0)
	v_mbcnt_lo_u32_b32 v3, s4, 0
	v_mbcnt_hi_u32_b32 v3, s5, v3
	v_cmp_eq_u32_e32 vcc, 0, v3
	s_and_saveexec_b64 s[6:7], vcc
	s_cbranch_execz .LBB0_448
	s_bcnt1_i32_b64 s4, s[4:5]
	v_mov_b32_e32 v4, 0xef03000
	v_mov_b32_e32 v5, s4
	global_atomic_add v4, v4, v5, s[24:25] offset:1024 sc0

; DI unsigned bar_add(unsigned* p, unsigned v) { return __hip_atomic_fetch_add(p, v, __ATOMIC_RELAXED, __HIP_MEMORY_SCOPE_AGENT); }
; DI void grid_barrier(unsigned* bar, unsigned k, volatile unsigned* meta) {
;   asm volatile("s_waitcnt vmcnt(0)" ::: "memory");
;   __syncthreads();
;   if (threadIdx.x == 0) {
;     const unsigned nloc = meta[0], nx = meta[1], x = meta[2];
;     const unsigned old = bar_add(bar + 1024 + 64 * x, 1u);
;     if (old + 1u == k * nloc) {
;       __builtin_amdgcn_fence(__ATOMIC_RELEASE, "agent");
;       asm volatile("s_waitcnt vmcnt(0)" ::: "memory");
;       const unsigned old2 = bar_add(bar + 3072, 1u);
;       if (old2 + 1u == k * nx) {
;         for (int j = 0; j < 16; ++j) __hip_atomic_store(bar + 2048 + 64 * j, k, __ATOMIC_RELAXED, __HIP_MEMORY_SCOPE_AGENT);
.LBB0_478:
	s_waitcnt vmcnt(0)
	s_waitcnt vmcnt(0) lgkmcnt(0)
	s_barrier
	s_and_saveexec_b64 s[0:1], s[8:9]
	s_cbranch_execz .LBB0_488
	s_mov_b64 s[2:3], src_shared_base
	v_mov_b32_e32 v0, 0x24040
	ds_read_b32 v3, v0
	ds_read_b32 v2, v0 offset:4
	ds_read_b32 v0, v0 offset:8
	v_mov_b32_e32 v1, 0
	v_mov_b32_e32 v6, 1
	s_waitcnt lgkmcnt(0)
	v_mul_lo_u32 v3, v3, 14
	v_lshlrev_b32_e32 v0, 6, v0
	v_lshl_add_u64 v[0:1], v[0:1], 2, s[24:25]
	v_add_co_u32_e32 v4, vcc, 0xef01000, v0
	s_nop 1
	v_addc_co_u32_e32 v5, vcc, 0, v1, vcc
	global_atomic_add v4, v[4:5], v6, off offset:1024 sc0
	s_waitcnt vmcnt(0)
	v_add_u32_e32 v4, 1, v4
	v_cmp_eq_u32_e32 vcc, v4, v3
	s_and_saveexec_b64 s[2:3], vcc
	s_cbranch_execz .LBB0_484
	s_mov_b64 s[4:5], exec
	buffer_wbl2 sc1
	s_waitcnt vmcnt(0)
	v_mbcnt_lo_u32_b32 v3, s4, 0
	v_mbcnt_hi_u32_b32 v3, s5, v3
	v_cmp_eq_u32_e32 vcc, 0, v3
	s_and_saveexec_b64 s[6:7], vcc
	s_cbranch_execz .LBB0_482
	s_bcnt1_i32_b64 s4, s[4:5]
	v_mov_b32_e32 v4, 0xef03000
	v_mov_b32_e32 v5, s4
	global_atomic_add v4, v4, v5, s[24:25] offset:1024 sc0

; DI unsigned bar_add(unsigned* p, unsigned v) { return __hip_atomic_fetch_add(p, v, __ATOMIC_RELAXED, __HIP_MEMORY_SCOPE_AGENT); }
; DI void grid_barrier(unsigned* bar, unsigned k, volatile unsigned* meta) {
;   asm volatile("s_waitcnt vmcnt(0)" ::: "memory");
;   __syncthreads();
;   if (threadIdx.x == 0) {
;     const unsigned nloc = meta[0], nx = meta[1], x = meta[2];
;     const unsigned old = bar_add(bar + 1024 + 64 * x, 1u);
;     if (old + 1u == k * nloc) {
;       __builtin_amdgcn_fence(__ATOMIC_RELEASE, "agent");
;       asm volatile("s_waitcnt vmcnt(0)" ::: "memory");
;       const unsigned old2 = bar_add(bar + 3072, 1u);
;       if (old2 + 1u == k * nx) {
;         for (int j = 0; j < 16; ++j) __hip_atomic_store(bar + 2048 + 64 * j, k, __ATOMIC_RELAXED, __HIP_MEMORY_SCOPE_AGENT);
.LBB0_491:
	s_or_b64 exec, exec, s[0:1]
	s_waitcnt vmcnt(0)
	s_barrier
	s_and_saveexec_b64 s[0:1], s[8:9]
	s_cbranch_execz .LBB0_501
	s_mov_b64 s[2:3], src_shared_base
	v_mov_b32_e32 v0, 0x24040
	ds_read_b32 v3, v0
	ds_read_b32 v2, v0 offset:4
	ds_read_b32 v0, v0 offset:8
	v_mov_b32_e32 v1, 0
	v_mov_b32_e32 v6, 1
	s_waitcnt lgkmcnt(0)
	v_mul_lo_u32 v3, v3, 15
	v_lshlrev_b32_e32 v0, 6, v0
	v_lshl_add_u64 v[0:1], v[0:1], 2, s[24:25]
	v_add_co_u32_e32 v4, vcc, 0xef01000, v0
	s_nop 1
	v_addc_co_u32_e32 v5, vcc, 0, v1, vcc
	global_atomic_add v4, v[4:5], v6, off offset:1024 sc0
	s_waitcnt vmcnt(0)
	v_add_u32_e32 v4, 1, v4
	v_cmp_eq_u32_e32 vcc, v4, v3
	s_and_saveexec_b64 s[2:3], vcc
	s_cbranch_execz .LBB0_497
	s_mov_b64 s[4:5], exec
	buffer_wbl2 sc1
	s_waitcnt vmcnt(0)
	v_mbcnt_lo_u32_b32 v3, s4, 0
	v_mbcnt_hi_u32_b32 v3, s5, v3
	v_cmp_eq_u32_e32 vcc, 0, v3
	s_and_saveexec_b64 s[6:7], vcc
	s_cbranch_execz .LBB0_495
	s_bcnt1_i32_b64 s4, s[4:5]
	v_mov_b32_e32 v4, 0xef03000
	v_mov_b32_e32 v5, s4
	global_atomic_add v4, v4, v5, s[24:25] offset:1024 sc0

; DI unsigned bar_add(unsigned* p, unsigned v) { return __hip_atomic_fetch_add(p, v, __ATOMIC_RELAXED, __HIP_MEMORY_SCOPE_AGENT); }
; DI void grid_barrier(unsigned* bar, unsigned k, volatile unsigned* meta) {
;   asm volatile("s_waitcnt vmcnt(0)" ::: "memory");
;   __syncthreads();
;   if (threadIdx.x == 0) {
;     const unsigned nloc = meta[0], nx = meta[1], x = meta[2];
;     const unsigned old = bar_add(bar + 1024 + 64 * x, 1u);
;     if (old + 1u == k * nloc) {
;       __builtin_amdgcn_fence(__ATOMIC_RELEASE, "agent");
;       asm volatile("s_waitcnt vmcnt(0)" ::: "memory");
;       const unsigned old2 = bar_add(bar + 3072, 1u);
;       if (old2 + 1u == k * nx) {
;         for (int j = 0; j < 16; ++j) __hip_atomic_store(bar + 2048 + 64 * j, k, __ATOMIC_RELAXED, __HIP_MEMORY_SCOPE_AGENT);
.LBB0_539:
	s_waitcnt vmcnt(0)
	s_waitcnt vmcnt(0) lgkmcnt(0)
	s_barrier
	s_and_saveexec_b64 s[0:1], s[8:9]
	s_cbranch_execz .LBB0_549
	s_mov_b64 s[2:3], src_shared_base
	v_mov_b32_e32 v0, 0x24040
	ds_read_b32 v3, v0
	ds_read_b32 v2, v0 offset:4
	ds_read_b32 v0, v0 offset:8
	v_mov_b32_e32 v1, 0
	v_mov_b32_e32 v6, 1
	s_waitcnt lgkmcnt(0)
	v_lshlrev_b32_e32 v3, 4, v3
	v_lshlrev_b32_e32 v0, 6, v0
	v_lshl_add_u64 v[0:1], v[0:1], 2, s[24:25]
	v_add_co_u32_e32 v4, vcc, 0xef01000, v0
	s_nop 1
	v_addc_co_u32_e32 v5, vcc, 0, v1, vcc
	global_atomic_add v4, v[4:5], v6, off offset:1024 sc0
	s_waitcnt vmcnt(0)
	v_add_u32_e32 v4, 1, v4
	v_cmp_eq_u32_e32 vcc, v4, v3
	s_and_saveexec_b64 s[2:3], vcc
	s_cbranch_execz .LBB0_545
	s_mov_b64 s[4:5], exec
	buffer_wbl2 sc1
	s_waitcnt vmcnt(0)
	v_mbcnt_lo_u32_b32 v3, s4, 0
	v_mbcnt_hi_u32_b32 v3, s5, v3
	v_cmp_eq_u32_e32 vcc, 0, v3
	s_and_saveexec_b64 s[6:7], vcc
	s_cbranch_execz .LBB0_543
	s_bcnt1_i32_b64 s4, s[4:5]
	v_mov_b32_e32 v4, 0xef03000
	v_mov_b32_e32 v5, s4
	global_atomic_add v4, v4, v5, s[24:25] offset:1024 sc0

; DI unsigned bar_add(unsigned* p, unsigned v) { return __hip_atomic_fetch_add(p, v, __ATOMIC_RELAXED, __HIP_MEMORY_SCOPE_AGENT); }
; DI void grid_barrier(unsigned* bar, unsigned k, volatile unsigned* meta) {
;   asm volatile("s_waitcnt vmcnt(0)" ::: "memory");
;   __syncthreads();
;   if (threadIdx.x == 0) {
;     const unsigned nloc = meta[0], nx = meta[1], x = meta[2];
;     const unsigned old = bar_add(bar + 1024 + 64 * x, 1u);
;     if (old + 1u == k * nloc) {
;       __builtin_amdgcn_fence(__ATOMIC_RELEASE, "agent");
;       asm volatile("s_waitcnt vmcnt(0)" ::: "memory");
;       const unsigned old2 = bar_add(bar + 3072, 1u);
;       if (old2 + 1u == k * nx) {
;         for (int j = 0; j < 16; ++j) __hip_atomic_store(bar + 2048 + 64 * j, k, __ATOMIC_RELAXED, __HIP_MEMORY_SCOPE_AGENT);
.LBB0_641:
	s_or_b64 exec, exec, s[6:7]
	s_waitcnt vmcnt(0)
	s_waitcnt lgkmcnt(0)
	s_barrier
	s_and_saveexec_b64 s[0:1], s[8:9]
	s_cbranch_execz .LBB0_651
	s_mov_b64 s[2:3], src_shared_base
	v_mov_b32_e32 v0, 0x24040
	ds_read_b32 v3, v0
	ds_read_b32 v2, v0 offset:4
	ds_read_b32 v0, v0 offset:8
	v_mov_b32_e32 v1, 0
	v_mov_b32_e32 v6, 1
	s_waitcnt lgkmcnt(0)
	v_lshl_add_u32 v3, v3, 4, v3
	v_lshlrev_b32_e32 v0, 6, v0
	v_lshl_add_u64 v[0:1], v[0:1], 2, s[24:25]
	v_add_co_u32_e32 v4, vcc, 0xef01000, v0
	s_nop 1
	v_addc_co_u32_e32 v5, vcc, 0, v1, vcc
	global_atomic_add v4, v[4:5], v6, off offset:1024 sc0
	s_waitcnt vmcnt(0)
	v_add_u32_e32 v4, 1, v4
	v_cmp_eq_u32_e32 vcc, v4, v3
	s_and_saveexec_b64 s[2:3], vcc
	s_cbranch_execz .LBB0_647
	s_mov_b64 s[4:5], exec
	buffer_wbl2 sc1
	s_waitcnt vmcnt(0)
	v_mbcnt_lo_u32_b32 v3, s4, 0
	v_mbcnt_hi_u32_b32 v3, s5, v3
	v_cmp_eq_u32_e32 vcc, 0, v3
	s_and_saveexec_b64 s[6:7], vcc
	s_cbranch_execz .LBB0_645
	s_bcnt1_i32_b64 s4, s[4:5]
	v_mov_b32_e32 v4, 0xef03000
	v_mov_b32_e32 v5, s4
	global_atomic_add v4, v4, v5, s[24:25] offset:1024 sc0

; DI unsigned bar_add(unsigned* p, unsigned v) { return __hip_atomic_fetch_add(p, v, __ATOMIC_RELAXED, __HIP_MEMORY_SCOPE_AGENT); }
; DI void grid_barrier(unsigned* bar, unsigned k, volatile unsigned* meta) {
;   asm volatile("s_waitcnt vmcnt(0)" ::: "memory");
;   __syncthreads();
;   if (threadIdx.x == 0) {
;     const unsigned nloc = meta[0], nx = meta[1], x = meta[2];
;     const unsigned old = bar_add(bar + 1024 + 64 * x, 1u);
;     if (old + 1u == k * nloc) {
;       __builtin_amdgcn_fence(__ATOMIC_RELEASE, "agent");
;       asm volatile("s_waitcnt vmcnt(0)" ::: "memory");
;       const unsigned old2 = bar_add(bar + 3072, 1u);
;       if (old2 + 1u == k * nx) {
;         for (int j = 0; j < 16; ++j) __hip_atomic_store(bar + 2048 + 64 * j, k, __ATOMIC_RELAXED, __HIP_MEMORY_SCOPE_AGENT);
.LBB0_659:
	s_or_b64 exec, exec, s[4:5]
	s_waitcnt vmcnt(0)
	s_waitcnt lgkmcnt(0)
	s_barrier
	s_and_saveexec_b64 s[0:1], s[8:9]
	s_cbranch_execz .LBB0_669
	s_mov_b64 s[2:3], src_shared_base
	s_waitcnt vmcnt(0)
	v_mov_b32_e32 v0, 0x24040
	ds_read_b32 v3, v0
	ds_read_b32 v2, v0 offset:4
	ds_read_b32 v0, v0 offset:8
	v_mov_b32_e32 v1, 0
	v_mov_b32_e32 v6, 1
	s_waitcnt lgkmcnt(0)
	v_mul_lo_u32 v3, v3, 18
	v_lshlrev_b32_e32 v0, 6, v0
	v_lshl_add_u64 v[0:1], v[0:1], 2, s[24:25]
	v_add_co_u32_e32 v4, vcc, 0xef01000, v0
	s_nop 1
	v_addc_co_u32_e32 v5, vcc, 0, v1, vcc
	global_atomic_add v4, v[4:5], v6, off offset:1024 sc0
	s_waitcnt vmcnt(0)
	v_add_u32_e32 v4, 1, v4
	v_cmp_eq_u32_e32 vcc, v4, v3
	s_and_saveexec_b64 s[2:3], vcc
	s_cbranch_execz .LBB0_665
	s_mov_b64 s[4:5], exec
	buffer_wbl2 sc1
	s_waitcnt vmcnt(0)
	v_mbcnt_lo_u32_b32 v3, s4, 0
	v_mbcnt_hi_u32_b32 v3, s5, v3
	v_cmp_eq_u32_e32 vcc, 0, v3
	s_and_saveexec_b64 s[6:7], vcc
	s_cbranch_execz .LBB0_663
	s_bcnt1_i32_b64 s4, s[4:5]
	v_mov_b32_e32 v4, 0xef03000
	v_mov_b32_e32 v5, s4
	global_atomic_add v4, v4, v5, s[24:25] offset:1024 sc0

; DI unsigned bar_add(unsigned* p, unsigned v) { return __hip_atomic_fetch_add(p, v, __ATOMIC_RELAXED, __HIP_MEMORY_SCOPE_AGENT); }
; DI void grid_barrier(unsigned* bar, unsigned k, volatile unsigned* meta) {
;   asm volatile("s_waitcnt vmcnt(0)" ::: "memory");
;   __syncthreads();
;   if (threadIdx.x == 0) {
;     const unsigned nloc = meta[0], nx = meta[1], x = meta[2];
;     const unsigned old = bar_add(bar + 1024 + 64 * x, 1u);
;     if (old + 1u == k * nloc) {
;       __builtin_amdgcn_fence(__ATOMIC_RELEASE, "agent");
;       asm volatile("s_waitcnt vmcnt(0)" ::: "memory");
;       const unsigned old2 = bar_add(bar + 3072, 1u);
;       if (old2 + 1u == k * nx) {
;         for (int j = 0; j < 16; ++j) __hip_atomic_store(bar + 2048 + 64 * j, k, __ATOMIC_RELAXED, __HIP_MEMORY_SCOPE_AGENT);
.LBB0_693:
	s_waitcnt vmcnt(0)
	s_waitcnt vmcnt(0) lgkmcnt(0)
	s_barrier
	s_and_saveexec_b64 s[0:1], s[8:9]
	s_cbranch_execz .LBB0_703
	s_mov_b64 s[2:3], src_shared_base
	v_mov_b32_e32 v0, 0x24040
	ds_read_b32 v3, v0
	ds_read_b32 v2, v0 offset:4
	ds_read_b32 v0, v0 offset:8
	v_mov_b32_e32 v1, 0
	v_mov_b32_e32 v6, 1
	s_waitcnt lgkmcnt(0)
	v_mul_lo_u32 v3, v3, 19
	v_lshlrev_b32_e32 v0, 6, v0
	v_lshl_add_u64 v[0:1], v[0:1], 2, s[24:25]
	v_add_co_u32_e32 v4, vcc, 0xef01000, v0
	s_nop 1
	v_addc_co_u32_e32 v5, vcc, 0, v1, vcc
	global_atomic_add v4, v[4:5], v6, off offset:1024 sc0
	s_waitcnt vmcnt(0)
	v_add_u32_e32 v4, 1, v4
	v_cmp_eq_u32_e32 vcc, v4, v3
	s_and_saveexec_b64 s[2:3], vcc
	s_cbranch_execz .LBB0_699
	s_mov_b64 s[4:5], exec
	buffer_wbl2 sc1
	s_waitcnt vmcnt(0)
	v_mbcnt_lo_u32_b32 v3, s4, 0
	v_mbcnt_hi_u32_b32 v3, s5, v3
	v_cmp_eq_u32_e32 vcc, 0, v3
	s_and_saveexec_b64 s[6:7], vcc
	s_cbranch_execz .LBB0_697
	s_bcnt1_i32_b64 s4, s[4:5]
	v_mov_b32_e32 v4, 0xef03000
	v_mov_b32_e32 v5, s4
	global_atomic_add v4, v4, v5, s[24:25] offset:1024 sc0

; DI unsigned bar_add(unsigned* p, unsigned v) { return __hip_atomic_fetch_add(p, v, __ATOMIC_RELAXED, __HIP_MEMORY_SCOPE_AGENT); }
; DI void grid_barrier(unsigned* bar, unsigned k, volatile unsigned* meta) {
;   asm volatile("s_waitcnt vmcnt(0)" ::: "memory");
;   __syncthreads();
;   if (threadIdx.x == 0) {
;     const unsigned nloc = meta[0], nx = meta[1], x = meta[2];
;     const unsigned old = bar_add(bar + 1024 + 64 * x, 1u);
;     if (old + 1u == k * nloc) {
;       __builtin_amdgcn_fence(__ATOMIC_RELEASE, "agent");
;       asm volatile("s_waitcnt vmcnt(0)" ::: "memory");
;       const unsigned old2 = bar_add(bar + 3072, 1u);
;       if (old2 + 1u == k * nx) {
;         for (int j = 0; j < 16; ++j) __hip_atomic_store(bar + 2048 + 64 * j, k, __ATOMIC_RELAXED, __HIP_MEMORY_SCOPE_AGENT);
.LBB0_706:
	s_or_b64 exec, exec, s[0:1]
	s_waitcnt vmcnt(0)
	s_barrier
	s_and_saveexec_b64 s[0:1], s[8:9]
	s_cbranch_execz .LBB0_716
	s_mov_b64 s[2:3], src_shared_base
	v_mov_b32_e32 v0, 0x24040
	ds_read_b32 v3, v0
	ds_read_b32 v2, v0 offset:4
	ds_read_b32 v0, v0 offset:8
	v_mov_b32_e32 v1, 0
	v_mov_b32_e32 v6, 1
	s_waitcnt lgkmcnt(0)
	v_mul_lo_u32 v3, v3, 20
	v_lshlrev_b32_e32 v0, 6, v0
	v_lshl_add_u64 v[0:1], v[0:1], 2, s[24:25]
	v_add_co_u32_e32 v4, vcc, 0xef01000, v0
	s_nop 1
	v_addc_co_u32_e32 v5, vcc, 0, v1, vcc
	global_atomic_add v4, v[4:5], v6, off offset:1024 sc0
	s_waitcnt vmcnt(0)
	v_add_u32_e32 v4, 1, v4
	v_cmp_eq_u32_e32 vcc, v4, v3
	s_and_saveexec_b64 s[2:3], vcc
	s_cbranch_execz .LBB0_712
	s_mov_b64 s[4:5], exec
	buffer_wbl2 sc1
	s_waitcnt vmcnt(0)
	v_mbcnt_lo_u32_b32 v3, s4, 0
	v_mbcnt_hi_u32_b32 v3, s5, v3
	v_cmp_eq_u32_e32 vcc, 0, v3
	s_and_saveexec_b64 s[6:7], vcc
	s_cbranch_execz .LBB0_710
	s_bcnt1_i32_b64 s4, s[4:5]
	v_mov_b32_e32 v4, 0xef03000
	v_mov_b32_e32 v5, s4
	global_atomic_add v4, v4, v5, s[24:25] offset:1024 sc0

; #define PG8_STAGE(bufoff, gbase, voff) do { _Pragma("unroll") for (int _i = 0; _i < 2; ++_i) \
;         __builtin_amdgcn_global_load_lds((const unsigned*)((const char*)(gbase) + (voff)[_i]), (PG8_LAS unsigned*)(lds + (bufoff) + ldsw + _i * 8192), 16, 0, 0); } while (0)
; #define PG8_LDA(dst, b, h) do { _Pragma("unroll") for (int m = 0; m < 4; ++m) _Pragma("unroll") for (int k = 0; k < 2; ++k) dst[m][k] = *(const PG8_LAS bf16x8*)(lds + PG8_SA(b, h) + aoff + m * 2048 + k * 1024); } while (0)
; #define PG8_LDB(dst, b, h) do { _Pragma("unroll") for (int n = 0; n < 2; ++n) _Pragma("unroll") for (int k = 0; k < 2; ++k) dst[n][k] = *(const PG8_LAS bf16x8*)(lds + PG8_SB(b, h) + boff + n * 2048 + k * 1024); } while (0)
; #define PG8_MMA(ai, bj, At, Bt) do { __builtin_amdgcn_s_setprio(1); _Pragma("unroll") for (int m = 0; m < 4; ++m) _Pragma("unroll") for (int n = 0; n < 2; ++n) _Pragma("unroll") for (int k = 0; k < 2; ++k) \
;         acc[ai][bj][m][n] = __builtin_amdgcn_mfma_f32_16x16x32_bf16(Bt[n][k], At[m][k], acc[ai][bj][m][n], 0, 0, 0); __builtin_amdgcn_s_setprio(0); } while (0)
; #define PG8_WAIT_V(n) asm volatile("s_waitcnt vmcnt(" #n ")" ::: "memory")
; #define PG8_WAIT_L(n) asm volatile("s_waitcnt lgkmcnt(" #n ")" ::: "memory")
; #define PG8_BAR __builtin_amdgcn_s_barrier()
; #define PG8_SCHED __builtin_amdgcn_sched_barrier(0)
; template <class Epi, class Sched, bool STAMP = false>
; __device__ __forceinline__ void gemm_phase(PG8_LAS unsigned char* lds, const Gemm g, const Sched& S, const Epi& E, unsigned long long* stamps) {
;     ...
;             PG8_LDB(B0, 1, 0); PG8_SCHED; PG8_LDA(At, 1, 0); PG8_STAGE(PG8_SA(0, 1), a2 + hstep, voffA);
;             PG8_WAIT_L(8); PG8_BAR; PG8_WAIT_L(0); PG8_MMA(0, 0, At, B0); PG8_BAR; PG8_SCHED;
;             PG8_LDB(B1, 1, 1); PG8_STAGE(PG8_SB(1, 0), b3, voffB);
;             PG8_BAR; PG8_WAIT_L(0); PG8_MMA(0, 1, At, B1); PG8_BAR;
;             PG8_LDA(At, 1, 1); PG8_STAGE(PG8_SA(1, 0), a3, voffA);
;             PG8_BAR; PG8_WAIT_L(0); PG8_MMA(1, 0, At, B0); PG8_BAR; PG8_SCHED;
;             PG8_STAGE(PG8_SB(1, 1), b3 + hstep, voffB);
;             PG8_WAIT_V(6); PG8_BAR; PG8_MMA(1, 1, At, B1); PG8_BAR;
.Lzp11_mid:
	ds_read_b128 v[140:143], v155
	ds_read_b128 v[170:173], v156
	ds_read_b128 v[174:177], v157
	ds_read_b128 v[178:181], v165
	s_add_u32 s16, s28, 0x44000
	s_addc_u32 s17, s29, 0
	s_mov_b32 m0, s44
	ds_read_b128 v[182:185], v145 offset:32768
	ds_read_b128 v[186:189], v145 offset:33792
	ds_read_b128 v[190:193], v145 offset:34816
	ds_read_b128 v[194:197], v145 offset:35840
	ds_read_b128 v[198:201], v145 offset:36864
	ds_read_b128 v[202:205], v145 offset:37888
	ds_read_b128 v[206:209], v145 offset:38912
	ds_read_b128 v[210:213], v145 offset:39936
	global_load_lds_dwordx4 v130, s[16:17]
	s_mov_b32 m0, s45
	s_nop 0
	global_load_lds_dwordx4 v128, s[16:17]
	s_waitcnt lgkmcnt(8)
	s_barrier
	s_waitcnt lgkmcnt(0)
	s_setprio 1
	s_waitcnt lgkmcnt(0)
	v_mfma_f32_16x16x32_bf16 v[124:127], v[140:143], v[182:185], v[124:127]
	v_mfma_f32_16x16x32_bf16 v[120:123], v[174:177], v[182:185], v[120:123]
	v_mfma_f32_16x16x32_bf16 v[108:111], v[140:143], v[190:193], v[108:111]
	v_mfma_f32_16x16x32_bf16 v[104:107], v[174:177], v[190:193], v[104:107]
	v_mfma_f32_16x16x32_bf16 v[92:95], v[140:143], v[198:201], v[92:95]
	v_mfma_f32_16x16x32_bf16 v[88:91], v[174:177], v[198:201], v[88:91]
	v_mfma_f32_16x16x32_bf16 v[76:79], v[140:143], v[206:209], v[76:79]
	v_mfma_f32_16x16x32_bf16 v[72:75], v[174:177], v[206:209], v[72:75]
	v_mfma_f32_16x16x32_bf16 v[124:127], v[170:173], v[186:189], v[124:127]
	v_mfma_f32_16x16x32_bf16 v[120:123], v[178:181], v[186:189], v[120:123]
	v_mfma_f32_16x16x32_bf16 v[108:111], v[170:173], v[194:197], v[108:111]
	v_mfma_f32_16x16x32_bf16 v[104:107], v[178:181], v[194:197], v[104:107]
	v_mfma_f32_16x16x32_bf16 v[92:95], v[170:173], v[202:205], v[92:95]
	v_mfma_f32_16x16x32_bf16 v[88:91], v[178:181], v[202:205], v[88:91]
	v_mfma_f32_16x16x32_bf16 v[76:79], v[170:173], v[210:213], v[76:79]
	v_mfma_f32_16x16x32_bf16 v[72:75], v[178:181], v[210:213], v[72:75]
	s_setprio 0
	s_barrier
	s_mov_b32 m0, s48
	ds_read_b128 v[214:217], v166
	ds_read_b128 v[218:221], v167
	ds_read_b128 v[222:225], v168
	ds_read_b128 v[226:229], v169
	s_add_u32 s100, s20, 0x80
	s_addc_u32 s101, s21, 0
	global_load_lds_dwordx4 v130, s[100:101]
	s_mov_b32 m0, s49
	s_nop 0
	global_load_lds_dwordx4 v128, s[100:101]
	s_barrier
	s_waitcnt lgkmcnt(0)
	s_setprio 1
	s_waitcnt lgkmcnt(0)
	v_mfma_f32_16x16x32_bf16 v[116:119], v[214:217], v[182:185], v[116:119]
	v_mfma_f32_16x16x32_bf16 v[112:115], v[222:225], v[182:185], v[112:115]
	v_mfma_f32_16x16x32_bf16 v[100:103], v[214:217], v[190:193], v[100:103]
	v_mfma_f32_16x16x32_bf16 v[96:99], v[222:225], v[190:193], v[96:99]
	v_mfma_f32_16x16x32_bf16 v[84:87], v[214:217], v[198:201], v[84:87]
	v_mfma_f32_16x16x32_bf16 v[80:83], v[222:225], v[198:201], v[80:83]
	v_mfma_f32_16x16x32_bf16 v[68:71], v[214:217], v[206:209], v[68:71]
	v_mfma_f32_16x16x32_bf16 v[64:67], v[222:225], v[206:209], v[64:67]
	v_mfma_f32_16x16x32_bf16 v[116:119], v[218:221], v[186:189], v[116:119]
	v_mfma_f32_16x16x32_bf16 v[112:115], v[226:229], v[186:189], v[112:115]
	v_mfma_f32_16x16x32_bf16 v[100:103], v[218:221], v[194:197], v[100:103]
	v_mfma_f32_16x16x32_bf16 v[96:99], v[226:229], v[194:197], v[96:99]
	v_mfma_f32_16x16x32_bf16 v[84:87], v[218:221], v[202:205], v[84:87]
	v_mfma_f32_16x16x32_bf16 v[80:83], v[226:229], v[202:205], v[80:83]
	v_mfma_f32_16x16x32_bf16 v[68:71], v[218:221], v[210:213], v[68:71]
	v_mfma_f32_16x16x32_bf16 v[64:67], v[226:229], v[210:213], v[64:67]
	s_setprio 0
	s_mov_b32 m0, s50
	s_barrier
	ds_read_b128 v[182:185], v145 offset:49152
	ds_read_b128 v[186:189], v145 offset:50176
	ds_read_b128 v[190:193], v145 offset:51200
	ds_read_b128 v[194:197], v145 offset:52224
	ds_read_b128 v[198:201], v145 offset:53248
	ds_read_b128 v[202:205], v145 offset:54272
	ds_read_b128 v[206:209], v145 offset:55296
	ds_read_b128 v[210:213], v145 offset:56320
	s_add_u32 s100, s28, 0x80
	s_addc_u32 s101, s29, 0
	global_load_lds_dwordx4 v130, s[100:101]
	s_mov_b32 m0, s51
	s_nop 0
	global_load_lds_dwordx4 v128, s[100:101]
	s_barrier
	s_waitcnt lgkmcnt(0)
	s_setprio 1
	s_waitcnt lgkmcnt(0)
	v_mfma_f32_16x16x32_bf16 v[60:63], v[140:143], v[182:185], v[60:63]
	v_mfma_f32_16x16x32_bf16 v[56:59], v[174:177], v[182:185], v[56:59]
	v_mfma_f32_16x16x32_bf16 v[44:47], v[140:143], v[190:193], v[44:47]
	v_mfma_f32_16x16x32_bf16 v[40:43], v[174:177], v[190:193], v[40:43]
	v_mfma_f32_16x16x32_bf16 v[28:31], v[140:143], v[198:201], v[28:31]
	v_mfma_f32_16x16x32_bf16 v[24:27], v[174:177], v[198:201], v[24:27]
	v_mfma_f32_16x16x32_bf16 v[12:15], v[140:143], v[206:209], v[12:15]
	v_mfma_f32_16x16x32_bf16 v[8:11], v[174:177], v[206:209], v[8:11]
	v_mfma_f32_16x16x32_bf16 v[60:63], v[170:173], v[186:189], v[60:63]
	v_mfma_f32_16x16x32_bf16 v[56:59], v[178:181], v[186:189], v[56:59]
	v_mfma_f32_16x16x32_bf16 v[44:47], v[170:173], v[194:197], v[44:47]
	v_mfma_f32_16x16x32_bf16 v[40:43], v[178:181], v[194:197], v[40:43]
	v_mfma_f32_16x16x32_bf16 v[28:31], v[170:173], v[202:205], v[28:31]
	v_mfma_f32_16x16x32_bf16 v[24:27], v[178:181], v[202:205], v[24:27]
	v_mfma_f32_16x16x32_bf16 v[12:15], v[170:173], v[210:213], v[12:15]
	v_mfma_f32_16x16x32_bf16 v[8:11], v[178:181], v[210:213], v[8:11]
	s_setprio 0
	s_barrier
	s_add_u32 s16, s20, 0x44080
	s_addc_u32 s17, s21, 0
	s_mov_b32 m0, s52
	s_nop 0
	global_load_lds_dwordx4 v130, s[16:17]
	s_mov_b32 m0, s53
	s_nop 0
	global_load_lds_dwordx4 v128, s[16:17]
	s_waitcnt vmcnt(6)
	s_barrier
; DI float ex2(float x) { return __builtin_amdgcn_exp2f(x); }
; #define PG8_STAMP() do { if (STAMP && wid == 0 && nts < 64) { const unsigned long long _c = 0ull; \
;         ts_lo = (lane == nts) ? (int)(unsigned)_c : ts_lo; ts_hi = (lane == nts) ? (int)(unsigned)(_c >> 32) : ts_hi; ++nts; } } while (0)
; #define PG8_STAGE(bufoff, gbase, voff) do { _Pragma("unroll") for (int _i = 0; _i < 2; ++_i) \
;         __builtin_amdgcn_global_load_lds((const unsigned*)((const char*)(gbase) + (voff)[_i]), (PG8_LAS unsigned*)(lds + (bufoff) + ldsw + _i * 8192), 16, 0, 0); } while (0)
;     DI void operator()(const f32x4 (&acc)[2][2][4][2], const Unit& u, int wr, int wc, int fr, int fq) const {
;         const int row0 = u.pm * BM + wr * 64 + fr, hcol0 = ((u.pn * BM + wc * 32) >> 1) + 4 * fq;
; #pragma unroll
;         for (int ai = 0; ai < 2; ++ai)
; #pragma unroll
;             for (int m = 0; m < 4; ++m) { u16* rowp = O + (size_t)(row0 + ai * HALF + m * 16) * ldc + hcol0;
; #pragma unroll
;                 for (int bj = 0; bj < 2; ++bj) { const f32x4 g = acc[ai][bj][m][0], up = acc[ai][bj][m][1]; float r[4];
; #pragma unroll
;                     for (int j = 0; j < 4; ++j) r[j] = g[j] * up[j] * __builtin_amdgcn_rcpf(1.f + ex2(-LOG2E * g[j]));
;                     uint2 w = {pack2(r[0], r[1]), pack2(r[2], r[3])}; *(uint2*)(rowp + bj * (HALF / 2)) = w; } }
; template <class Epi, class Sched, bool STAMP = false>
; __device__ __forceinline__ void gemm_phase(PG8_LAS unsigned char* lds, const Gemm g, const Sched& S, const Epi& E, unsigned long long* stamps) {
;     ...
;             PG8_WAIT_V(6); PG8_BAR; PG8_MMA(1, 1, At, B1); PG8_BAR;
;             PG8_LDB(B0, 1, 0); PG8_SCHED; PG8_LDA(At, 1, 0); PG8_STAGE(PG8_SA(0, 1), a2 + hstep, voffA);
;             PG8_WAIT_L(8); PG8_BAR; PG8_WAIT_L(0); PG8_MMA(0, 0, At, B0); PG8_BAR; PG8_SCHED;
;             PG8_LDB(B1, 1, 1); PG8_STAGE(PG8_SB(1, 0), b3, voffB);
;             PG8_BAR; PG8_WAIT_L(0); PG8_MMA(0, 1, At, B1); PG8_BAR;
;             PG8_LDA(At, 1, 1); PG8_STAGE(PG8_SA(1, 0), a3, voffA);
;             PG8_BAR; PG8_WAIT_L(0); PG8_MMA(1, 0, At, B0); PG8_BAR; PG8_SCHED;
;             PG8_STAGE(PG8_SB(1, 1), b3 + hstep, voffB);
;             PG8_WAIT_V(6); PG8_BAR; PG8_MMA(1, 1, At, B1); PG8_BAR;
;         }
;         PG8_STAMP();
;         if constexpr (!Epi::AFTER_DRAIN) { E(acc, cur, wr, wc, fr, fq); S.done(cur); }
	s_setprio 1
	v_mfma_f32_16x16x32_bf16 v[52:55], v[214:217], v[182:185], v[52:55]
	v_mfma_f32_16x16x32_bf16 v[48:51], v[222:225], v[182:185], v[48:51]
	v_mfma_f32_16x16x32_bf16 v[36:39], v[214:217], v[190:193], v[36:39]
	v_mfma_f32_16x16x32_bf16 v[32:35], v[222:225], v[190:193], v[32:35]
	v_mfma_f32_16x16x32_bf16 v[20:23], v[214:217], v[198:201], v[20:23]
	v_mfma_f32_16x16x32_bf16 v[16:19], v[222:225], v[198:201], v[16:19]
	v_mfma_f32_16x16x32_bf16 v[4:7], v[214:217], v[206:209], v[4:7]
	v_mfma_f32_16x16x32_bf16 v[0:3], v[222:225], v[206:209], v[0:3]
	v_mfma_f32_16x16x32_bf16 v[52:55], v[218:221], v[186:189], v[52:55]
	v_mfma_f32_16x16x32_bf16 v[48:51], v[226:229], v[186:189], v[48:51]
	v_mfma_f32_16x16x32_bf16 v[36:39], v[218:221], v[194:197], v[36:39]
	v_mfma_f32_16x16x32_bf16 v[32:35], v[226:229], v[194:197], v[32:35]
	v_mfma_f32_16x16x32_bf16 v[20:23], v[218:221], v[202:205], v[20:23]
	v_mfma_f32_16x16x32_bf16 v[16:19], v[226:229], v[202:205], v[16:19]
	v_mfma_f32_16x16x32_bf16 v[4:7], v[218:221], v[210:213], v[4:7]
	v_mfma_f32_16x16x32_bf16 v[0:3], v[226:229], v[210:213], v[0:3]
	s_setprio 0
	s_add_i32 s10, s10, 2
	s_add_u32 s62, s62, 0x100
	s_addc_u32 s63, s63, 0
	s_cmp_gt_u32 s10, 13
	s_mov_b64 s[16:17], s[18:19]
	s_barrier
	s_cbranch_scc0 .LBB0_727
	v_exp_f32_e64 v171, -v124
	v_exp_f32_e64 v175, -v125
	s_lshl_b32 s10, s61, 8
	v_add_f32_e32 v171, 1.0, v171
	v_rcp_f32_e32 v174, v171
	v_add_f32_e32 v171, 1.0, v175
	v_exp_f32_e64 v176, -v126
	v_exp_f32_e64 v177, -v127
	v_rcp_f32_e32 v175, v171
	v_add_f32_e32 v171, 1.0, v176
	v_rcp_f32_e32 v176, v171
	v_add_f32_e32 v171, 1.0, v177
	v_rcp_f32_e32 v177, v171
	v_pk_mul_f32 v[122:123], v[126:127], v[122:123]
	v_pk_mul_f32 v[120:121], v[124:125], v[120:121]
	s_or_b32 s10, s10, s47
	v_pk_mul_f32 v[120:121], v[120:121], v[174:175]
	v_pk_mul_f32 v[122:123], v[122:123], v[176:177]
	s_ashr_i32 s10, s10, 1
	v_cvt_pk_bf16_f32 v120, v120, v121
	v_cvt_pk_bf16_f32 v121, v122, v123
	v_or_b32_e32 v140, s10, v146
	v_exp_f32_e64 v122, -v116
	v_exp_f32_e64 v123, -v117
	v_lshl_add_u32 v170, s60, 8, v144
	v_ashrrev_i32_e32 v141, 31, v140
	v_mov_b64_e32 v[142:143], s[12:13]
	v_mad_i64_i32 v[172:173], s[16:17], v170, s57, v[142:143]
	v_lshlrev_b64 v[140:141], 1, v[140:141]
	v_lshl_add_u64 v[172:173], v[172:173], 0, v[140:141]
	global_store_dwordx2 v[172:173], v[120:121], off
	v_add_f32_e32 v120, 1.0, v122
	v_add_f32_e32 v121, 1.0, v123
	v_exp_f32_e64 v122, -v118
	v_exp_f32_e64 v123, -v119
	v_rcp_f32_e32 v120, v120
	v_rcp_f32_e32 v121, v121
	v_add_f32_e32 v122, 1.0, v122
	v_add_f32_e32 v123, 1.0, v123
	v_rcp_f32_e32 v122, v122
	v_rcp_f32_e32 v123, v123
	v_pk_mul_f32 v[114:115], v[118:119], v[114:115]
	v_pk_mul_f32 v[112:113], v[116:117], v[112:113]
	v_pk_mul_f32 v[112:113], v[112:113], v[120:121]
	v_pk_mul_f32 v[114:115], v[114:115], v[122:123]
	v_cvt_pk_bf16_f32 v112, v112, v113
	v_cvt_pk_bf16_f32 v113, v114, v115
	v_exp_f32_e64 v114, -v108
	v_exp_f32_e64 v115, -v109
	v_exp_f32_e64 v116, -v110
	v_exp_f32_e64 v117, -v111
	v_add_f32_e32 v114, 1.0, v114
	v_add_f32_e32 v115, 1.0, v115
	v_add_f32_e32 v116, 1.0, v116
	v_add_f32_e32 v117, 1.0, v117
	v_rcp_f32_e32 v114, v114
	v_rcp_f32_e32 v115, v115
	v_rcp_f32_e32 v116, v116
	v_rcp_f32_e32 v117, v117
	v_pk_mul_f32 v[106:107], v[110:111], v[106:107]
	v_pk_mul_f32 v[104:105], v[108:109], v[104:105]
	global_store_dwordx2 v[172:173], v[112:113], off offset:128
	v_pk_mul_f32 v[104:105], v[104:105], v[114:115]
	v_pk_mul_f32 v[106:107], v[106:107], v[116:117]
	v_cvt_pk_bf16_f32 v104, v104, v105
	v_cvt_pk_bf16_f32 v105, v106, v107
	v_exp_f32_e64 v106, -v100
	v_exp_f32_e64 v107, -v101
	v_or_b32_e32 v112, 16, v170
	v_mad_i64_i32 v[112:113], s[16:17], v112, s57, v[142:143]
	v_lshl_add_u64 v[112:113], v[112:113], 0, v[140:141]
	global_store_dwordx2 v[112:113], v[104:105], off
	v_add_f32_e32 v104, 1.0, v106
	v_add_f32_e32 v105, 1.0, v107
	v_exp_f32_e64 v106, -v102
	v_exp_f32_e64 v107, -v103
	v_rcp_f32_e32 v104, v104
	v_rcp_f32_e32 v105, v105
	v_add_f32_e32 v106, 1.0, v106
	v_add_f32_e32 v107, 1.0, v107
	v_rcp_f32_e32 v106, v106
	v_rcp_f32_e32 v107, v107
	v_pk_mul_f32 v[98:99], v[102:103], v[98:99]
	v_pk_mul_f32 v[96:97], v[100:101], v[96:97]
	v_pk_mul_f32 v[96:97], v[96:97], v[104:105]
	v_pk_mul_f32 v[98:99], v[98:99], v[106:107]
	v_cvt_pk_bf16_f32 v96, v96, v97
	v_cvt_pk_bf16_f32 v97, v98, v99
	v_exp_f32_e64 v98, -v92
	v_exp_f32_e64 v99, -v93
	v_exp_f32_e64 v100, -v94
	v_exp_f32_e64 v101, -v95
	v_add_f32_e32 v98, 1.0, v98
	v_add_f32_e32 v99, 1.0, v99
	v_add_f32_e32 v100, 1.0, v100
	v_add_f32_e32 v101, 1.0, v101
	v_rcp_f32_e32 v98, v98
	v_rcp_f32_e32 v99, v99
	v_rcp_f32_e32 v100, v100
	v_rcp_f32_e32 v101, v101
	v_pk_mul_f32 v[90:91], v[94:95], v[90:91]
	v_pk_mul_f32 v[88:89], v[92:93], v[88:89]
	global_store_dwordx2 v[112:113], v[96:97], off offset:128
	v_pk_mul_f32 v[88:89], v[88:89], v[98:99]
	v_pk_mul_f32 v[90:91], v[90:91], v[100:101]
	v_cvt_pk_bf16_f32 v88, v88, v89
	v_cvt_pk_bf16_f32 v89, v90, v91
	v_exp_f32_e64 v90, -v84
	v_exp_f32_e64 v91, -v85
	v_or_b32_e32 v96, 32, v170
	v_mad_i64_i32 v[96:97], s[16:17], v96, s57, v[142:143]
	v_lshl_add_u64 v[96:97], v[96:97], 0, v[140:141]
	global_store_dwordx2 v[96:97], v[88:89], off
	v_add_f32_e32 v88, 1.0, v90
	v_add_f32_e32 v89, 1.0, v91
	v_exp_f32_e64 v90, -v86
	v_exp_f32_e64 v91, -v87
	v_rcp_f32_e32 v88, v88
	v_rcp_f32_e32 v89, v89
	v_add_f32_e32 v90, 1.0, v90
	v_add_f32_e32 v91, 1.0, v91
	v_rcp_f32_e32 v90, v90
	v_rcp_f32_e32 v91, v91
	v_pk_mul_f32 v[82:83], v[86:87], v[82:83]
	v_pk_mul_f32 v[80:81], v[84:85], v[80:81]
	v_pk_mul_f32 v[80:81], v[80:81], v[88:89]
	v_pk_mul_f32 v[82:83], v[82:83], v[90:91]
	v_cvt_pk_bf16_f32 v80, v80, v81
; DI float ex2(float x) { return __builtin_amdgcn_exp2f(x); }
;     DI void operator()(const f32x4 (&acc)[2][2][4][2], const Unit& u, int wr, int wc, int fr, int fq) const {
;         const int row0 = u.pm * BM + wr * 64 + fr, hcol0 = ((u.pn * BM + wc * 32) >> 1) + 4 * fq;
; #pragma unroll
;         for (int ai = 0; ai < 2; ++ai)
; #pragma unroll
;             for (int m = 0; m < 4; ++m) { u16* rowp = O + (size_t)(row0 + ai * HALF + m * 16) * ldc + hcol0;
; #pragma unroll
;                 for (int bj = 0; bj < 2; ++bj) { const f32x4 g = acc[ai][bj][m][0], up = acc[ai][bj][m][1]; float r[4];
; #pragma unroll
;                     for (int j = 0; j < 4; ++j) r[j] = g[j] * up[j] * __builtin_amdgcn_rcpf(1.f + ex2(-LOG2E * g[j]));
;                     uint2 w = {pack2(r[0], r[1]), pack2(r[2], r[3])}; *(uint2*)(rowp + bj * (HALF / 2)) = w; } }
; template <class Epi, class Sched, bool STAMP = false>
; __device__ __forceinline__ void gemm_phase(PG8_LAS unsigned char* lds, const Gemm g, const Sched& S, const Epi& E, unsigned long long* stamps) {
;     ...
;         if (!has_next) break;
; #pragma unroll
;         for (int a = 0; a < 2; ++a)
; #pragma unroll
;             for (int b = 0; b < 2; ++b)
; #pragma unroll
;                 for (int m = 0; m < 4; ++m)
; #pragma unroll
;                     for (int n = 0; n < 2; ++n) acc[a][b][m][n] = (f32x4){0.f, 0.f, 0.f, 0.f};
;         cur = nxt; cA = nA; cB = nB; ++ui;
	v_cvt_pk_bf16_f32 v81, v82, v83
	v_exp_f32_e64 v82, -v76
	v_exp_f32_e64 v83, -v77
	v_exp_f32_e64 v84, -v78
	v_exp_f32_e64 v85, -v79
	v_add_f32_e32 v82, 1.0, v82
	v_add_f32_e32 v83, 1.0, v83
	v_add_f32_e32 v84, 1.0, v84
	v_add_f32_e32 v85, 1.0, v85
	v_rcp_f32_e32 v82, v82
	v_rcp_f32_e32 v83, v83
	v_rcp_f32_e32 v84, v84
	v_rcp_f32_e32 v85, v85
	v_pk_mul_f32 v[74:75], v[78:79], v[74:75]
	v_pk_mul_f32 v[72:73], v[76:77], v[72:73]
	global_store_dwordx2 v[96:97], v[80:81], off offset:128
	v_pk_mul_f32 v[72:73], v[72:73], v[82:83]
	v_pk_mul_f32 v[74:75], v[74:75], v[84:85]
	v_cvt_pk_bf16_f32 v72, v72, v73
	v_cvt_pk_bf16_f32 v73, v74, v75
	v_exp_f32_e64 v74, -v68
	v_exp_f32_e64 v75, -v69
	v_or_b32_e32 v80, 48, v170
	v_mad_i64_i32 v[80:81], s[16:17], v80, s57, v[142:143]
	v_lshl_add_u64 v[80:81], v[80:81], 0, v[140:141]
	global_store_dwordx2 v[80:81], v[72:73], off
	v_add_f32_e32 v72, 1.0, v74
	v_add_f32_e32 v73, 1.0, v75
	v_exp_f32_e64 v74, -v70
	v_exp_f32_e64 v75, -v71
	v_rcp_f32_e32 v72, v72
	v_rcp_f32_e32 v73, v73
	v_add_f32_e32 v74, 1.0, v74
	v_add_f32_e32 v75, 1.0, v75
	v_rcp_f32_e32 v74, v74
	v_rcp_f32_e32 v75, v75
	v_pk_mul_f32 v[66:67], v[70:71], v[66:67]
	v_pk_mul_f32 v[64:65], v[68:69], v[64:65]
	v_pk_mul_f32 v[64:65], v[64:65], v[72:73]
	v_pk_mul_f32 v[66:67], v[66:67], v[74:75]
	v_cvt_pk_bf16_f32 v64, v64, v65
	v_cvt_pk_bf16_f32 v65, v66, v67
	v_exp_f32_e64 v66, -v60
	v_exp_f32_e64 v67, -v61
	v_exp_f32_e64 v68, -v62
	v_exp_f32_e64 v69, -v63
	v_add_f32_e32 v66, 1.0, v66
	v_add_f32_e32 v67, 1.0, v67
	v_add_f32_e32 v68, 1.0, v68
	v_add_f32_e32 v69, 1.0, v69
	v_rcp_f32_e32 v66, v66
	v_rcp_f32_e32 v67, v67
	v_rcp_f32_e32 v68, v68
	v_rcp_f32_e32 v69, v69
	v_pk_mul_f32 v[58:59], v[62:63], v[58:59]
	v_pk_mul_f32 v[56:57], v[60:61], v[56:57]
	global_store_dwordx2 v[80:81], v[64:65], off offset:128
	v_pk_mul_f32 v[56:57], v[56:57], v[66:67]
	v_pk_mul_f32 v[58:59], v[58:59], v[68:69]
	v_cvt_pk_bf16_f32 v56, v56, v57
	v_cvt_pk_bf16_f32 v57, v58, v59
	v_exp_f32_e64 v58, -v52
	v_exp_f32_e64 v59, -v53
	v_add_u32_e32 v64, 0x80, v170
	v_mad_i64_i32 v[64:65], s[16:17], v64, s57, v[142:143]
	v_lshl_add_u64 v[64:65], v[64:65], 0, v[140:141]
	global_store_dwordx2 v[64:65], v[56:57], off
	v_add_f32_e32 v56, 1.0, v58
	v_add_f32_e32 v57, 1.0, v59
	v_exp_f32_e64 v58, -v54
	v_exp_f32_e64 v59, -v55
	v_rcp_f32_e32 v56, v56
	v_rcp_f32_e32 v57, v57
	v_add_f32_e32 v58, 1.0, v58
	v_add_f32_e32 v59, 1.0, v59
	v_rcp_f32_e32 v58, v58
	v_rcp_f32_e32 v59, v59
	v_pk_mul_f32 v[50:51], v[54:55], v[50:51]
	v_pk_mul_f32 v[48:49], v[52:53], v[48:49]
	v_pk_mul_f32 v[48:49], v[48:49], v[56:57]
	v_pk_mul_f32 v[50:51], v[50:51], v[58:59]
	v_cvt_pk_bf16_f32 v48, v48, v49
	v_cvt_pk_bf16_f32 v49, v50, v51
	v_exp_f32_e64 v50, -v44
	v_exp_f32_e64 v51, -v45
	v_exp_f32_e64 v52, -v46
	v_exp_f32_e64 v53, -v47
	v_add_f32_e32 v50, 1.0, v50
	v_add_f32_e32 v51, 1.0, v51
	v_add_f32_e32 v52, 1.0, v52
	v_add_f32_e32 v53, 1.0, v53
	v_rcp_f32_e32 v50, v50
	v_rcp_f32_e32 v51, v51
	v_rcp_f32_e32 v52, v52
	v_rcp_f32_e32 v53, v53
	v_pk_mul_f32 v[42:43], v[46:47], v[42:43]
	v_pk_mul_f32 v[40:41], v[44:45], v[40:41]
	global_store_dwordx2 v[64:65], v[48:49], off offset:128
	v_pk_mul_f32 v[40:41], v[40:41], v[50:51]
	v_pk_mul_f32 v[42:43], v[42:43], v[52:53]
	v_cvt_pk_bf16_f32 v40, v40, v41
	v_cvt_pk_bf16_f32 v41, v42, v43
	v_exp_f32_e64 v42, -v36
	v_exp_f32_e64 v43, -v37
	v_add_u32_e32 v48, 0x90, v170
	v_mad_i64_i32 v[48:49], s[16:17], v48, s57, v[142:143]
	v_lshl_add_u64 v[48:49], v[48:49], 0, v[140:141]
	global_store_dwordx2 v[48:49], v[40:41], off
	v_add_f32_e32 v40, 1.0, v42
	v_add_f32_e32 v41, 1.0, v43
	v_exp_f32_e64 v42, -v38
	v_exp_f32_e64 v43, -v39
	v_rcp_f32_e32 v40, v40
	v_rcp_f32_e32 v41, v41
	v_add_f32_e32 v42, 1.0, v42
	v_add_f32_e32 v43, 1.0, v43
	v_rcp_f32_e32 v42, v42
	v_rcp_f32_e32 v43, v43
	v_pk_mul_f32 v[34:35], v[38:39], v[34:35]
	v_pk_mul_f32 v[32:33], v[36:37], v[32:33]
	v_pk_mul_f32 v[32:33], v[32:33], v[40:41]
	v_pk_mul_f32 v[34:35], v[34:35], v[42:43]
	v_cvt_pk_bf16_f32 v32, v32, v33
	v_cvt_pk_bf16_f32 v33, v34, v35
	v_exp_f32_e64 v34, -v28
	v_exp_f32_e64 v35, -v29
	v_exp_f32_e64 v36, -v30
	v_exp_f32_e64 v37, -v31
	v_add_f32_e32 v34, 1.0, v34
	v_add_f32_e32 v35, 1.0, v35
	v_add_f32_e32 v36, 1.0, v36
	v_add_f32_e32 v37, 1.0, v37
	v_rcp_f32_e32 v34, v34
	v_rcp_f32_e32 v35, v35
	v_rcp_f32_e32 v36, v36
	v_rcp_f32_e32 v37, v37
	v_pk_mul_f32 v[26:27], v[30:31], v[26:27]
	v_pk_mul_f32 v[24:25], v[28:29], v[24:25]
	global_store_dwordx2 v[48:49], v[32:33], off offset:128
	v_pk_mul_f32 v[24:25], v[24:25], v[34:35]
	v_pk_mul_f32 v[26:27], v[26:27], v[36:37]
	v_cvt_pk_bf16_f32 v24, v24, v25
	v_cvt_pk_bf16_f32 v25, v26, v27
	v_exp_f32_e64 v26, -v20
	v_exp_f32_e64 v27, -v21
	v_add_u32_e32 v32, 0xa0, v170
	v_mad_i64_i32 v[32:33], s[16:17], v32, s57, v[142:143]
	v_lshl_add_u64 v[32:33], v[32:33], 0, v[140:141]
	global_store_dwordx2 v[32:33], v[24:25], off
	v_add_f32_e32 v24, 1.0, v26
	v_add_f32_e32 v25, 1.0, v27
	v_exp_f32_e64 v26, -v22
	v_exp_f32_e64 v27, -v23
	v_rcp_f32_e32 v24, v24
	v_rcp_f32_e32 v25, v25
	v_add_f32_e32 v26, 1.0, v26
	v_add_f32_e32 v27, 1.0, v27
	v_rcp_f32_e32 v26, v26
	v_rcp_f32_e32 v27, v27
	v_pk_mul_f32 v[18:19], v[22:23], v[18:19]
	v_pk_mul_f32 v[16:17], v[20:21], v[16:17]
	v_pk_mul_f32 v[16:17], v[16:17], v[24:25]
	v_pk_mul_f32 v[18:19], v[18:19], v[26:27]
	v_cvt_pk_bf16_f32 v16, v16, v17
	v_cvt_pk_bf16_f32 v17, v18, v19
	v_exp_f32_e64 v18, -v12
	v_exp_f32_e64 v19, -v13
	v_exp_f32_e64 v20, -v14
	v_exp_f32_e64 v21, -v15
	v_add_f32_e32 v18, 1.0, v18
	v_add_f32_e32 v19, 1.0, v19
	v_add_f32_e32 v20, 1.0, v20
	v_add_f32_e32 v21, 1.0, v21
	v_rcp_f32_e32 v18, v18
	v_rcp_f32_e32 v19, v19
	v_rcp_f32_e32 v20, v20
	v_rcp_f32_e32 v21, v21
	v_pk_mul_f32 v[10:11], v[14:15], v[10:11]
	v_pk_mul_f32 v[8:9], v[12:13], v[8:9]
	global_store_dwordx2 v[32:33], v[16:17], off offset:128
	v_pk_mul_f32 v[8:9], v[8:9], v[18:19]
	v_pk_mul_f32 v[10:11], v[10:11], v[20:21]
	v_cvt_pk_bf16_f32 v8, v8, v9
	v_cvt_pk_bf16_f32 v9, v10, v11
	v_exp_f32_e64 v10, -v4
	v_exp_f32_e64 v11, -v5
	v_add_u32_e32 v16, 0xb0, v170
	v_mad_i64_i32 v[16:17], s[16:17], v16, s57, v[142:143]
	v_lshl_add_u64 v[16:17], v[16:17], 0, v[140:141]
	global_store_dwordx2 v[16:17], v[8:9], off
	v_add_f32_e32 v8, 1.0, v10
	v_add_f32_e32 v9, 1.0, v11
	v_exp_f32_e64 v10, -v6
	v_exp_f32_e64 v11, -v7
	v_rcp_f32_e32 v8, v8
	v_rcp_f32_e32 v9, v9
	v_add_f32_e32 v10, 1.0, v10
	v_add_f32_e32 v11, 1.0, v11
	v_rcp_f32_e32 v10, v10
	v_rcp_f32_e32 v11, v11
	v_pk_mul_f32 v[2:3], v[6:7], v[2:3]
	v_pk_mul_f32 v[0:1], v[4:5], v[0:1]
	s_and_b64 vcc, exec, s[2:3]
	v_pk_mul_f32 v[0:1], v[0:1], v[8:9]
	v_pk_mul_f32 v[2:3], v[2:3], v[10:11]
	v_cvt_pk_bf16_f32 v0, v0, v1
	v_cvt_pk_bf16_f32 v1, v2, v3
	s_mov_b32 s61, s58
	s_mov_b32 s60, s59
	s_mov_b64 s[18:19], s[0:1]
	s_mov_b64 s[16:17], s[4:5]
	global_store_dwordx2 v[16:17], v[0:1], off offset:128
	s_cbranch_vccz .LBB0_720
	s_branch .Lgu4_done

; #define PG8_STAGE(bufoff, gbase, voff) do { _Pragma("unroll") for (int _i = 0; _i < 2; ++_i) \
;         __builtin_amdgcn_global_load_lds((const unsigned*)((const char*)(gbase) + (voff)[_i]), (PG8_LAS unsigned*)(lds + (bufoff) + ldsw + _i * 8192), 16, 0, 0); } while (0)
; #define PG8_LDA(dst, b, h) do { _Pragma("unroll") for (int m = 0; m < 4; ++m) _Pragma("unroll") for (int k = 0; k < 2; ++k) dst[m][k] = *(const PG8_LAS bf16x8*)(lds + PG8_SA(b, h) + aoff + m * 2048 + k * 1024); } while (0)
; #define PG8_WAIT_V(n) asm volatile("s_waitcnt vmcnt(" #n ")" ::: "memory")
; #define PG8_WAIT_L(n) asm volatile("s_waitcnt lgkmcnt(" #n ")" ::: "memory")
; template <class Epi, class Sched, bool STAMP = false>
; __device__ __forceinline__ void gemm_phase(PG8_LAS unsigned char* lds, const Gemm g, const Sched& S, const Epi& E, unsigned long long* stamps) {
;     ...
;         for (int t = 0; t < nt; t += 2) {
;             const bool last = (t == nt - 2);
;             const char* a1 = cA + (size_t)(t + 1) * kstep;
;             const char* a2 = last ? nA : cA + (size_t)(t + 2) * kstep; const char* b2 = last ? nB : cB + (size_t)(t + 2) * kstep;
;             const char* a3 = a2 + kstep; const char* b3 = b2 + kstep;
;             if (last && has_next) S.a_ready(nxt);
;             PG8_LDB(B0, 0, 0); PG8_SCHED; PG8_LDA(At, 0, 0); PG8_STAGE(PG8_SA(1, 1), a1 + hstep, voffA);
;             PG8_WAIT_L(8); PG8_BAR; PG8_WAIT_L(0); PG8_MMA(0, 0, At, B0); PG8_BAR; PG8_SCHED;
;             PG8_LDB(B1, 0, 1); PG8_STAGE(PG8_SB(0, 0), b2, voffB);
;             PG8_BAR; PG8_WAIT_L(0); PG8_MMA(0, 1, At, B1); PG8_BAR;
;             PG8_LDA(At, 0, 1); PG8_STAGE(PG8_SA(0, 0), a2, voffA);
;             PG8_BAR; PG8_WAIT_L(0); PG8_MMA(1, 0, At, B0); PG8_BAR; PG8_SCHED;
;             PG8_STAGE(PG8_SB(0, 1), b2 + hstep, voffB);
;             PG8_WAIT_V(6); PG8_BAR; PG8_MMA(1, 1, At, B1); PG8_BAR;
;             PG8_LDB(B0, 1, 0); PG8_SCHED; PG8_LDA(At, 1, 0); PG8_STAGE(PG8_SA(0, 1), a2 + hstep, voffA);
;             PG8_WAIT_L(8); PG8_BAR; PG8_WAIT_L(0); PG8_MMA(0, 0, At, B0); PG8_BAR; PG8_SCHED;
;             PG8_LDB(B1, 1, 1); PG8_STAGE(PG8_SB(1, 0), b3, voffB);
;             PG8_BAR; PG8_WAIT_L(0); PG8_MMA(0, 1, At, B1); PG8_BAR;
;             PG8_LDA(At, 1, 1); PG8_STAGE(PG8_SA(1, 0), a3, voffA);
;             PG8_BAR; PG8_WAIT_L(0); PG8_MMA(1, 0, At, B0); PG8_BAR; PG8_SCHED;
.Lgu4_half_loop:
	ds_read_b128 v[140:143], v147
	ds_read_b128 v[170:173], v148
	ds_read_b128 v[174:177], v149
	ds_read_b128 v[178:181], v150
	s_add_u32 s18, s16, 0x100
	s_addc_u32 s19, s17, 0
	s_cmp_eq_u32 s10, 12
	s_cselect_b32 s29, s5, s19
	s_cselect_b32 s28, s4, s18
	s_cselect_b32 s21, s1, s63
	s_cselect_b32 s20, s0, s62
	s_mov_b32 m0, s55
	ds_read_b128 v[182:185], v145
	ds_read_b128 v[186:189], v145 offset:1024
	ds_read_b128 v[190:193], v145 offset:2048
	ds_read_b128 v[194:197], v145 offset:3072
	ds_read_b128 v[198:201], v145 offset:4096
	ds_read_b128 v[202:205], v145 offset:5120
	ds_read_b128 v[206:209], v145 offset:6144
	ds_read_b128 v[210:213], v145 offset:7168
	global_load_lds_dwordx4 v132, s[16:17]
	s_mov_b32 m0, s56
	s_nop 0
	global_load_lds_dwordx4 v134, s[16:17]
	s_waitcnt lgkmcnt(8)
	s_barrier
	s_waitcnt lgkmcnt(0)
	s_setprio 1
	s_waitcnt lgkmcnt(0)
	v_mfma_f32_16x16x32_bf16 v[124:127], v[140:143], v[182:185], v[124:127]
	v_mfma_f32_16x16x32_bf16 v[120:123], v[174:177], v[182:185], v[120:123]
	v_mfma_f32_16x16x32_bf16 v[108:111], v[140:143], v[190:193], v[108:111]
	v_mfma_f32_16x16x32_bf16 v[104:107], v[174:177], v[190:193], v[104:107]
	v_mfma_f32_16x16x32_bf16 v[92:95], v[140:143], v[198:201], v[92:95]
	v_mfma_f32_16x16x32_bf16 v[88:91], v[174:177], v[198:201], v[88:91]
	v_mfma_f32_16x16x32_bf16 v[76:79], v[140:143], v[206:209], v[76:79]
	v_mfma_f32_16x16x32_bf16 v[72:75], v[174:177], v[206:209], v[72:75]
	v_mfma_f32_16x16x32_bf16 v[124:127], v[170:173], v[186:189], v[124:127]
	v_mfma_f32_16x16x32_bf16 v[120:123], v[178:181], v[186:189], v[120:123]
	v_mfma_f32_16x16x32_bf16 v[108:111], v[170:173], v[194:197], v[108:111]
	v_mfma_f32_16x16x32_bf16 v[104:107], v[178:181], v[194:197], v[104:107]
	v_mfma_f32_16x16x32_bf16 v[92:95], v[170:173], v[202:205], v[92:95]
	v_mfma_f32_16x16x32_bf16 v[88:91], v[178:181], v[202:205], v[88:91]
	v_mfma_f32_16x16x32_bf16 v[76:79], v[170:173], v[210:213], v[76:79]
	v_mfma_f32_16x16x32_bf16 v[72:75], v[178:181], v[210:213], v[72:75]
	s_setprio 0
	s_barrier
	s_mov_b32 m0, s37
	s_nop 0
	global_load_lds_dwordx4 v130, s[20:21]
	s_mov_b32 m0, s40
	s_nop 0
	global_load_lds_dwordx4 v128, s[20:21]
	s_barrier
	s_waitcnt lgkmcnt(0)
	s_setprio 1
	s_waitcnt lgkmcnt(0)
	s_setprio 0
	s_mov_b32 m0, s34
	s_barrier
	ds_read_b128 v[182:185], v145 offset:16384
	ds_read_b128 v[186:189], v145 offset:17408
	ds_read_b128 v[190:193], v145 offset:18432
	ds_read_b128 v[194:197], v145 offset:19456
	ds_read_b128 v[198:201], v145 offset:20480
	ds_read_b128 v[202:205], v145 offset:21504
	ds_read_b128 v[206:209], v145 offset:22528
	ds_read_b128 v[210:213], v145 offset:23552
	global_load_lds_dwordx4 v130, s[28:29]
	s_mov_b32 m0, s41
	s_nop 0
	global_load_lds_dwordx4 v128, s[28:29]
	s_barrier
	s_waitcnt lgkmcnt(0)
	s_setprio 1
	s_waitcnt lgkmcnt(0)
	v_mfma_f32_16x16x32_bf16 v[60:63], v[140:143], v[182:185], v[60:63]
	v_mfma_f32_16x16x32_bf16 v[56:59], v[174:177], v[182:185], v[56:59]
	v_mfma_f32_16x16x32_bf16 v[44:47], v[140:143], v[190:193], v[44:47]
	v_mfma_f32_16x16x32_bf16 v[40:43], v[174:177], v[190:193], v[40:43]
	v_mfma_f32_16x16x32_bf16 v[28:31], v[140:143], v[198:201], v[28:31]
	v_mfma_f32_16x16x32_bf16 v[24:27], v[174:177], v[198:201], v[24:27]
	v_mfma_f32_16x16x32_bf16 v[12:15], v[140:143], v[206:209], v[12:15]
	v_mfma_f32_16x16x32_bf16 v[8:11], v[174:177], v[206:209], v[8:11]
	v_mfma_f32_16x16x32_bf16 v[60:63], v[170:173], v[186:189], v[60:63]
	v_mfma_f32_16x16x32_bf16 v[56:59], v[178:181], v[186:189], v[56:59]
	v_mfma_f32_16x16x32_bf16 v[44:47], v[170:173], v[194:197], v[44:47]
	v_mfma_f32_16x16x32_bf16 v[40:43], v[178:181], v[194:197], v[40:43]
	v_mfma_f32_16x16x32_bf16 v[28:31], v[170:173], v[202:205], v[28:31]
	v_mfma_f32_16x16x32_bf16 v[24:27], v[178:181], v[202:205], v[24:27]
	v_mfma_f32_16x16x32_bf16 v[12:15], v[170:173], v[210:213], v[12:15]
	v_mfma_f32_16x16x32_bf16 v[8:11], v[178:181], v[210:213], v[8:11]
	s_setprio 0
	s_barrier
	s_add_u32 s16, s20, 0x44000
	s_addc_u32 s17, s21, 0
	s_mov_b32 m0, s42
	s_nop 0
	global_load_lds_dwordx4 v130, s[16:17]
	s_mov_b32 m0, s43
	s_nop 0
	global_load_lds_dwordx4 v128, s[16:17]
	s_waitcnt vmcnt(6)
	s_barrier
	s_setprio 1
	s_setprio 0
	s_barrier
	ds_read_b128 v[140:143], v155
	ds_read_b128 v[170:173], v156
	ds_read_b128 v[174:177], v157
	ds_read_b128 v[178:181], v165
	s_add_u32 s16, s28, 0x44000
	s_addc_u32 s17, s29, 0
	s_mov_b32 m0, s44
	ds_read_b128 v[182:185], v145 offset:32768
	ds_read_b128 v[186:189], v145 offset:33792
	ds_read_b128 v[190:193], v145 offset:34816
	ds_read_b128 v[194:197], v145 offset:35840
	ds_read_b128 v[198:201], v145 offset:36864
	ds_read_b128 v[202:205], v145 offset:37888
	ds_read_b128 v[206:209], v145 offset:38912
	ds_read_b128 v[210:213], v145 offset:39936
	global_load_lds_dwordx4 v130, s[16:17]
	s_mov_b32 m0, s45
	s_nop 0
	global_load_lds_dwordx4 v128, s[16:17]
	s_waitcnt lgkmcnt(8)
	s_barrier
	s_waitcnt lgkmcnt(0)
	s_setprio 1
	s_waitcnt lgkmcnt(0)
	v_mfma_f32_16x16x32_bf16 v[124:127], v[140:143], v[182:185], v[124:127]
	v_mfma_f32_16x16x32_bf16 v[120:123], v[174:177], v[182:185], v[120:123]
	v_mfma_f32_16x16x32_bf16 v[108:111], v[140:143], v[190:193], v[108:111]
	v_mfma_f32_16x16x32_bf16 v[104:107], v[174:177], v[190:193], v[104:107]
	v_mfma_f32_16x16x32_bf16 v[92:95], v[140:143], v[198:201], v[92:95]
	v_mfma_f32_16x16x32_bf16 v[88:91], v[174:177], v[198:201], v[88:91]
	v_mfma_f32_16x16x32_bf16 v[76:79], v[140:143], v[206:209], v[76:79]
	v_mfma_f32_16x16x32_bf16 v[72:75], v[174:177], v[206:209], v[72:75]
	v_mfma_f32_16x16x32_bf16 v[124:127], v[170:173], v[186:189], v[124:127]
	v_mfma_f32_16x16x32_bf16 v[120:123], v[178:181], v[186:189], v[120:123]
	v_mfma_f32_16x16x32_bf16 v[108:111], v[170:173], v[194:197], v[108:111]
	v_mfma_f32_16x16x32_bf16 v[104:107], v[178:181], v[194:197], v[104:107]
	v_mfma_f32_16x16x32_bf16 v[92:95], v[170:173], v[202:205], v[92:95]
	v_mfma_f32_16x16x32_bf16 v[88:91], v[178:181], v[202:205], v[88:91]
	v_mfma_f32_16x16x32_bf16 v[76:79], v[170:173], v[210:213], v[76:79]
	v_mfma_f32_16x16x32_bf16 v[72:75], v[178:181], v[210:213], v[72:75]
	s_setprio 0
	s_barrier
; #define PG8_STAGE(bufoff, gbase, voff) do { _Pragma("unroll") for (int _i = 0; _i < 2; ++_i) \
;         __builtin_amdgcn_global_load_lds((const unsigned*)((const char*)(gbase) + (voff)[_i]), (PG8_LAS unsigned*)(lds + (bufoff) + ldsw + _i * 8192), 16, 0, 0); } while (0)
; #define PG8_LDA(dst, b, h) do { _Pragma("unroll") for (int m = 0; m < 4; ++m) _Pragma("unroll") for (int k = 0; k < 2; ++k) dst[m][k] = *(const PG8_LAS bf16x8*)(lds + PG8_SA(b, h) + aoff + m * 2048 + k * 1024); } while (0)
; #define PG8_LDB(dst, b, h) do { _Pragma("unroll") for (int n = 0; n < 2; ++n) _Pragma("unroll") for (int k = 0; k < 2; ++k) dst[n][k] = *(const PG8_LAS bf16x8*)(lds + PG8_SB(b, h) + boff + n * 2048 + k * 1024); } while (0)
; #define PG8_MMA(ai, bj, At, Bt) do { __builtin_amdgcn_s_setprio(1); _Pragma("unroll") for (int m = 0; m < 4; ++m) _Pragma("unroll") for (int n = 0; n < 2; ++n) _Pragma("unroll") for (int k = 0; k < 2; ++k) \
;         acc[ai][bj][m][n] = __builtin_amdgcn_mfma_f32_16x16x32_bf16(Bt[n][k], At[m][k], acc[ai][bj][m][n], 0, 0, 0); __builtin_amdgcn_s_setprio(0); } while (0)
; #define PG8_WAIT_V(n) asm volatile("s_waitcnt vmcnt(" #n ")" ::: "memory")
; #define PG8_WAIT_L(n) asm volatile("s_waitcnt lgkmcnt(" #n ")" ::: "memory")
; #define PG8_BAR __builtin_amdgcn_s_barrier()
; #define PG8_SCHED __builtin_amdgcn_sched_barrier(0)
; template <class Epi, class Sched, bool STAMP = false>
; __device__ __forceinline__ void gemm_phase(PG8_LAS unsigned char* lds, const Gemm g, const Sched& S, const Epi& E, unsigned long long* stamps) {
;     ...
;             PG8_LDB(B1, 1, 1); PG8_STAGE(PG8_SB(1, 0), b3, voffB);
;             PG8_BAR; PG8_WAIT_L(0); PG8_MMA(0, 1, At, B1); PG8_BAR;
;             PG8_LDA(At, 1, 1); PG8_STAGE(PG8_SA(1, 0), a3, voffA);
;             PG8_BAR; PG8_WAIT_L(0); PG8_MMA(1, 0, At, B0); PG8_BAR; PG8_SCHED;
;             PG8_STAGE(PG8_SB(1, 1), b3 + hstep, voffB);
;             PG8_WAIT_V(6); PG8_BAR; PG8_MMA(1, 1, At, B1); PG8_BAR;
;         }
	s_mov_b32 m0, s48
	s_add_u32 s100, s20, 0x80
	s_addc_u32 s101, s21, 0
	global_load_lds_dwordx4 v130, s[100:101]
	s_mov_b32 m0, s49
	s_nop 0
	global_load_lds_dwordx4 v128, s[100:101]
	s_barrier
	s_waitcnt lgkmcnt(0)
	s_setprio 1
	s_waitcnt lgkmcnt(0)
	s_setprio 0
	s_mov_b32 m0, s50
	s_barrier
	ds_read_b128 v[182:185], v145 offset:49152
	ds_read_b128 v[186:189], v145 offset:50176
	ds_read_b128 v[190:193], v145 offset:51200
	ds_read_b128 v[194:197], v145 offset:52224
	ds_read_b128 v[198:201], v145 offset:53248
	ds_read_b128 v[202:205], v145 offset:54272
	ds_read_b128 v[206:209], v145 offset:55296
	ds_read_b128 v[210:213], v145 offset:56320
	s_add_u32 s100, s28, 0x80
	s_addc_u32 s101, s29, 0
	global_load_lds_dwordx4 v130, s[100:101]
	s_mov_b32 m0, s51
	s_nop 0
	global_load_lds_dwordx4 v128, s[100:101]
	s_barrier
	s_waitcnt lgkmcnt(0)
	s_setprio 1
	s_waitcnt lgkmcnt(0)
	v_mfma_f32_16x16x32_bf16 v[60:63], v[140:143], v[182:185], v[60:63]
	v_mfma_f32_16x16x32_bf16 v[56:59], v[174:177], v[182:185], v[56:59]
	v_mfma_f32_16x16x32_bf16 v[44:47], v[140:143], v[190:193], v[44:47]
	v_mfma_f32_16x16x32_bf16 v[40:43], v[174:177], v[190:193], v[40:43]
	v_mfma_f32_16x16x32_bf16 v[28:31], v[140:143], v[198:201], v[28:31]
	v_mfma_f32_16x16x32_bf16 v[24:27], v[174:177], v[198:201], v[24:27]
	v_mfma_f32_16x16x32_bf16 v[12:15], v[140:143], v[206:209], v[12:15]
	v_mfma_f32_16x16x32_bf16 v[8:11], v[174:177], v[206:209], v[8:11]
	v_mfma_f32_16x16x32_bf16 v[60:63], v[170:173], v[186:189], v[60:63]
	v_mfma_f32_16x16x32_bf16 v[56:59], v[178:181], v[186:189], v[56:59]
	v_mfma_f32_16x16x32_bf16 v[44:47], v[170:173], v[194:197], v[44:47]
	v_mfma_f32_16x16x32_bf16 v[40:43], v[178:181], v[194:197], v[40:43]
	v_mfma_f32_16x16x32_bf16 v[28:31], v[170:173], v[202:205], v[28:31]
	v_mfma_f32_16x16x32_bf16 v[24:27], v[178:181], v[202:205], v[24:27]
	v_mfma_f32_16x16x32_bf16 v[12:15], v[170:173], v[210:213], v[12:15]
	v_mfma_f32_16x16x32_bf16 v[8:11], v[178:181], v[210:213], v[8:11]
	s_setprio 0
	s_barrier
	s_add_u32 s16, s20, 0x44080
	s_addc_u32 s17, s21, 0
	s_mov_b32 m0, s52
	s_nop 0
	global_load_lds_dwordx4 v130, s[16:17]
	s_mov_b32 m0, s53
	s_nop 0
	global_load_lds_dwordx4 v128, s[16:17]
	s_waitcnt vmcnt(6)
	s_barrier
	s_setprio 1
	s_setprio 0
	s_add_i32 s10, s10, 2
	s_add_u32 s62, s62, 0x100
	s_addc_u32 s63, s63, 0
	s_cmp_gt_u32 s10, 13
	s_mov_b64 s[16:17], s[18:19]
	s_barrier
	s_cbranch_scc0 .Lgu4_half_loop
; DI float ex2(float x) { return __builtin_amdgcn_exp2f(x); }
;     DI void operator()(const f32x4 (&acc)[2][2][4][2], const Unit& u, int wr, int wc, int fr, int fq) const {
;         const int row0 = u.pm * BM + wr * 64 + fr, hcol0 = ((u.pn * BM + wc * 32) >> 1) + 4 * fq;
; #pragma unroll
;         for (int ai = 0; ai < 2; ++ai)
; #pragma unroll
;             for (int m = 0; m < 4; ++m) { u16* rowp = O + (size_t)(row0 + ai * HALF + m * 16) * ldc + hcol0;
; #pragma unroll
;                 for (int bj = 0; bj < 2; ++bj) { const f32x4 g = acc[ai][bj][m][0], up = acc[ai][bj][m][1]; float r[4];
; #pragma unroll
;                     for (int j = 0; j < 4; ++j) r[j] = g[j] * up[j] * __builtin_amdgcn_rcpf(1.f + ex2(-LOG2E * g[j]));
;                     uint2 w = {pack2(r[0], r[1]), pack2(r[2], r[3])}; *(uint2*)(rowp + bj * (HALF / 2)) = w; } }
	v_exp_f32_e64 v171, -v124
	v_exp_f32_e64 v175, -v125
	s_lshl_b32 s10, s61, 8
	v_add_f32_e32 v171, 1.0, v171
	v_rcp_f32_e32 v174, v171
	v_add_f32_e32 v171, 1.0, v175
	v_exp_f32_e64 v176, -v126
	v_exp_f32_e64 v177, -v127
	v_rcp_f32_e32 v175, v171
	v_add_f32_e32 v171, 1.0, v176
	v_rcp_f32_e32 v176, v171
	v_add_f32_e32 v171, 1.0, v177
	v_rcp_f32_e32 v177, v171
	v_pk_mul_f32 v[122:123], v[126:127], v[122:123]
	v_pk_mul_f32 v[120:121], v[124:125], v[120:121]
	s_or_b32 s10, s10, s47
	s_or_b32 s10, s10, s98
	v_pk_mul_f32 v[120:121], v[120:121], v[174:175]
	v_pk_mul_f32 v[122:123], v[122:123], v[176:177]
	s_ashr_i32 s10, s10, 1
	v_cvt_pk_bf16_f32 v120, v120, v121
	v_cvt_pk_bf16_f32 v121, v122, v123
	v_or_b32_e32 v140, s10, v146
	v_lshl_add_u32 v170, s60, 8, v144
	v_ashrrev_i32_e32 v141, 31, v140
	v_mov_b64_e32 v[142:143], s[12:13]
	v_mad_i64_i32 v[172:173], s[16:17], v170, s57, v[142:143]
	v_lshlrev_b64 v[140:141], 1, v[140:141]
	v_lshl_add_u64 v[172:173], v[172:173], 0, v[140:141]
	global_store_dwordx2 v[172:173], v[120:121], off
	v_exp_f32_e64 v114, -v108
	v_exp_f32_e64 v115, -v109
	v_exp_f32_e64 v116, -v110
	v_exp_f32_e64 v117, -v111
	v_add_f32_e32 v114, 1.0, v114
	v_add_f32_e32 v115, 1.0, v115
	v_add_f32_e32 v116, 1.0, v116
	v_add_f32_e32 v117, 1.0, v117
	v_rcp_f32_e32 v114, v114
	v_rcp_f32_e32 v115, v115
	v_rcp_f32_e32 v116, v116
	v_rcp_f32_e32 v117, v117
	v_pk_mul_f32 v[106:107], v[110:111], v[106:107]
	v_pk_mul_f32 v[104:105], v[108:109], v[104:105]
	v_pk_mul_f32 v[104:105], v[104:105], v[114:115]
	v_pk_mul_f32 v[106:107], v[106:107], v[116:117]
	v_cvt_pk_bf16_f32 v104, v104, v105
	v_cvt_pk_bf16_f32 v105, v106, v107
	v_or_b32_e32 v112, 16, v170
	v_mad_i64_i32 v[112:113], s[16:17], v112, s57, v[142:143]
	v_lshl_add_u64 v[112:113], v[112:113], 0, v[140:141]
	global_store_dwordx2 v[112:113], v[104:105], off
	v_exp_f32_e64 v98, -v92
	v_exp_f32_e64 v99, -v93
	v_exp_f32_e64 v100, -v94
	v_exp_f32_e64 v101, -v95
	v_add_f32_e32 v98, 1.0, v98
	v_add_f32_e32 v99, 1.0, v99
	v_add_f32_e32 v100, 1.0, v100
	v_add_f32_e32 v101, 1.0, v101
	v_rcp_f32_e32 v98, v98
	v_rcp_f32_e32 v99, v99
	v_rcp_f32_e32 v100, v100
	v_rcp_f32_e32 v101, v101
	v_pk_mul_f32 v[90:91], v[94:95], v[90:91]
	v_pk_mul_f32 v[88:89], v[92:93], v[88:89]
	v_pk_mul_f32 v[88:89], v[88:89], v[98:99]
	v_pk_mul_f32 v[90:91], v[90:91], v[100:101]
	v_cvt_pk_bf16_f32 v88, v88, v89
	v_cvt_pk_bf16_f32 v89, v90, v91
	v_or_b32_e32 v96, 32, v170
	v_mad_i64_i32 v[96:97], s[16:17], v96, s57, v[142:143]
	v_lshl_add_u64 v[96:97], v[96:97], 0, v[140:141]
	global_store_dwordx2 v[96:97], v[88:89], off
	v_exp_f32_e64 v82, -v76
	v_exp_f32_e64 v83, -v77
	v_exp_f32_e64 v84, -v78
	v_exp_f32_e64 v85, -v79
	v_add_f32_e32 v82, 1.0, v82
	v_add_f32_e32 v83, 1.0, v83
	v_add_f32_e32 v84, 1.0, v84
	v_add_f32_e32 v85, 1.0, v85
	v_rcp_f32_e32 v82, v82
	v_rcp_f32_e32 v83, v83
	v_rcp_f32_e32 v84, v84
	v_rcp_f32_e32 v85, v85
	v_pk_mul_f32 v[74:75], v[78:79], v[74:75]
	v_pk_mul_f32 v[72:73], v[76:77], v[72:73]
	v_pk_mul_f32 v[72:73], v[72:73], v[82:83]
	v_pk_mul_f32 v[74:75], v[74:75], v[84:85]
	v_cvt_pk_bf16_f32 v72, v72, v73
	v_cvt_pk_bf16_f32 v73, v74, v75
	v_or_b32_e32 v80, 48, v170
	v_mad_i64_i32 v[80:81], s[16:17], v80, s57, v[142:143]
	v_lshl_add_u64 v[80:81], v[80:81], 0, v[140:141]
	global_store_dwordx2 v[80:81], v[72:73], off
	v_exp_f32_e64 v66, -v60
	v_exp_f32_e64 v67, -v61
	v_exp_f32_e64 v68, -v62
	v_exp_f32_e64 v69, -v63
	v_add_f32_e32 v66, 1.0, v66
	v_add_f32_e32 v67, 1.0, v67
	v_add_f32_e32 v68, 1.0, v68
	v_add_f32_e32 v69, 1.0, v69
	v_rcp_f32_e32 v66, v66
	v_rcp_f32_e32 v67, v67
	v_rcp_f32_e32 v68, v68
	v_rcp_f32_e32 v69, v69
	v_pk_mul_f32 v[58:59], v[62:63], v[58:59]
	v_pk_mul_f32 v[56:57], v[60:61], v[56:57]
	v_pk_mul_f32 v[56:57], v[56:57], v[66:67]
	v_pk_mul_f32 v[58:59], v[58:59], v[68:69]
	v_cvt_pk_bf16_f32 v56, v56, v57
	v_cvt_pk_bf16_f32 v57, v58, v59
	v_add_u32_e32 v64, 0x80, v170
	v_mad_i64_i32 v[64:65], s[16:17], v64, s57, v[142:143]
	v_lshl_add_u64 v[64:65], v[64:65], 0, v[140:141]
	global_store_dwordx2 v[64:65], v[56:57], off
	v_exp_f32_e64 v50, -v44
	v_exp_f32_e64 v51, -v45
	v_exp_f32_e64 v52, -v46
	v_exp_f32_e64 v53, -v47
	v_add_f32_e32 v50, 1.0, v50
	v_add_f32_e32 v51, 1.0, v51
	v_add_f32_e32 v52, 1.0, v52
	v_add_f32_e32 v53, 1.0, v53
	v_rcp_f32_e32 v50, v50
	v_rcp_f32_e32 v51, v51
	v_rcp_f32_e32 v52, v52
	v_rcp_f32_e32 v53, v53
	v_pk_mul_f32 v[42:43], v[46:47], v[42:43]
	v_pk_mul_f32 v[40:41], v[44:45], v[40:41]
	v_pk_mul_f32 v[40:41], v[40:41], v[50:51]
	v_pk_mul_f32 v[42:43], v[42:43], v[52:53]
	v_cvt_pk_bf16_f32 v40, v40, v41
	v_cvt_pk_bf16_f32 v41, v42, v43
	v_add_u32_e32 v48, 0x90, v170
	v_mad_i64_i32 v[48:49], s[16:17], v48, s57, v[142:143]
	v_lshl_add_u64 v[48:49], v[48:49], 0, v[140:141]
	global_store_dwordx2 v[48:49], v[40:41], off
	v_exp_f32_e64 v34, -v28
	v_exp_f32_e64 v35, -v29
	v_exp_f32_e64 v36, -v30
	v_exp_f32_e64 v37, -v31
	v_add_f32_e32 v34, 1.0, v34
	v_add_f32_e32 v35, 1.0, v35
	v_add_f32_e32 v36, 1.0, v36
	v_add_f32_e32 v37, 1.0, v37
	v_rcp_f32_e32 v34, v34
	v_rcp_f32_e32 v35, v35
	v_rcp_f32_e32 v36, v36
	v_rcp_f32_e32 v37, v37
	v_pk_mul_f32 v[26:27], v[30:31], v[26:27]
	v_pk_mul_f32 v[24:25], v[28:29], v[24:25]
	v_pk_mul_f32 v[24:25], v[24:25], v[34:35]
	v_pk_mul_f32 v[26:27], v[26:27], v[36:37]
	v_cvt_pk_bf16_f32 v24, v24, v25
	v_cvt_pk_bf16_f32 v25, v26, v27
	v_add_u32_e32 v32, 0xa0, v170
	v_mad_i64_i32 v[32:33], s[16:17], v32, s57, v[142:143]
	v_lshl_add_u64 v[32:33], v[32:33], 0, v[140:141]
	global_store_dwordx2 v[32:33], v[24:25], off
	v_exp_f32_e64 v18, -v12
	v_exp_f32_e64 v19, -v13
	v_exp_f32_e64 v20, -v14
	v_exp_f32_e64 v21, -v15
	v_add_f32_e32 v18, 1.0, v18
	v_add_f32_e32 v19, 1.0, v19
	v_add_f32_e32 v20, 1.0, v20
	v_add_f32_e32 v21, 1.0, v21
	v_rcp_f32_e32 v18, v18
	v_rcp_f32_e32 v19, v19
	v_rcp_f32_e32 v20, v20
	v_rcp_f32_e32 v21, v21
	v_pk_mul_f32 v[10:11], v[14:15], v[10:11]
	v_pk_mul_f32 v[8:9], v[12:13], v[8:9]
	v_pk_mul_f32 v[8:9], v[8:9], v[18:19]
	v_pk_mul_f32 v[10:11], v[10:11], v[20:21]
	v_cvt_pk_bf16_f32 v8, v8, v9
	v_cvt_pk_bf16_f32 v9, v10, v11
	v_add_u32_e32 v16, 0xb0, v170
	v_mad_i64_i32 v[16:17], s[16:17], v16, s57, v[142:143]
	v_lshl_add_u64 v[16:17], v[16:17], 0, v[140:141]
	global_store_dwordx2 v[16:17], v[8:9], off
	s_and_b64 vcc, exec, s[2:3]
	s_mov_b32 s61, s58
	s_mov_b32 s60, s59
	s_mov_b64 s[18:19], s[0:1]
	s_mov_b64 s[16:17], s[4:5]

; DI unsigned bar_add(unsigned* p, unsigned v) { return __hip_atomic_fetch_add(p, v, __ATOMIC_RELAXED, __HIP_MEMORY_SCOPE_AGENT); }
; DI void grid_barrier(unsigned* bar, unsigned k, volatile unsigned* meta) {
;   asm volatile("s_waitcnt vmcnt(0)" ::: "memory");
;   __syncthreads();
;   if (threadIdx.x == 0) {
;     const unsigned nloc = meta[0], nx = meta[1], x = meta[2];
;     const unsigned old = bar_add(bar + 1024 + 64 * x, 1u);
;     if (old + 1u == k * nloc) {
;       __builtin_amdgcn_fence(__ATOMIC_RELEASE, "agent");
;       asm volatile("s_waitcnt vmcnt(0)" ::: "memory");
;       const unsigned old2 = bar_add(bar + 3072, 1u);
;       if (old2 + 1u == k * nx) {
;         for (int j = 0; j < 16; ++j) __hip_atomic_store(bar + 2048 + 64 * j, k, __ATOMIC_RELAXED, __HIP_MEMORY_SCOPE_AGENT);
.LBB0_732:
	s_waitcnt vmcnt(0)
	s_waitcnt vmcnt(0) lgkmcnt(0)
	s_barrier
	s_and_saveexec_b64 s[0:1], s[8:9]
	s_cbranch_execz .LBB0_742
	s_mov_b64 s[2:3], src_shared_base
	v_mov_b32_e32 v0, 0x24040
	ds_read_b32 v3, v0
	ds_read_b32 v2, v0 offset:4
	ds_read_b32 v0, v0 offset:8
	v_mov_b32_e32 v1, 0
	v_mov_b32_e32 v6, 1
	s_waitcnt lgkmcnt(0)
	v_mul_lo_u32 v3, v3, 21
	v_lshlrev_b32_e32 v0, 6, v0
	v_lshl_add_u64 v[0:1], v[0:1], 2, s[24:25]
	v_add_co_u32_e32 v4, vcc, 0xef01000, v0
	s_nop 1
	v_addc_co_u32_e32 v5, vcc, 0, v1, vcc
	global_atomic_add v4, v[4:5], v6, off offset:1024 sc0
	s_waitcnt vmcnt(0)
	v_add_u32_e32 v4, 1, v4
	v_cmp_eq_u32_e32 vcc, v4, v3
	s_and_saveexec_b64 s[2:3], vcc
	s_cbranch_execz .LBB0_738
	s_mov_b64 s[4:5], exec
	buffer_wbl2 sc1
	s_waitcnt vmcnt(0)
	v_mbcnt_lo_u32_b32 v3, s4, 0
	v_mbcnt_hi_u32_b32 v3, s5, v3
	v_cmp_eq_u32_e32 vcc, 0, v3
	s_and_saveexec_b64 s[6:7], vcc
	s_cbranch_execz .LBB0_736
	s_bcnt1_i32_b64 s4, s[4:5]
	v_mov_b32_e32 v4, 0xef03000
	v_mov_b32_e32 v5, s4
	global_atomic_add v4, v4, v5, s[24:25] offset:1024 sc0

; DI unsigned bar_add(unsigned* p, unsigned v) { return __hip_atomic_fetch_add(p, v, __ATOMIC_RELAXED, __HIP_MEMORY_SCOPE_AGENT); }
; DI void grid_barrier(unsigned* bar, unsigned k, volatile unsigned* meta) {
;   asm volatile("s_waitcnt vmcnt(0)" ::: "memory");
;   __syncthreads();
;   if (threadIdx.x == 0) {
;     const unsigned nloc = meta[0], nx = meta[1], x = meta[2];
;     const unsigned old = bar_add(bar + 1024 + 64 * x, 1u);
;     if (old + 1u == k * nloc) {
;       __builtin_amdgcn_fence(__ATOMIC_RELEASE, "agent");
;       asm volatile("s_waitcnt vmcnt(0)" ::: "memory");
;       const unsigned old2 = bar_add(bar + 3072, 1u);
;       if (old2 + 1u == k * nx) {
;         for (int j = 0; j < 16; ++j) __hip_atomic_store(bar + 2048 + 64 * j, k, __ATOMIC_RELAXED, __HIP_MEMORY_SCOPE_AGENT);
.LBB0_766:
	s_waitcnt vmcnt(0)
	s_waitcnt vmcnt(0) lgkmcnt(0)
	s_barrier
	s_and_saveexec_b64 s[0:1], s[8:9]
	s_cbranch_execz .LBB0_776
	s_mov_b64 s[2:3], src_shared_base
	v_mov_b32_e32 v0, 0x24040
	ds_read_b32 v3, v0
	ds_read_b32 v2, v0 offset:4
	ds_read_b32 v0, v0 offset:8
	v_mov_b32_e32 v1, 0
	v_mov_b32_e32 v6, 1
	s_waitcnt lgkmcnt(0)
	v_mul_lo_u32 v3, v3, 22
	v_lshlrev_b32_e32 v0, 6, v0
	v_lshl_add_u64 v[0:1], v[0:1], 2, s[24:25]
	v_add_co_u32_e32 v4, vcc, 0xef01000, v0
	s_nop 1
	v_addc_co_u32_e32 v5, vcc, 0, v1, vcc
	global_atomic_add v4, v[4:5], v6, off offset:1024 sc0
	s_waitcnt vmcnt(0)
	v_add_u32_e32 v4, 1, v4
	v_cmp_eq_u32_e32 vcc, v4, v3
	s_and_saveexec_b64 s[2:3], vcc
	s_cbranch_execz .LBB0_772
	s_mov_b64 s[4:5], exec
	buffer_wbl2 sc1
	s_waitcnt vmcnt(0)
	v_mbcnt_lo_u32_b32 v3, s4, 0
	v_mbcnt_hi_u32_b32 v3, s5, v3
	v_cmp_eq_u32_e32 vcc, 0, v3
	s_and_saveexec_b64 s[6:7], vcc
	s_cbranch_execz .LBB0_770
	s_bcnt1_i32_b64 s4, s[4:5]
	v_mov_b32_e32 v4, 0xef03000
	v_mov_b32_e32 v5, s4
	global_atomic_add v4, v4, v5, s[24:25] offset:1024 sc0
